# GEMM K-loops: removed per-segment s_setprio toggling, one static priority raise for waves 0-3 during GEMM phases
# speedup vs baseline: 1.0011x; 1.0011x over previous
.LBB0_205:
	s_load_dwordx2 s[24:25], s[22:23], 0x4
	s_waitcnt lgkmcnt(0)
	s_mov_b64 s[6:7], s[0:1]
	s_getreg_b32 s3, hwreg(HW_REG_XCC_ID, 0, 4)
	s_setprio 0
	s_waitcnt vmcnt(0)
	s_waitcnt vmcnt(0)
	s_barrier
	s_and_saveexec_b64 s[4:5], s[20:21]
	s_cbranch_execz .Lcgx_301
	s_add_i32 s8, 0, 0x23fc0
	v_mov_b32_e32 v0, s8
	s_load_dwordx2 s[6:7], s[6:7], 0x138
	s_waitcnt vmcnt(0) expcnt(0) lgkmcnt(0)
	ds_read_b32 v2, v0
	s_add_i32 s8, 0, 0x23fc4
	v_mov_b32_e32 v0, s8
	ds_read_b32 v0, v0
	s_and_b32 s3, s3, 15
	s_waitcnt lgkmcnt(1)
	v_cmp_ne_u32_e32 vcc, 0, v2
	s_cbranch_vccnz .Lcgx_265
	s_load_dword s8, s[22:23], 0x14
	s_mov_b32 s56, 1
	v_mov_b32_e32 v16, 0
	s_waitcnt lgkmcnt(0)
	s_lshr_b32 s10, s8, 16
	s_and_b32 s8, s8, 0xffff
	s_cmp_lg_u32 s8, 0
	s_cselect_b64 s[8:9], -1, 0
	s_cmp_lg_u64 s[8:9], 0
	s_addc_u32 s8, s24, 0
	s_cmp_lg_u32 s10, 0
	s_mul_i32 s57, s8, s33
	s_cselect_b64 s[8:9], -1, 0
	s_cmp_lg_u64 s[8:9], 0
	s_addc_u32 s8, s25, 0
	s_mul_i32 s57, s57, s8
	s_add_u32 s8, s6, 0x4200
	s_addc_u32 s9, s7, 0
	s_add_u32 s10, s6, 0x4400
	s_addc_u32 s11, s7, 0
	s_add_u32 s12, s6, 0x4500
	s_addc_u32 s13, s7, 0
	s_add_u32 s14, s6, 0x4600
	s_addc_u32 s15, s7, 0
	s_add_u32 s16, s6, 0x4700
	s_addc_u32 s17, s7, 0
	s_add_u32 s18, s6, 0x4800
	s_addc_u32 s19, s7, 0
	s_add_u32 s26, s6, 0x4900
	s_addc_u32 s27, s7, 0
	s_add_u32 s28, s6, 0x4a00
	s_addc_u32 s29, s7, 0
	s_add_u32 s30, s6, 0x4b00
	s_addc_u32 s31, s7, 0
	s_add_u32 s34, s6, 0x4c00
	s_addc_u32 s35, s7, 0
	s_add_u32 s36, s6, 0x4d00
	s_addc_u32 s37, s7, 0
	s_add_u32 s38, s6, 0x4e00
	s_addc_u32 s39, s7, 0
	s_add_u32 s40, s6, 0x4f00
	s_addc_u32 s41, s7, 0
	s_add_u32 s42, s6, 0x5000
	s_addc_u32 s43, s7, 0
	s_add_u32 s44, s6, 0x5100
	s_addc_u32 s45, s7, 0
	s_add_u32 s46, s6, 0x5200
	s_addc_u32 s47, s7, 0
	s_add_u32 s48, s6, 0x5300
	s_addc_u32 s49, s7, 0
	s_branch .Lcgx_253

.Lcgx_301:
	s_or_b64 exec, exec, s[4:5]
	s_waitcnt lgkmcnt(0)
	s_mov_b32 s100, 0
	s_mov_b64 s[4:5], s[0:1]
	s_mov_b64 s[8:9], s[0:1]
	s_mov_b32 s3, s33
	s_mov_b32 s40, s2
	s_barrier
	v_readfirstlane_b32 s94, v154
	s_cmpk_ge_u32 s94, 0x100
	s_cbranch_scc1 .Lprio_skip_1
	s_setprio 1
.Lprio_skip_1:
	v_mov_b32_e32 v8, v154
	s_cmpk_lt_i32 s40, 0x2c0
	s_cselect_b64 s[10:11], -1, 0
	s_cmpk_gt_i32 s40, 0x2bf
	v_readfirstlane_b32 s12, v8
	s_cbranch_scc1 .LBB0_217
	s_ashr_i32 s6, s40, 31
	s_lshr_b32 s6, s6, 29
	s_add_i32 s6, s40, s6
	s_ashr_i32 s7, s6, 3
	s_and_b32 s6, s6, -8
	s_sub_i32 s6, s40, s6
	s_cmp_lt_i32 s6, 0
	s_movk_i32 s13, 0x59
	s_cselect_b32 s13, s13, 0x58
	s_mul_i32 s6, s13, s6
	s_add_i32 s6, s6, s7
	s_mul_hi_i32 s7, s6, 0x2e8ba2e9
	s_lshr_b32 s13, s7, 31
	s_ashr_i32 s7, s7, 4
	s_add_i32 s7, s7, s13
	s_lshl_b32 s13, s7, 3
	s_mulk_i32 s7, 0x58
	s_sub_i32 s6, s6, s7
	s_bfe_i32 s7, s6, 0x80000
	s_bfe_u32 s7, s7, 0x3000c
	s_add_i32 s7, s6, s7
	s_bfe_i32 s14, s7, 0x80000
	s_and_b32 s7, s7, 0xf8
	s_sub_i32 s6, s6, s7
	s_sext_i32_i16 s14, s14
	s_sext_i32_i8 s6, s6
	s_add_i32 s30, s13, s6
	s_ashr_i32 s6, s14, 3

.LBB0_226:
	ds_read_b128 v[144:147], v151
	ds_read_b128 v[158:161], v151 offset:1024
	ds_read_b128 v[162:165], v151 offset:2048
	ds_read_b128 v[166:169], v151 offset:3072
	ds_read_b128 v[170:173], v152
	ds_read_b128 v[174:177], v152 offset:1024
	ds_read_b128 v[178:181], v152 offset:2048
	ds_read_b128 v[182:185], v152 offset:3072
	s_add_u32 s36, s34, 0xfffc0080
	s_addc_u32 s37, s35, -1
	s_cmp_eq_u32 s63, 12
	s_cselect_b32 s39, s7, s37
	s_cselect_b32 s38, s19, s36
	s_cselect_b32 s37, s17, s62
	s_cselect_b32 s36, s31, s61
	v_lshl_add_u64 v[218:219], s[34:35], 0, v[138:139]
	s_add_i32 m0, s46, 0xc000
	ds_read_b128 v[186:189], v153
	ds_read_b128 v[190:193], v153 offset:1024
	ds_read_b128 v[194:197], v153 offset:2048
	ds_read_b128 v[198:201], v153 offset:3072
	ds_read_b128 v[202:205], v153 offset:4096
	ds_read_b128 v[206:209], v153 offset:5120
	ds_read_b128 v[210:213], v153 offset:6144
	ds_read_b128 v[214:217], v153 offset:7168
	global_load_lds_dwordx4 v[218:219], off
	v_lshl_add_u64 v[218:219], s[34:35], 0, v[136:137]
	s_add_i32 m0, s46, 0xe000
	s_nop 0
	global_load_lds_dwordx4 v[218:219], off
	s_waitcnt vmcnt(8)
	s_waitcnt lgkmcnt(0)
	s_barrier
	s_waitcnt lgkmcnt(0)
	v_mfma_f32_16x16x32_bf16 v[124:127], v[144:147], v[186:189], v[124:127]
	v_mfma_f32_16x16x32_bf16 v[120:123], v[162:165], v[186:189], v[120:123]
	v_mfma_f32_16x16x32_bf16 v[108:111], v[144:147], v[194:197], v[108:111]
	v_mfma_f32_16x16x32_bf16 v[104:107], v[162:165], v[194:197], v[104:107]
	v_mfma_f32_16x16x32_bf16 v[92:95], v[144:147], v[202:205], v[92:95]
	v_mfma_f32_16x16x32_bf16 v[88:91], v[162:165], v[202:205], v[88:91]
	v_mfma_f32_16x16x32_bf16 v[76:79], v[144:147], v[210:213], v[76:79]
	v_mfma_f32_16x16x32_bf16 v[72:75], v[162:165], v[210:213], v[72:75]
	v_mfma_f32_16x16x32_bf16 v[124:127], v[158:161], v[190:193], v[124:127]
	v_mfma_f32_16x16x32_bf16 v[120:123], v[166:169], v[190:193], v[120:123]
	v_mfma_f32_16x16x32_bf16 v[108:111], v[158:161], v[198:201], v[108:111]
	v_mfma_f32_16x16x32_bf16 v[104:107], v[166:169], v[198:201], v[104:107]
	v_mfma_f32_16x16x32_bf16 v[92:95], v[158:161], v[206:209], v[92:95]
	v_mfma_f32_16x16x32_bf16 v[88:91], v[166:169], v[206:209], v[88:91]
	v_mfma_f32_16x16x32_bf16 v[76:79], v[158:161], v[214:217], v[76:79]
	v_mfma_f32_16x16x32_bf16 v[72:75], v[166:169], v[214:217], v[72:75]
	v_mfma_f32_16x16x32_bf16 v[116:119], v[170:173], v[186:189], v[116:119]
	v_mfma_f32_16x16x32_bf16 v[112:115], v[178:181], v[186:189], v[112:115]
	v_mfma_f32_16x16x32_bf16 v[100:103], v[170:173], v[194:197], v[100:103]
	v_mfma_f32_16x16x32_bf16 v[96:99], v[178:181], v[194:197], v[96:99]
	v_mfma_f32_16x16x32_bf16 v[84:87], v[170:173], v[202:205], v[84:87]
	v_mfma_f32_16x16x32_bf16 v[80:83], v[178:181], v[202:205], v[80:83]
	v_mfma_f32_16x16x32_bf16 v[68:71], v[170:173], v[210:213], v[68:71]
	v_mfma_f32_16x16x32_bf16 v[64:67], v[178:181], v[210:213], v[64:67]
	v_mfma_f32_16x16x32_bf16 v[116:119], v[174:177], v[190:193], v[116:119]
	v_mfma_f32_16x16x32_bf16 v[112:115], v[182:185], v[190:193], v[112:115]
	v_mfma_f32_16x16x32_bf16 v[100:103], v[174:177], v[198:201], v[100:103]
	v_mfma_f32_16x16x32_bf16 v[96:99], v[182:185], v[198:201], v[96:99]
	v_mfma_f32_16x16x32_bf16 v[84:87], v[174:177], v[206:209], v[84:87]
	v_mfma_f32_16x16x32_bf16 v[80:83], v[182:185], v[206:209], v[80:83]
	v_mfma_f32_16x16x32_bf16 v[68:71], v[174:177], v[214:217], v[68:71]
	v_mfma_f32_16x16x32_bf16 v[64:67], v[182:185], v[214:217], v[64:67]
	s_barrier
	s_add_i32 s64, s58, s45
	v_lshl_add_u64 v[218:219], s[36:37], 0, v[130:131]
	s_mov_b32 m0, s64
	ds_read_b128 v[186:189], v153 offset:16384
	ds_read_b128 v[190:193], v153 offset:17408
	ds_read_b128 v[194:197], v153 offset:18432
	ds_read_b128 v[198:201], v153 offset:19456
	ds_read_b128 v[202:205], v153 offset:20480
	ds_read_b128 v[206:209], v153 offset:21504
	ds_read_b128 v[210:213], v153 offset:22528
	ds_read_b128 v[214:217], v153 offset:23552
	global_load_lds_dwordx4 v[218:219], off
	s_add_i32 m0, s64, 0x2000
	s_add_u32 s64, s36, 0x40000
	v_lshl_add_u64 v[220:221], s[36:37], 0, v[134:135]
	s_addc_u32 s65, s37, 0
	s_add_i32 s66, s59, s45
	global_load_lds_dwordx4 v[220:221], off
	v_lshl_add_u64 v[222:223], s[64:65], 0, v[130:131]
	s_mov_b32 m0, s66
	v_lshl_add_u64 v[224:225], s[38:39], 0, v[132:133]
	global_load_lds_dwordx4 v[222:223], off
	v_lshl_add_u64 v[222:223], s[64:65], 0, v[134:135]
	s_add_i32 m0, s66, 0x2000
	s_nop 0
	global_load_lds_dwordx4 v[222:223], off
	v_lshl_add_u64 v[222:223], s[38:39], 0, v[128:129]
	s_mov_b32 m0, s46
	s_nop 0
	global_load_lds_dwordx4 v[222:223], off
	s_mov_b32 m0, s47
	s_nop 0
	global_load_lds_dwordx4 v[224:225], off
	s_waitcnt vmcnt(8)
	s_waitcnt lgkmcnt(0)
	s_barrier
	s_waitcnt lgkmcnt(0)
	v_mfma_f32_16x16x32_bf16 v[60:63], v[144:147], v[186:189], v[60:63]
	v_mfma_f32_16x16x32_bf16 v[56:59], v[162:165], v[186:189], v[56:59]
	v_mfma_f32_16x16x32_bf16 v[44:47], v[144:147], v[194:197], v[44:47]
	v_mfma_f32_16x16x32_bf16 v[40:43], v[162:165], v[194:197], v[40:43]
	v_mfma_f32_16x16x32_bf16 v[28:31], v[144:147], v[202:205], v[28:31]
	v_mfma_f32_16x16x32_bf16 v[24:27], v[162:165], v[202:205], v[24:27]
	v_mfma_f32_16x16x32_bf16 v[12:15], v[144:147], v[210:213], v[12:15]
	v_mfma_f32_16x16x32_bf16 v[8:11], v[162:165], v[210:213], v[8:11]
	v_mfma_f32_16x16x32_bf16 v[60:63], v[158:161], v[190:193], v[60:63]
	v_mfma_f32_16x16x32_bf16 v[56:59], v[166:169], v[190:193], v[56:59]
	v_mfma_f32_16x16x32_bf16 v[44:47], v[158:161], v[198:201], v[44:47]
	v_mfma_f32_16x16x32_bf16 v[40:43], v[166:169], v[198:201], v[40:43]
	v_mfma_f32_16x16x32_bf16 v[28:31], v[158:161], v[206:209], v[28:31]
	v_mfma_f32_16x16x32_bf16 v[24:27], v[166:169], v[206:209], v[24:27]
	v_mfma_f32_16x16x32_bf16 v[12:15], v[158:161], v[214:217], v[12:15]
	v_mfma_f32_16x16x32_bf16 v[8:11], v[166:169], v[214:217], v[8:11]
	v_mfma_f32_16x16x32_bf16 v[52:55], v[170:173], v[186:189], v[52:55]
	v_mfma_f32_16x16x32_bf16 v[48:51], v[178:181], v[186:189], v[48:51]
	v_mfma_f32_16x16x32_bf16 v[36:39], v[170:173], v[194:197], v[36:39]
	v_mfma_f32_16x16x32_bf16 v[32:35], v[178:181], v[194:197], v[32:35]
	v_mfma_f32_16x16x32_bf16 v[20:23], v[170:173], v[202:205], v[20:23]
	v_mfma_f32_16x16x32_bf16 v[16:19], v[178:181], v[202:205], v[16:19]
	v_mfma_f32_16x16x32_bf16 v[4:7], v[170:173], v[210:213], v[4:7]
	v_mfma_f32_16x16x32_bf16 v[0:3], v[178:181], v[210:213], v[0:3]
	v_mfma_f32_16x16x32_bf16 v[52:55], v[174:177], v[190:193], v[52:55]
	v_mfma_f32_16x16x32_bf16 v[48:51], v[182:185], v[190:193], v[48:51]
	v_mfma_f32_16x16x32_bf16 v[36:39], v[174:177], v[198:201], v[36:39]
	v_mfma_f32_16x16x32_bf16 v[32:35], v[182:185], v[198:201], v[32:35]
	v_mfma_f32_16x16x32_bf16 v[20:23], v[174:177], v[206:209], v[20:23]
	v_mfma_f32_16x16x32_bf16 v[16:19], v[182:185], v[206:209], v[16:19]
	v_mfma_f32_16x16x32_bf16 v[4:7], v[174:177], v[214:217], v[4:7]
	v_mfma_f32_16x16x32_bf16 v[0:3], v[182:185], v[214:217], v[0:3]
	s_barrier
	s_add_i32 s64, 0, 0x18000
	v_add_u32_e32 v148, s64, v149
	s_add_i32 s65, 0, 0x1c000
	ds_read_b128 v[144:147], v148
	ds_read_b128 v[158:161], v148 offset:1024
	ds_read_b128 v[162:165], v148 offset:2048
	ds_read_b128 v[166:169], v148 offset:3072
	v_add_u32_e32 v148, s65, v149
	ds_read_b128 v[170:173], v148
	ds_read_b128 v[174:177], v148 offset:1024
	ds_read_b128 v[178:181], v148 offset:2048
	ds_read_b128 v[182:185], v148 offset:3072
	s_add_u32 s38, s38, 0x40000
	s_addc_u32 s39, s39, 0
	s_mov_b32 m0, s48
	v_lshl_add_u64 v[226:227], s[38:39], 0, v[128:129]
	ds_read_b128 v[186:189], v153 offset:32768
	ds_read_b128 v[190:193], v153 offset:33792
	ds_read_b128 v[194:197], v153 offset:34816
	ds_read_b128 v[198:201], v153 offset:35840
	ds_read_b128 v[202:205], v153 offset:36864
	ds_read_b128 v[206:209], v153 offset:37888
	ds_read_b128 v[210:213], v153 offset:38912
	ds_read_b128 v[214:217], v153 offset:39936
	global_load_lds_dwordx4 v[226:227], off
	v_lshl_add_u64 v[226:227], s[38:39], 0, v[132:133]
	s_mov_b32 m0, s49
	s_nop 0
	global_load_lds_dwordx4 v[226:227], off
	s_waitcnt vmcnt(8)
	s_waitcnt lgkmcnt(0)
	s_barrier
	s_waitcnt lgkmcnt(0)
	v_mfma_f32_16x16x32_bf16 v[124:127], v[144:147], v[186:189], v[124:127]
	v_mfma_f32_16x16x32_bf16 v[120:123], v[162:165], v[186:189], v[120:123]
	v_mfma_f32_16x16x32_bf16 v[108:111], v[144:147], v[194:197], v[108:111]
	v_mfma_f32_16x16x32_bf16 v[104:107], v[162:165], v[194:197], v[104:107]
	v_mfma_f32_16x16x32_bf16 v[92:95], v[144:147], v[202:205], v[92:95]
	v_mfma_f32_16x16x32_bf16 v[88:91], v[162:165], v[202:205], v[88:91]
	v_mfma_f32_16x16x32_bf16 v[76:79], v[144:147], v[210:213], v[76:79]
	v_mfma_f32_16x16x32_bf16 v[72:75], v[162:165], v[210:213], v[72:75]
	v_mfma_f32_16x16x32_bf16 v[124:127], v[158:161], v[190:193], v[124:127]
	v_mfma_f32_16x16x32_bf16 v[120:123], v[166:169], v[190:193], v[120:123]
	v_mfma_f32_16x16x32_bf16 v[108:111], v[158:161], v[198:201], v[108:111]
	v_mfma_f32_16x16x32_bf16 v[104:107], v[166:169], v[198:201], v[104:107]
	v_mfma_f32_16x16x32_bf16 v[92:95], v[158:161], v[206:209], v[92:95]
	v_mfma_f32_16x16x32_bf16 v[88:91], v[166:169], v[206:209], v[88:91]
	v_mfma_f32_16x16x32_bf16 v[76:79], v[158:161], v[214:217], v[76:79]
	v_mfma_f32_16x16x32_bf16 v[72:75], v[166:169], v[214:217], v[72:75]
	v_mfma_f32_16x16x32_bf16 v[116:119], v[170:173], v[186:189], v[116:119]
	v_mfma_f32_16x16x32_bf16 v[112:115], v[178:181], v[186:189], v[112:115]
	v_mfma_f32_16x16x32_bf16 v[100:103], v[170:173], v[194:197], v[100:103]
	v_mfma_f32_16x16x32_bf16 v[96:99], v[178:181], v[194:197], v[96:99]
	v_mfma_f32_16x16x32_bf16 v[84:87], v[170:173], v[202:205], v[84:87]
	v_mfma_f32_16x16x32_bf16 v[80:83], v[178:181], v[202:205], v[80:83]
	v_mfma_f32_16x16x32_bf16 v[68:71], v[170:173], v[210:213], v[68:71]
	v_mfma_f32_16x16x32_bf16 v[64:67], v[178:181], v[210:213], v[64:67]
	v_mfma_f32_16x16x32_bf16 v[116:119], v[174:177], v[190:193], v[116:119]
	v_mfma_f32_16x16x32_bf16 v[112:115], v[182:185], v[190:193], v[112:115]
	v_mfma_f32_16x16x32_bf16 v[100:103], v[174:177], v[198:201], v[100:103]
	v_mfma_f32_16x16x32_bf16 v[96:99], v[182:185], v[198:201], v[96:99]
	v_mfma_f32_16x16x32_bf16 v[84:87], v[174:177], v[206:209], v[84:87]
	v_mfma_f32_16x16x32_bf16 v[80:83], v[182:185], v[206:209], v[80:83]
	v_mfma_f32_16x16x32_bf16 v[68:71], v[174:177], v[214:217], v[68:71]
	v_mfma_f32_16x16x32_bf16 v[64:67], v[182:185], v[214:217], v[64:67]
	s_barrier
	s_add_i32 s38, s64, s45
	v_lshl_add_u64 v[218:219], v[218:219], 0, s[10:11]
	s_mov_b32 m0, s38
	ds_read_b128 v[186:189], v153 offset:49152
	ds_read_b128 v[190:193], v153 offset:50176
	ds_read_b128 v[194:197], v153 offset:51200
	ds_read_b128 v[198:201], v153 offset:52224
	ds_read_b128 v[202:205], v153 offset:53248
	ds_read_b128 v[206:209], v153 offset:54272
	ds_read_b128 v[210:213], v153 offset:55296
	ds_read_b128 v[214:217], v153 offset:56320
	global_load_lds_dwordx4 v[218:219], off
	s_add_i32 m0, s38, 0x2000
	s_add_u32 s36, s36, 0x40080
	v_lshl_add_u64 v[218:219], v[220:221], 0, s[10:11]
	s_addc_u32 s37, s37, 0
	s_add_i32 s38, s65, s45
	global_load_lds_dwordx4 v[218:219], off
	v_lshl_add_u64 v[218:219], s[36:37], 0, v[130:131]
	s_mov_b32 m0, s38
	s_nop 0
	global_load_lds_dwordx4 v[218:219], off
	v_lshl_add_u64 v[218:219], s[36:37], 0, v[134:135]
	s_add_i32 m0, s38, 0x2000
	s_nop 0
	global_load_lds_dwordx4 v[218:219], off
	v_lshl_add_u64 v[218:219], v[222:223], 0, s[10:11]
	s_mov_b32 m0, s53
	s_nop 0
	global_load_lds_dwordx4 v[218:219], off
	v_lshl_add_u64 v[218:219], v[224:225], 0, s[10:11]
	s_mov_b32 m0, s54
	s_nop 0
	global_load_lds_dwordx4 v[218:219], off
	s_waitcnt vmcnt(8)
	s_waitcnt lgkmcnt(0)
	s_barrier
	s_waitcnt lgkmcnt(0)
	v_mfma_f32_16x16x32_bf16 v[60:63], v[144:147], v[186:189], v[60:63]
	v_mfma_f32_16x16x32_bf16 v[56:59], v[162:165], v[186:189], v[56:59]
	v_mfma_f32_16x16x32_bf16 v[44:47], v[144:147], v[194:197], v[44:47]
	v_mfma_f32_16x16x32_bf16 v[40:43], v[162:165], v[194:197], v[40:43]
	v_mfma_f32_16x16x32_bf16 v[28:31], v[144:147], v[202:205], v[28:31]
	v_mfma_f32_16x16x32_bf16 v[24:27], v[162:165], v[202:205], v[24:27]
	v_mfma_f32_16x16x32_bf16 v[12:15], v[144:147], v[210:213], v[12:15]
	v_mfma_f32_16x16x32_bf16 v[8:11], v[162:165], v[210:213], v[8:11]
	v_mfma_f32_16x16x32_bf16 v[60:63], v[158:161], v[190:193], v[60:63]
	v_mfma_f32_16x16x32_bf16 v[56:59], v[166:169], v[190:193], v[56:59]
	v_mfma_f32_16x16x32_bf16 v[44:47], v[158:161], v[198:201], v[44:47]
	v_mfma_f32_16x16x32_bf16 v[40:43], v[166:169], v[198:201], v[40:43]
	v_mfma_f32_16x16x32_bf16 v[28:31], v[158:161], v[206:209], v[28:31]
	v_mfma_f32_16x16x32_bf16 v[24:27], v[166:169], v[206:209], v[24:27]
	v_mfma_f32_16x16x32_bf16 v[12:15], v[158:161], v[214:217], v[12:15]
	v_mfma_f32_16x16x32_bf16 v[8:11], v[166:169], v[214:217], v[8:11]
	v_mfma_f32_16x16x32_bf16 v[52:55], v[170:173], v[186:189], v[52:55]
	v_mfma_f32_16x16x32_bf16 v[48:51], v[178:181], v[186:189], v[48:51]
	v_mfma_f32_16x16x32_bf16 v[36:39], v[170:173], v[194:197], v[36:39]
	v_mfma_f32_16x16x32_bf16 v[32:35], v[178:181], v[194:197], v[32:35]
	v_mfma_f32_16x16x32_bf16 v[20:23], v[170:173], v[202:205], v[20:23]
	v_mfma_f32_16x16x32_bf16 v[16:19], v[178:181], v[202:205], v[16:19]
	v_mfma_f32_16x16x32_bf16 v[4:7], v[170:173], v[210:213], v[4:7]
	v_mfma_f32_16x16x32_bf16 v[0:3], v[178:181], v[210:213], v[0:3]
	v_mfma_f32_16x16x32_bf16 v[52:55], v[174:177], v[190:193], v[52:55]
	v_mfma_f32_16x16x32_bf16 v[48:51], v[182:185], v[190:193], v[48:51]
	v_mfma_f32_16x16x32_bf16 v[36:39], v[174:177], v[198:201], v[36:39]
	v_mfma_f32_16x16x32_bf16 v[32:35], v[182:185], v[198:201], v[32:35]
	v_mfma_f32_16x16x32_bf16 v[20:23], v[174:177], v[206:209], v[20:23]
	v_mfma_f32_16x16x32_bf16 v[16:19], v[182:185], v[206:209], v[16:19]
	v_mfma_f32_16x16x32_bf16 v[4:7], v[174:177], v[214:217], v[4:7]
	v_mfma_f32_16x16x32_bf16 v[0:3], v[182:185], v[214:217], v[0:3]
	s_barrier
	s_add_i32 s63, s63, 2
	s_add_u32 s61, s61, 0x100
	s_addc_u32 s62, s62, 0
	s_add_u32 s34, s34, 0x100
	s_addc_u32 s35, s35, 0
	s_cmp_gt_u32 s63, 13
	s_cbranch_scc0 .LBB0_226
	s_and_b64 vcc, exec, s[12:13]
	s_cbranch_vccz .LBB0_229
	s_barrier

.LBB0_249:
	s_mov_b64 s[6:7], s[0:1]
	s_getreg_b32 s3, hwreg(HW_REG_XCC_ID, 0, 4)
	s_setprio 0
	s_waitcnt vmcnt(0)
	s_waitcnt vmcnt(0)
	s_barrier
	s_and_saveexec_b64 s[4:5], s[20:21]
	s_cbranch_execz .LBB0_301
	s_add_i32 s8, 0, 0x23fc0
	v_mov_b32_e32 v0, s8
	s_load_dwordx2 s[6:7], s[6:7], 0x138
	s_waitcnt vmcnt(0) expcnt(0) lgkmcnt(0)
	ds_read_b32 v2, v0
	s_add_i32 s8, 0, 0x23fc4
	v_mov_b32_e32 v0, s8
	ds_read_b32 v0, v0
	s_and_b32 s3, s3, 15
	s_waitcnt lgkmcnt(1)
	v_cmp_ne_u32_e32 vcc, 0, v2
	s_cbranch_vccnz .LBB0_265
	s_load_dword s8, s[22:23], 0x14
	s_mov_b32 s56, 1
	v_mov_b32_e32 v16, 0
	s_waitcnt lgkmcnt(0)
	s_lshr_b32 s10, s8, 16
	s_and_b32 s8, s8, 0xffff
	s_cmp_lg_u32 s8, 0
	s_cselect_b64 s[8:9], -1, 0
	s_cmp_lg_u64 s[8:9], 0
	s_addc_u32 s8, s24, 0
	s_cmp_lg_u32 s10, 0
	s_mul_i32 s57, s8, s33
	s_cselect_b64 s[8:9], -1, 0
	s_cmp_lg_u64 s[8:9], 0
	s_addc_u32 s8, s25, 0
	s_mul_i32 s57, s57, s8
	s_add_u32 s8, s6, 0x4200
	s_addc_u32 s9, s7, 0
	s_add_u32 s10, s6, 0x4400
	s_addc_u32 s11, s7, 0
	s_add_u32 s12, s6, 0x4500
	s_addc_u32 s13, s7, 0
	s_add_u32 s14, s6, 0x4600
	s_addc_u32 s15, s7, 0
	s_add_u32 s16, s6, 0x4700
	s_addc_u32 s17, s7, 0
	s_add_u32 s18, s6, 0x4800
	s_addc_u32 s19, s7, 0
	s_add_u32 s26, s6, 0x4900
	s_addc_u32 s27, s7, 0
	s_add_u32 s28, s6, 0x4a00
	s_addc_u32 s29, s7, 0
	s_add_u32 s30, s6, 0x4b00
	s_addc_u32 s31, s7, 0
	s_add_u32 s34, s6, 0x4c00
	s_addc_u32 s35, s7, 0
	s_add_u32 s36, s6, 0x4d00
	s_addc_u32 s37, s7, 0
	s_add_u32 s38, s6, 0x4e00
	s_addc_u32 s39, s7, 0
	s_add_u32 s40, s6, 0x4f00
	s_addc_u32 s41, s7, 0
	s_add_u32 s42, s6, 0x5000
	s_addc_u32 s43, s7, 0
	s_add_u32 s44, s6, 0x5100
	s_addc_u32 s45, s7, 0
	s_add_u32 s46, s6, 0x5200
	s_addc_u32 s47, s7, 0
	s_add_u32 s48, s6, 0x5300
	s_addc_u32 s49, s7, 0
	s_branch .LBB0_253

.LBB0_392:
	s_mov_b64 s[6:7], s[0:1]
	s_getreg_b32 s3, hwreg(HW_REG_XCC_ID, 0, 4)
	s_setprio 0
	s_waitcnt vmcnt(0)
	s_barrier
	s_and_saveexec_b64 s[4:5], s[20:21]
	s_cbranch_execz .LBB0_444
	s_add_i32 s8, 0, 0x23fc0
	v_mov_b32_e32 v0, s8
	s_load_dwordx2 s[6:7], s[6:7], 0x138
	s_waitcnt vmcnt(0) expcnt(0) lgkmcnt(0)
	ds_read_b32 v2, v0
	s_add_i32 s8, 0, 0x23fc4
	v_mov_b32_e32 v0, s8
	ds_read_b32 v0, v0
	s_and_b32 s3, s3, 15
	s_waitcnt lgkmcnt(1)
	v_cmp_ne_u32_e32 vcc, 0, v2
	s_cbranch_vccnz .LBB0_408
	s_load_dword s8, s[22:23], 0x14
	s_mov_b32 s56, 1
	v_mov_b32_e32 v16, 0
	s_waitcnt lgkmcnt(0)
	s_lshr_b32 s10, s8, 16
	s_and_b32 s8, s8, 0xffff
	s_cmp_lg_u32 s8, 0
	s_cselect_b64 s[8:9], -1, 0
	s_cmp_lg_u64 s[8:9], 0
	s_addc_u32 s8, s24, 0
	s_cmp_lg_u32 s10, 0
	s_mul_i32 s57, s8, s33
	s_cselect_b64 s[8:9], -1, 0
	s_cmp_lg_u64 s[8:9], 0
	s_addc_u32 s8, s25, 0
	s_mul_i32 s57, s57, s8
	s_add_u32 s8, s6, 0x4200
	s_addc_u32 s9, s7, 0
	s_add_u32 s10, s6, 0x4400
	s_addc_u32 s11, s7, 0
	s_add_u32 s12, s6, 0x4500
	s_addc_u32 s13, s7, 0
	s_add_u32 s14, s6, 0x4600
	s_addc_u32 s15, s7, 0
	s_add_u32 s16, s6, 0x4700
	s_addc_u32 s17, s7, 0
	s_add_u32 s18, s6, 0x4800
	s_addc_u32 s19, s7, 0
	s_add_u32 s26, s6, 0x4900
	s_addc_u32 s27, s7, 0
	s_add_u32 s28, s6, 0x4a00
	s_addc_u32 s29, s7, 0
	s_add_u32 s30, s6, 0x4b00
	s_addc_u32 s31, s7, 0
	s_add_u32 s34, s6, 0x4c00
	s_addc_u32 s35, s7, 0
	s_add_u32 s36, s6, 0x4d00
	s_addc_u32 s37, s7, 0
	s_add_u32 s38, s6, 0x4e00
	s_addc_u32 s39, s7, 0
	s_add_u32 s40, s6, 0x4f00
	s_addc_u32 s41, s7, 0
	s_add_u32 s42, s6, 0x5000
	s_addc_u32 s43, s7, 0
	s_add_u32 s44, s6, 0x5100
	s_addc_u32 s45, s7, 0
	s_add_u32 s46, s6, 0x5200
	s_addc_u32 s47, s7, 0
	s_add_u32 s48, s6, 0x5300
	s_addc_u32 s49, s7, 0
	s_branch .LBB0_396

.LBB0_450:
	s_or_b64 exec, exec, s[4:5]
	s_mov_b64 s[6:7], s[0:1]
	s_getreg_b32 s3, hwreg(HW_REG_XCC_ID, 0, 4)
	s_setprio 0
	s_waitcnt vmcnt(0)
	s_barrier
	s_and_saveexec_b64 s[4:5], s[20:21]
	s_cbranch_execz .LBB0_502
	s_add_i32 s8, 0, 0x23fc0
	v_mov_b32_e32 v0, s8
	s_load_dwordx2 s[6:7], s[6:7], 0x138
	s_waitcnt vmcnt(0) expcnt(0) lgkmcnt(0)
	ds_read_b32 v2, v0
	s_add_i32 s8, 0, 0x23fc4
	v_mov_b32_e32 v0, s8
	ds_read_b32 v0, v0
	s_and_b32 s3, s3, 15
	s_waitcnt lgkmcnt(1)
	v_cmp_ne_u32_e32 vcc, 0, v2
	s_cbranch_vccnz .LBB0_466
	s_load_dword s8, s[22:23], 0x14
	s_mov_b32 s56, 1
	v_mov_b32_e32 v16, 0
	s_waitcnt lgkmcnt(0)
	s_lshr_b32 s10, s8, 16
	s_and_b32 s8, s8, 0xffff
	s_cmp_lg_u32 s8, 0
	s_cselect_b64 s[8:9], -1, 0
	s_cmp_lg_u64 s[8:9], 0
	s_addc_u32 s8, s24, 0
	s_cmp_lg_u32 s10, 0
	s_mul_i32 s57, s8, s33
	s_cselect_b64 s[8:9], -1, 0
	s_cmp_lg_u64 s[8:9], 0
	s_addc_u32 s8, s25, 0
	s_mul_i32 s57, s57, s8
	s_add_u32 s8, s6, 0x4200
	s_addc_u32 s9, s7, 0
	s_add_u32 s10, s6, 0x4400
	s_addc_u32 s11, s7, 0
	s_add_u32 s12, s6, 0x4500
	s_addc_u32 s13, s7, 0
	s_add_u32 s14, s6, 0x4600
	s_addc_u32 s15, s7, 0
	s_add_u32 s16, s6, 0x4700
	s_addc_u32 s17, s7, 0
	s_add_u32 s18, s6, 0x4800
	s_addc_u32 s19, s7, 0
	s_add_u32 s26, s6, 0x4900
	s_addc_u32 s27, s7, 0
	s_add_u32 s28, s6, 0x4a00
	s_addc_u32 s29, s7, 0
	s_add_u32 s30, s6, 0x4b00
	s_addc_u32 s31, s7, 0
	s_add_u32 s34, s6, 0x4c00
	s_addc_u32 s35, s7, 0
	s_add_u32 s36, s6, 0x4d00
	s_addc_u32 s37, s7, 0
	s_add_u32 s38, s6, 0x4e00
	s_addc_u32 s39, s7, 0
	s_add_u32 s40, s6, 0x4f00
	s_addc_u32 s41, s7, 0
	s_add_u32 s42, s6, 0x5000
	s_addc_u32 s43, s7, 0
	s_add_u32 s44, s6, 0x5100
	s_addc_u32 s45, s7, 0
	s_add_u32 s46, s6, 0x5200
	s_addc_u32 s47, s7, 0
	s_add_u32 s48, s6, 0x5300
	s_addc_u32 s49, s7, 0
	s_branch .LBB0_454

.LBB0_580:
	s_or_b64 exec, exec, s[4:5]
	s_mov_b64 s[4:5], s[0:1]
	s_waitcnt lgkmcnt(0)
	s_barrier
	v_readfirstlane_b32 s94, v154
	s_cmpk_ge_u32 s94, 0x100
	s_cbranch_scc1 .Lprio_skip_5
	s_setprio 1
.Lprio_skip_5:
	s_load_dwordx2 s[4:5], s[4:5], 0x138
	s_mov_b32 s3, s33
	s_mov_b32 s38, s2
	v_mov_b32_e32 v8, v154
	s_cmpk_lt_i32 s38, 0x100
	s_cselect_b64 s[6:7], -1, 0
	s_cmpk_gt_i32 s38, 0xff
	v_readfirstlane_b32 s14, v8
	s_cbranch_scc1 .LBB0_586
	s_ashr_i32 s8, s38, 31
	s_lshr_b32 s8, s8, 29
	s_add_i32 s12, s38, s8
	s_and_b32 s8, s12, -8
	s_sub_i32 s10, s38, s8
	s_cmp_gt_i32 s10, -1
	s_cbranch_scc0 .LBB0_583
	s_lshl_b32 s11, s10, 5
	s_ashr_i32 s8, s12, 3
	s_cbranch_execz .LBB0_584
	s_branch .LBB0_585

.LBB0_599:
	ds_read_b128 v[144:147], v149
	ds_read_b128 v[156:159], v149 offset:1024
	ds_read_b128 v[160:163], v149 offset:2048
	ds_read_b128 v[164:167], v149 offset:3072
	ds_read_b128 v[168:171], v150
	ds_read_b128 v[172:175], v150 offset:1024
	ds_read_b128 v[176:179], v150 offset:2048
	ds_read_b128 v[180:183], v150 offset:3072
	s_add_u32 s34, s10, 0xfffc0080
	s_addc_u32 s35, s11, -1
	s_cmp_eq_u32 s60, 12
	s_cselect_b32 s37, s9, s35
	s_cselect_b32 s36, s19, s34
	s_cselect_b32 s35, s17, s59
	s_cselect_b32 s34, s31, s58
	v_lshl_add_u64 v[216:217], s[10:11], 0, v[138:139]
	s_add_i32 m0, s44, 0xc000
	ds_read_b128 v[184:187], v151
	ds_read_b128 v[188:191], v151 offset:1024
	ds_read_b128 v[192:195], v151 offset:2048
	ds_read_b128 v[196:199], v151 offset:3072
	ds_read_b128 v[200:203], v151 offset:4096
	ds_read_b128 v[204:207], v151 offset:5120
	ds_read_b128 v[208:211], v151 offset:6144
	ds_read_b128 v[212:215], v151 offset:7168
	global_load_lds_dwordx4 v[216:217], off
	v_lshl_add_u64 v[216:217], s[10:11], 0, v[136:137]
	s_add_i32 m0, s44, 0xe000
	s_nop 0
	global_load_lds_dwordx4 v[216:217], off
	s_waitcnt vmcnt(8)
	s_waitcnt lgkmcnt(0)
	s_barrier
	s_waitcnt lgkmcnt(0)
	v_mfma_f32_16x16x32_bf16 v[124:127], v[144:147], v[184:187], v[124:127]
	v_mfma_f32_16x16x32_bf16 v[120:123], v[160:163], v[184:187], v[120:123]
	v_mfma_f32_16x16x32_bf16 v[108:111], v[144:147], v[192:195], v[108:111]
	v_mfma_f32_16x16x32_bf16 v[104:107], v[160:163], v[192:195], v[104:107]
	v_mfma_f32_16x16x32_bf16 v[92:95], v[144:147], v[200:203], v[92:95]
	v_mfma_f32_16x16x32_bf16 v[88:91], v[160:163], v[200:203], v[88:91]
	v_mfma_f32_16x16x32_bf16 v[76:79], v[144:147], v[208:211], v[76:79]
	v_mfma_f32_16x16x32_bf16 v[72:75], v[160:163], v[208:211], v[72:75]
	v_mfma_f32_16x16x32_bf16 v[124:127], v[156:159], v[188:191], v[124:127]
	v_mfma_f32_16x16x32_bf16 v[120:123], v[164:167], v[188:191], v[120:123]
	v_mfma_f32_16x16x32_bf16 v[108:111], v[156:159], v[196:199], v[108:111]
	v_mfma_f32_16x16x32_bf16 v[104:107], v[164:167], v[196:199], v[104:107]
	v_mfma_f32_16x16x32_bf16 v[92:95], v[156:159], v[204:207], v[92:95]
	v_mfma_f32_16x16x32_bf16 v[88:91], v[164:167], v[204:207], v[88:91]
	v_mfma_f32_16x16x32_bf16 v[76:79], v[156:159], v[212:215], v[76:79]
	v_mfma_f32_16x16x32_bf16 v[72:75], v[164:167], v[212:215], v[72:75]
	v_mfma_f32_16x16x32_bf16 v[116:119], v[168:171], v[184:187], v[116:119]
	v_mfma_f32_16x16x32_bf16 v[112:115], v[176:179], v[184:187], v[112:115]
	v_mfma_f32_16x16x32_bf16 v[100:103], v[168:171], v[192:195], v[100:103]
	v_mfma_f32_16x16x32_bf16 v[96:99], v[176:179], v[192:195], v[96:99]
	v_mfma_f32_16x16x32_bf16 v[84:87], v[168:171], v[200:203], v[84:87]
	v_mfma_f32_16x16x32_bf16 v[80:83], v[176:179], v[200:203], v[80:83]
	v_mfma_f32_16x16x32_bf16 v[68:71], v[168:171], v[208:211], v[68:71]
	v_mfma_f32_16x16x32_bf16 v[64:67], v[176:179], v[208:211], v[64:67]
	v_mfma_f32_16x16x32_bf16 v[116:119], v[172:175], v[188:191], v[116:119]
	v_mfma_f32_16x16x32_bf16 v[112:115], v[180:183], v[188:191], v[112:115]
	v_mfma_f32_16x16x32_bf16 v[100:103], v[172:175], v[196:199], v[100:103]
	v_mfma_f32_16x16x32_bf16 v[96:99], v[180:183], v[196:199], v[96:99]
	v_mfma_f32_16x16x32_bf16 v[84:87], v[172:175], v[204:207], v[84:87]
	v_mfma_f32_16x16x32_bf16 v[80:83], v[180:183], v[204:207], v[80:83]
	v_mfma_f32_16x16x32_bf16 v[68:71], v[172:175], v[212:215], v[68:71]
	v_mfma_f32_16x16x32_bf16 v[64:67], v[180:183], v[212:215], v[64:67]
	s_barrier
	s_add_i32 s61, s56, s43
	v_lshl_add_u64 v[216:217], s[34:35], 0, v[130:131]
	s_mov_b32 m0, s61
	ds_read_b128 v[184:187], v151 offset:16384
	ds_read_b128 v[188:191], v151 offset:17408
	ds_read_b128 v[192:195], v151 offset:18432
	ds_read_b128 v[196:199], v151 offset:19456
	ds_read_b128 v[200:203], v151 offset:20480
	ds_read_b128 v[204:207], v151 offset:21504
	ds_read_b128 v[208:211], v151 offset:22528
	ds_read_b128 v[212:215], v151 offset:23552
	global_load_lds_dwordx4 v[216:217], off
	s_add_i32 m0, s61, 0x2000
	s_add_u32 s62, s34, 0x40000
	v_lshl_add_u64 v[218:219], s[34:35], 0, v[134:135]
	s_addc_u32 s63, s35, 0
	s_add_i32 s61, s57, s43
	global_load_lds_dwordx4 v[218:219], off
	v_lshl_add_u64 v[220:221], s[62:63], 0, v[130:131]
	s_mov_b32 m0, s61
	v_lshl_add_u64 v[222:223], s[36:37], 0, v[132:133]
	global_load_lds_dwordx4 v[220:221], off
	v_lshl_add_u64 v[220:221], s[62:63], 0, v[134:135]
	s_add_i32 m0, s61, 0x2000
	s_nop 0
	global_load_lds_dwordx4 v[220:221], off
	v_lshl_add_u64 v[220:221], s[36:37], 0, v[128:129]
	s_mov_b32 m0, s44
	s_nop 0
	global_load_lds_dwordx4 v[220:221], off
	s_mov_b32 m0, s45
	s_nop 0
	global_load_lds_dwordx4 v[222:223], off
	s_waitcnt vmcnt(8)
	s_waitcnt lgkmcnt(0)
	s_barrier
	s_waitcnt lgkmcnt(0)
	v_mfma_f32_16x16x32_bf16 v[60:63], v[144:147], v[184:187], v[60:63]
	v_mfma_f32_16x16x32_bf16 v[56:59], v[160:163], v[184:187], v[56:59]
	v_mfma_f32_16x16x32_bf16 v[44:47], v[144:147], v[192:195], v[44:47]
	v_mfma_f32_16x16x32_bf16 v[40:43], v[160:163], v[192:195], v[40:43]
	v_mfma_f32_16x16x32_bf16 v[28:31], v[144:147], v[200:203], v[28:31]
	v_mfma_f32_16x16x32_bf16 v[24:27], v[160:163], v[200:203], v[24:27]
	v_mfma_f32_16x16x32_bf16 v[12:15], v[144:147], v[208:211], v[12:15]
	v_mfma_f32_16x16x32_bf16 v[8:11], v[160:163], v[208:211], v[8:11]
	v_mfma_f32_16x16x32_bf16 v[60:63], v[156:159], v[188:191], v[60:63]
	v_mfma_f32_16x16x32_bf16 v[56:59], v[164:167], v[188:191], v[56:59]
	v_mfma_f32_16x16x32_bf16 v[44:47], v[156:159], v[196:199], v[44:47]
	v_mfma_f32_16x16x32_bf16 v[40:43], v[164:167], v[196:199], v[40:43]
	v_mfma_f32_16x16x32_bf16 v[28:31], v[156:159], v[204:207], v[28:31]
	v_mfma_f32_16x16x32_bf16 v[24:27], v[164:167], v[204:207], v[24:27]
	v_mfma_f32_16x16x32_bf16 v[12:15], v[156:159], v[212:215], v[12:15]
	v_mfma_f32_16x16x32_bf16 v[8:11], v[164:167], v[212:215], v[8:11]
	v_mfma_f32_16x16x32_bf16 v[52:55], v[168:171], v[184:187], v[52:55]
	v_mfma_f32_16x16x32_bf16 v[48:51], v[176:179], v[184:187], v[48:51]
	v_mfma_f32_16x16x32_bf16 v[36:39], v[168:171], v[192:195], v[36:39]
	v_mfma_f32_16x16x32_bf16 v[32:35], v[176:179], v[192:195], v[32:35]
	v_mfma_f32_16x16x32_bf16 v[20:23], v[168:171], v[200:203], v[20:23]
	v_mfma_f32_16x16x32_bf16 v[16:19], v[176:179], v[200:203], v[16:19]
	v_mfma_f32_16x16x32_bf16 v[4:7], v[168:171], v[208:211], v[4:7]
	v_mfma_f32_16x16x32_bf16 v[0:3], v[176:179], v[208:211], v[0:3]
	v_mfma_f32_16x16x32_bf16 v[52:55], v[172:175], v[188:191], v[52:55]
	v_mfma_f32_16x16x32_bf16 v[48:51], v[180:183], v[188:191], v[48:51]
	v_mfma_f32_16x16x32_bf16 v[36:39], v[172:175], v[196:199], v[36:39]
	v_mfma_f32_16x16x32_bf16 v[32:35], v[180:183], v[196:199], v[32:35]
	v_mfma_f32_16x16x32_bf16 v[20:23], v[172:175], v[204:207], v[20:23]
	v_mfma_f32_16x16x32_bf16 v[16:19], v[180:183], v[204:207], v[16:19]
	v_mfma_f32_16x16x32_bf16 v[4:7], v[172:175], v[212:215], v[4:7]
	v_mfma_f32_16x16x32_bf16 v[0:3], v[180:183], v[212:215], v[0:3]
	s_barrier
	s_add_i32 s61, 0, 0x18000
	v_add_u32_e32 v153, s61, v148
	s_add_i32 s62, 0, 0x1c000
	ds_read_b128 v[144:147], v153
	ds_read_b128 v[156:159], v153 offset:1024
	ds_read_b128 v[160:163], v153 offset:2048
	ds_read_b128 v[164:167], v153 offset:3072
	v_add_u32_e32 v153, s62, v148
	ds_read_b128 v[168:171], v153
	ds_read_b128 v[172:175], v153 offset:1024
	ds_read_b128 v[176:179], v153 offset:2048
	ds_read_b128 v[180:183], v153 offset:3072
	s_add_u32 s36, s36, 0x40000
	s_addc_u32 s37, s37, 0
	s_mov_b32 m0, s46
	v_lshl_add_u64 v[224:225], s[36:37], 0, v[128:129]
	ds_read_b128 v[184:187], v151 offset:32768
	ds_read_b128 v[188:191], v151 offset:33792
	ds_read_b128 v[192:195], v151 offset:34816
	ds_read_b128 v[196:199], v151 offset:35840
	ds_read_b128 v[200:203], v151 offset:36864
	ds_read_b128 v[204:207], v151 offset:37888
	ds_read_b128 v[208:211], v151 offset:38912
	ds_read_b128 v[212:215], v151 offset:39936
	global_load_lds_dwordx4 v[224:225], off
	v_lshl_add_u64 v[224:225], s[36:37], 0, v[132:133]
	s_mov_b32 m0, s47
	s_nop 0
	global_load_lds_dwordx4 v[224:225], off
	s_waitcnt vmcnt(8)
	s_waitcnt lgkmcnt(0)
	s_barrier
	s_waitcnt lgkmcnt(0)
	v_mfma_f32_16x16x32_bf16 v[124:127], v[144:147], v[184:187], v[124:127]
	v_mfma_f32_16x16x32_bf16 v[120:123], v[160:163], v[184:187], v[120:123]
	v_mfma_f32_16x16x32_bf16 v[108:111], v[144:147], v[192:195], v[108:111]
	v_mfma_f32_16x16x32_bf16 v[104:107], v[160:163], v[192:195], v[104:107]
	v_mfma_f32_16x16x32_bf16 v[92:95], v[144:147], v[200:203], v[92:95]
	v_mfma_f32_16x16x32_bf16 v[88:91], v[160:163], v[200:203], v[88:91]
	v_mfma_f32_16x16x32_bf16 v[76:79], v[144:147], v[208:211], v[76:79]
	v_mfma_f32_16x16x32_bf16 v[72:75], v[160:163], v[208:211], v[72:75]
	v_mfma_f32_16x16x32_bf16 v[124:127], v[156:159], v[188:191], v[124:127]
	v_mfma_f32_16x16x32_bf16 v[120:123], v[164:167], v[188:191], v[120:123]
	v_mfma_f32_16x16x32_bf16 v[108:111], v[156:159], v[196:199], v[108:111]
	v_mfma_f32_16x16x32_bf16 v[104:107], v[164:167], v[196:199], v[104:107]
	v_mfma_f32_16x16x32_bf16 v[92:95], v[156:159], v[204:207], v[92:95]
	v_mfma_f32_16x16x32_bf16 v[88:91], v[164:167], v[204:207], v[88:91]
	v_mfma_f32_16x16x32_bf16 v[76:79], v[156:159], v[212:215], v[76:79]
	v_mfma_f32_16x16x32_bf16 v[72:75], v[164:167], v[212:215], v[72:75]
	v_mfma_f32_16x16x32_bf16 v[116:119], v[168:171], v[184:187], v[116:119]
	v_mfma_f32_16x16x32_bf16 v[112:115], v[176:179], v[184:187], v[112:115]
	v_mfma_f32_16x16x32_bf16 v[100:103], v[168:171], v[192:195], v[100:103]
	v_mfma_f32_16x16x32_bf16 v[96:99], v[176:179], v[192:195], v[96:99]
	v_mfma_f32_16x16x32_bf16 v[84:87], v[168:171], v[200:203], v[84:87]
	v_mfma_f32_16x16x32_bf16 v[80:83], v[176:179], v[200:203], v[80:83]
	v_mfma_f32_16x16x32_bf16 v[68:71], v[168:171], v[208:211], v[68:71]
	v_mfma_f32_16x16x32_bf16 v[64:67], v[176:179], v[208:211], v[64:67]
	v_mfma_f32_16x16x32_bf16 v[116:119], v[172:175], v[188:191], v[116:119]
	v_mfma_f32_16x16x32_bf16 v[112:115], v[180:183], v[188:191], v[112:115]
	v_mfma_f32_16x16x32_bf16 v[100:103], v[172:175], v[196:199], v[100:103]
	v_mfma_f32_16x16x32_bf16 v[96:99], v[180:183], v[196:199], v[96:99]
	v_mfma_f32_16x16x32_bf16 v[84:87], v[172:175], v[204:207], v[84:87]
	v_mfma_f32_16x16x32_bf16 v[80:83], v[180:183], v[204:207], v[80:83]
	v_mfma_f32_16x16x32_bf16 v[68:71], v[172:175], v[212:215], v[68:71]
	v_mfma_f32_16x16x32_bf16 v[64:67], v[180:183], v[212:215], v[64:67]
	s_barrier
	s_add_i32 s36, s61, s43
	v_lshl_add_u64 v[216:217], v[216:217], 0, s[12:13]
	s_mov_b32 m0, s36
	ds_read_b128 v[184:187], v151 offset:49152
	ds_read_b128 v[188:191], v151 offset:50176
	ds_read_b128 v[192:195], v151 offset:51200
	ds_read_b128 v[196:199], v151 offset:52224
	ds_read_b128 v[200:203], v151 offset:53248
	ds_read_b128 v[204:207], v151 offset:54272
	ds_read_b128 v[208:211], v151 offset:55296
	ds_read_b128 v[212:215], v151 offset:56320
	global_load_lds_dwordx4 v[216:217], off
	s_add_i32 m0, s36, 0x2000
	s_add_u32 s34, s34, 0x40080
	v_lshl_add_u64 v[216:217], v[218:219], 0, s[12:13]
	s_addc_u32 s35, s35, 0
	s_add_i32 s36, s62, s43
	global_load_lds_dwordx4 v[216:217], off
	v_lshl_add_u64 v[216:217], s[34:35], 0, v[130:131]
	s_mov_b32 m0, s36
	s_nop 0
	global_load_lds_dwordx4 v[216:217], off
	v_lshl_add_u64 v[216:217], s[34:35], 0, v[134:135]
	s_add_i32 m0, s36, 0x2000
	s_nop 0
	global_load_lds_dwordx4 v[216:217], off
	v_lshl_add_u64 v[216:217], v[220:221], 0, s[12:13]
	s_mov_b32 m0, s52
	s_nop 0
	global_load_lds_dwordx4 v[216:217], off
	v_lshl_add_u64 v[216:217], v[222:223], 0, s[12:13]
	s_mov_b32 m0, s53
	s_nop 0
	global_load_lds_dwordx4 v[216:217], off
	s_waitcnt vmcnt(8)
	s_waitcnt lgkmcnt(0)
	s_barrier
	s_waitcnt lgkmcnt(0)
	v_mfma_f32_16x16x32_bf16 v[60:63], v[144:147], v[184:187], v[60:63]
	v_mfma_f32_16x16x32_bf16 v[56:59], v[160:163], v[184:187], v[56:59]
	v_mfma_f32_16x16x32_bf16 v[44:47], v[144:147], v[192:195], v[44:47]
	v_mfma_f32_16x16x32_bf16 v[40:43], v[160:163], v[192:195], v[40:43]
	v_mfma_f32_16x16x32_bf16 v[28:31], v[144:147], v[200:203], v[28:31]
	v_mfma_f32_16x16x32_bf16 v[24:27], v[160:163], v[200:203], v[24:27]
	v_mfma_f32_16x16x32_bf16 v[12:15], v[144:147], v[208:211], v[12:15]
	v_mfma_f32_16x16x32_bf16 v[8:11], v[160:163], v[208:211], v[8:11]
	v_mfma_f32_16x16x32_bf16 v[60:63], v[156:159], v[188:191], v[60:63]
	v_mfma_f32_16x16x32_bf16 v[56:59], v[164:167], v[188:191], v[56:59]
	v_mfma_f32_16x16x32_bf16 v[44:47], v[156:159], v[196:199], v[44:47]
	v_mfma_f32_16x16x32_bf16 v[40:43], v[164:167], v[196:199], v[40:43]
	v_mfma_f32_16x16x32_bf16 v[28:31], v[156:159], v[204:207], v[28:31]
	v_mfma_f32_16x16x32_bf16 v[24:27], v[164:167], v[204:207], v[24:27]
	v_mfma_f32_16x16x32_bf16 v[12:15], v[156:159], v[212:215], v[12:15]
	v_mfma_f32_16x16x32_bf16 v[8:11], v[164:167], v[212:215], v[8:11]
	v_mfma_f32_16x16x32_bf16 v[52:55], v[168:171], v[184:187], v[52:55]
	v_mfma_f32_16x16x32_bf16 v[48:51], v[176:179], v[184:187], v[48:51]
	v_mfma_f32_16x16x32_bf16 v[36:39], v[168:171], v[192:195], v[36:39]
	v_mfma_f32_16x16x32_bf16 v[32:35], v[176:179], v[192:195], v[32:35]
	v_mfma_f32_16x16x32_bf16 v[20:23], v[168:171], v[200:203], v[20:23]
	v_mfma_f32_16x16x32_bf16 v[16:19], v[176:179], v[200:203], v[16:19]
	v_mfma_f32_16x16x32_bf16 v[4:7], v[168:171], v[208:211], v[4:7]
	v_mfma_f32_16x16x32_bf16 v[0:3], v[176:179], v[208:211], v[0:3]
	v_mfma_f32_16x16x32_bf16 v[52:55], v[172:175], v[188:191], v[52:55]
	v_mfma_f32_16x16x32_bf16 v[48:51], v[180:183], v[188:191], v[48:51]
	v_mfma_f32_16x16x32_bf16 v[36:39], v[172:175], v[196:199], v[36:39]
	v_mfma_f32_16x16x32_bf16 v[32:35], v[180:183], v[196:199], v[32:35]
	v_mfma_f32_16x16x32_bf16 v[20:23], v[172:175], v[204:207], v[20:23]
	v_mfma_f32_16x16x32_bf16 v[16:19], v[180:183], v[204:207], v[16:19]
	v_mfma_f32_16x16x32_bf16 v[4:7], v[172:175], v[212:215], v[4:7]
	v_mfma_f32_16x16x32_bf16 v[0:3], v[180:183], v[212:215], v[0:3]
	s_barrier
	s_add_i32 s60, s60, 2
	s_add_u32 s58, s58, 0x100
	s_addc_u32 s59, s59, 0
	s_add_u32 s10, s10, 0x100
	s_addc_u32 s11, s11, 0
	s_cmp_gt_u32 s60, 13
	s_cbranch_scc0 .LBB0_599
	s_and_b64 vcc, exec, s[14:15]
	s_cbranch_vccz .LBB0_602
	s_barrier

.LBB0_622:
	s_mov_b64 s[6:7], s[0:1]
	s_getreg_b32 s3, hwreg(HW_REG_XCC_ID, 0, 4)
	s_setprio 0
	s_waitcnt vmcnt(0)
	s_waitcnt lgkmcnt(0)
	s_barrier
	s_and_saveexec_b64 s[4:5], s[20:21]
	s_cbranch_execz .LBB0_674
	s_add_i32 s8, 0, 0x23fc0
	v_mov_b32_e32 v0, s8
	s_load_dwordx2 s[6:7], s[6:7], 0x138
	s_waitcnt vmcnt(0) expcnt(0) lgkmcnt(0)
	ds_read_b32 v2, v0
	s_add_i32 s8, 0, 0x23fc4
	v_mov_b32_e32 v0, s8
	ds_read_b32 v0, v0
	s_and_b32 s3, s3, 15
	s_waitcnt lgkmcnt(1)
	v_cmp_ne_u32_e32 vcc, 0, v2
	s_cbranch_vccnz .LBB0_638
	s_load_dword s8, s[22:23], 0x14
	s_mov_b32 s56, 1
	v_mov_b32_e32 v16, 0
	s_waitcnt lgkmcnt(0)
	s_lshr_b32 s10, s8, 16
	s_and_b32 s8, s8, 0xffff
	s_cmp_lg_u32 s8, 0
	s_cselect_b64 s[8:9], -1, 0
	s_cmp_lg_u64 s[8:9], 0
	s_addc_u32 s8, s24, 0
	s_cmp_lg_u32 s10, 0
	s_mul_i32 s57, s8, s33
	s_cselect_b64 s[8:9], -1, 0
	s_cmp_lg_u64 s[8:9], 0
	s_addc_u32 s8, s25, 0
	s_mul_i32 s57, s57, s8
	s_add_u32 s8, s6, 0x4200
	s_addc_u32 s9, s7, 0
	s_add_u32 s10, s6, 0x4400
	s_addc_u32 s11, s7, 0
	s_add_u32 s12, s6, 0x4500
	s_addc_u32 s13, s7, 0
	s_add_u32 s14, s6, 0x4600
	s_addc_u32 s15, s7, 0
	s_add_u32 s16, s6, 0x4700
	s_addc_u32 s17, s7, 0
	s_add_u32 s18, s6, 0x4800
	s_addc_u32 s19, s7, 0
	s_add_u32 s26, s6, 0x4900
	s_addc_u32 s27, s7, 0
	s_add_u32 s28, s6, 0x4a00
	s_addc_u32 s29, s7, 0
	s_add_u32 s30, s6, 0x4b00
	s_addc_u32 s31, s7, 0
	s_add_u32 s34, s6, 0x4c00
	s_addc_u32 s35, s7, 0
	s_add_u32 s36, s6, 0x4d00
	s_addc_u32 s37, s7, 0
	s_add_u32 s38, s6, 0x4e00
	s_addc_u32 s39, s7, 0
	s_add_u32 s40, s6, 0x4f00
	s_addc_u32 s41, s7, 0
	s_add_u32 s42, s6, 0x5000
	s_addc_u32 s43, s7, 0
	s_add_u32 s44, s6, 0x5100
	s_addc_u32 s45, s7, 0
	s_add_u32 s46, s6, 0x5200
	s_addc_u32 s47, s7, 0
	s_add_u32 s48, s6, 0x5300
	s_addc_u32 s49, s7, 0
	s_branch .LBB0_626

.LBB0_674:
	s_or_b64 exec, exec, s[4:5]
	s_mov_b32 s100, 0
	s_mov_b64 s[4:5], s[0:1]
	s_mov_b64 s[8:9], s[0:1]
	s_mov_b32 s3, s33
	s_mov_b32 s40, s2
	v_mov_b32_e32 v8, v154
	s_waitcnt lgkmcnt(0)
	s_barrier
	v_readfirstlane_b32 s94, v154
	s_cmpk_ge_u32 s94, 0x100
	s_cbranch_scc1 .Lprio_skip_6
	s_setprio 1
.Lprio_skip_6:
	s_cmpk_gt_i32 s40, 0x57f
	v_readfirstlane_b32 s12, v8
	s_cbranch_scc1 .LBB0_690
	v_lshlrev_b32_e32 v0, 4, v8
	v_add_u32_e32 v1, 0x2000, v0
	v_ashrrev_i32_e32 v2, 31, v1
	v_lshrrev_b32_e32 v2, 22, v2
	v_add_u32_e32 v2, v1, v2
	v_ashrrev_i32_e32 v9, 10, v2
	v_mul_i32_i24_e32 v2, 0x400, v9
	v_sub_u32_e32 v1, v1, v2
	v_lshrrev_b32_e32 v2, 4, v1
	v_bitop3_b32 v1, v2, v1, 32 bitop3:0x6c
	v_ashrrev_i32_e32 v2, 31, v1
	v_lshrrev_b32_e32 v2, 26, v2
	v_add_u32_e32 v2, v1, v2
	v_lshlrev_b32_e32 v3, 3, v9
	v_ashrrev_i32_e32 v10, 6, v2
	v_and_b32_e32 v3, -16, v3
	v_add_u32_e32 v3, v10, v3
	s_load_dwordx2 s[10:11], s[8:9], 0x138
	s_load_dwordx2 s[6:7], s[4:5], 0x130
	v_and_b32_e32 v4, 3, v10
	s_mov_b32 s4, 0x1fffe0
	v_lshrrev_b32_e32 v5, 2, v3
	v_lshlrev_b32_e32 v6, 1, v3
	v_and_b32_e32 v2, 0xc0, v2
	v_and_or_b32 v4, v3, s4, v4
	v_and_b32_e32 v5, 4, v5
	v_and_b32_e32 v6, 24, v6
	v_sub_u32_e32 v1, v1, v2
	v_mov_b32_e32 v2, 1
	v_or3_b32 v4, v4, v5, v6
	v_lshlrev_b32_e32 v5, 5, v9
	v_ashrrev_i16_sdwa v1, v2, sext(v1) dst_sel:DWORD dst_unused:UNUSED_PAD src0_sel:DWORD src1_sel:BYTE_0
	v_and_b32_e32 v5, 32, v5
	v_bfe_i32 v11, v1, 0, 16
	v_add_lshl_u32 v1, v5, v11, 1
	v_lshl_add_u32 v128, v4, 11, v1
	v_lshl_add_u32 v130, v3, 11, v1
	v_bfe_i32 v1, v8, 27, 1
	v_lshrrev_b32_e32 v1, 22, v1
	v_add_u32_e32 v1, v0, v1
	v_and_b32_e32 v1, 0xfffffc00, v1
	v_sub_u32_e32 v0, v0, v1
	v_lshrrev_b32_e32 v1, 4, v0
	v_ashrrev_i32_e32 v3, 31, v8
	v_bitop3_b32 v0, v1, v0, 32 bitop3:0x6c
	v_lshrrev_b32_e32 v3, 26, v3
	v_ashrrev_i32_e32 v1, 31, v0
	v_add_u32_e32 v3, v8, v3
	v_lshrrev_b32_e32 v1, 26, v1
	v_ashrrev_i32_e32 v13, 6, v3
	v_add_u32_e32 v1, v0, v1
	v_lshlrev_b32_e32 v3, 3, v13
	s_waitcnt lgkmcnt(0)
	s_add_u32 s41, s10, 0xa80000
	v_ashrrev_i32_e32 v12, 6, v1
	v_and_b32_e32 v3, -16, v3
	s_addc_u32 s42, s11, 0
	v_add_u32_e32 v3, v12, v3
	v_and_b32_e32 v4, 3, v12
	s_ashr_i32 s44, s40, 31
	v_and_or_b32 v4, v3, s4, v4
	s_lshr_b32 s4, s44, 29
	s_add_i32 s4, s40, s4
	s_ashr_i32 s10, s12, 6
	s_ashr_i32 s8, s4, 3
	s_and_b32 s4, s4, -8
	s_ashr_i32 s5, s12, 8
	s_lshl_b32 s43, s10, 10
	s_sub_i32 s4, s40, s4
	s_cmp_lt_i32 s4, 0
	s_movk_i32 s45, 0xb1
	s_cselect_b32 s9, s45, 0xb0
	s_mul_i32 s4, s9, s4
	s_add_i32 s4, s4, s8
	s_mul_hi_i32 s8, s4, 0x2e8ba2e9
	s_lshr_b32 s9, s8, 31
	s_ashr_i32 s8, s8, 5
	s_add_i32 s8, s8, s9
	s_lshl_b32 s9, s8, 3
	s_mulk_i32 s8, 0xb0
	s_sub_i32 s8, s4, s8
	s_bfe_u32 s4, s8, 0x3001c
	s_add_i32 s11, s8, s4
	s_sext_i32_i16 s4, s11
	s_and_b32 s11, s11, 0xfff8
	s_sub_i32 s8, s8, s11
	s_sext_i32_i16 s8, s8
	v_lshrrev_b32_e32 v5, 2, v3
	v_lshlrev_b32_e32 v6, 1, v3
	v_and_b32_e32 v1, 0xc0, v1
	s_lshr_b32 s4, s4, 3
	s_add_i32 s34, s9, s8
	v_and_b32_e32 v5, 4, v5
	v_and_b32_e32 v6, 24, v6
	v_sub_u32_e32 v0, v0, v1
	s_ashr_i32 s35, s34, 31
	s_bfe_i64 s[14:15], s[4:5], 0x100000
	v_or3_b32 v4, v4, v5, v6
	v_lshlrev_b32_e32 v5, 5, v13
	v_ashrrev_i16_sdwa v0, v2, sext(v0) dst_sel:DWORD dst_unused:UNUSED_PAD src0_sel:DWORD src1_sel:BYTE_0
	s_lshl_b64 s[8:9], s[34:35], 19
	s_lshl_b64 s[14:15], s[14:15], 19
	v_and_b32_e32 v5, 32, v5
	v_bfe_i32 v14, v0, 0, 16
	s_add_u32 s30, s41, s14
	v_add_lshl_u32 v0, v5, v14, 1
	s_addc_u32 s31, s42, s15
	s_add_i32 s35, s43, 0
	v_lshl_add_u32 v132, v4, 11, v0
	s_add_i32 m0, s35, 0x10000
	v_lshl_add_u32 v134, v3, 11, v0
	global_load_lds_dwordx4 v132, s[30:31]
	s_add_i32 m0, s35, 0x12000
	s_add_u32 s14, s30, 0x40000
	global_load_lds_dwordx4 v128, s[30:31]
	s_addc_u32 s15, s31, 0
	s_add_i32 m0, s35, 0x14000
	v_mov_b32_e32 v133, 0
	global_load_lds_dwordx4 v132, s[14:15]
	s_add_i32 m0, s35, 0x16000
	s_add_u32 s36, s6, s8
	s_addc_u32 s37, s7, s9
	s_add_i32 s46, s35, 0x2000
	global_load_lds_dwordx4 v128, s[14:15]
	s_mov_b32 m0, s35
	s_add_u32 s8, s36, 0x40000
	global_load_lds_dwordx4 v134, s[36:37]
	s_mov_b32 m0, s46
	s_addc_u32 s9, s37, 0
	s_add_i32 s47, s35, 0x4000
	global_load_lds_dwordx4 v130, s[36:37]
	s_mov_b32 m0, s47
	s_add_i32 s48, s35, 0x6000
	global_load_lds_dwordx4 v134, s[8:9]
	s_mov_b32 m0, s48
	v_mov_b32_e32 v129, v133
	global_load_lds_dwordx4 v130, s[8:9]
	v_mov_b32_e32 v135, v133
	v_mov_b32_e32 v131, v133
	s_cmp_eq_u32 s5, 1
	s_mov_b32 s49, 0
	v_lshl_add_u64 v[6:7], s[30:31], 0, v[132:133]
	v_lshl_add_u64 v[4:5], s[30:31], 0, v[128:129]
	v_lshl_add_u64 v[0:1], s[36:37], 0, v[134:135]
	s_cselect_b64 s[8:9], -1, 0
	s_cmp_lg_u32 s5, 1
	v_lshl_add_u64 v[2:3], s[36:37], 0, v[130:131]
	s_cbranch_scc1 .LBB0_677
	s_barrier

.LBB0_683:
	ds_read_b128 v[144:147], v149
	ds_read_b128 v[156:159], v149 offset:1024
	ds_read_b128 v[160:163], v149 offset:2048
	ds_read_b128 v[164:167], v149 offset:3072
	ds_read_b128 v[168:171], v150
	ds_read_b128 v[172:175], v150 offset:1024
	ds_read_b128 v[176:179], v150 offset:2048
	ds_read_b128 v[180:183], v150 offset:3072
	s_add_u32 s36, s30, 0xfffc0080
	s_addc_u32 s37, s31, -1
	s_cmp_eq_u32 s63, 12
	s_cselect_b32 s39, s19, s37
	s_cselect_b32 s38, s59, s36
	s_cselect_b32 s37, s17, s62
	s_cselect_b32 s36, s60, s61
	v_lshl_add_u64 v[216:217], s[30:31], 0, v[138:139]
	s_add_i32 m0, s35, 0xc000
	ds_read_b128 v[184:187], v151
	ds_read_b128 v[188:191], v151 offset:1024
	ds_read_b128 v[192:195], v151 offset:2048
	ds_read_b128 v[196:199], v151 offset:3072
	ds_read_b128 v[200:203], v151 offset:4096
	ds_read_b128 v[204:207], v151 offset:5120
	ds_read_b128 v[208:211], v151 offset:6144
	ds_read_b128 v[212:215], v151 offset:7168
	global_load_lds_dwordx4 v[216:217], off
	v_lshl_add_u64 v[216:217], s[30:31], 0, v[136:137]
	s_add_i32 m0, s35, 0xe000
	s_nop 0
	global_load_lds_dwordx4 v[216:217], off
	s_waitcnt vmcnt(8)
	s_waitcnt lgkmcnt(0)
	s_barrier
	s_waitcnt lgkmcnt(0)
	v_mfma_f32_16x16x32_bf16 v[124:127], v[144:147], v[184:187], v[124:127]
	v_mfma_f32_16x16x32_bf16 v[120:123], v[160:163], v[184:187], v[120:123]
	v_mfma_f32_16x16x32_bf16 v[108:111], v[144:147], v[192:195], v[108:111]
	v_mfma_f32_16x16x32_bf16 v[104:107], v[160:163], v[192:195], v[104:107]
	v_mfma_f32_16x16x32_bf16 v[92:95], v[144:147], v[200:203], v[92:95]
	v_mfma_f32_16x16x32_bf16 v[88:91], v[160:163], v[200:203], v[88:91]
	v_mfma_f32_16x16x32_bf16 v[76:79], v[144:147], v[208:211], v[76:79]
	v_mfma_f32_16x16x32_bf16 v[72:75], v[160:163], v[208:211], v[72:75]
	v_mfma_f32_16x16x32_bf16 v[124:127], v[156:159], v[188:191], v[124:127]
	v_mfma_f32_16x16x32_bf16 v[120:123], v[164:167], v[188:191], v[120:123]
	v_mfma_f32_16x16x32_bf16 v[108:111], v[156:159], v[196:199], v[108:111]
	v_mfma_f32_16x16x32_bf16 v[104:107], v[164:167], v[196:199], v[104:107]
	v_mfma_f32_16x16x32_bf16 v[92:95], v[156:159], v[204:207], v[92:95]
	v_mfma_f32_16x16x32_bf16 v[88:91], v[164:167], v[204:207], v[88:91]
	v_mfma_f32_16x16x32_bf16 v[76:79], v[156:159], v[212:215], v[76:79]
	v_mfma_f32_16x16x32_bf16 v[72:75], v[164:167], v[212:215], v[72:75]
	v_mfma_f32_16x16x32_bf16 v[116:119], v[168:171], v[184:187], v[116:119]
	v_mfma_f32_16x16x32_bf16 v[112:115], v[176:179], v[184:187], v[112:115]
	v_mfma_f32_16x16x32_bf16 v[100:103], v[168:171], v[192:195], v[100:103]
	v_mfma_f32_16x16x32_bf16 v[96:99], v[176:179], v[192:195], v[96:99]
	v_mfma_f32_16x16x32_bf16 v[84:87], v[168:171], v[200:203], v[84:87]
	v_mfma_f32_16x16x32_bf16 v[80:83], v[176:179], v[200:203], v[80:83]
	v_mfma_f32_16x16x32_bf16 v[68:71], v[168:171], v[208:211], v[68:71]
	v_mfma_f32_16x16x32_bf16 v[64:67], v[176:179], v[208:211], v[64:67]
	v_mfma_f32_16x16x32_bf16 v[116:119], v[172:175], v[188:191], v[116:119]
	v_mfma_f32_16x16x32_bf16 v[112:115], v[180:183], v[188:191], v[112:115]
	v_mfma_f32_16x16x32_bf16 v[100:103], v[172:175], v[196:199], v[100:103]
	v_mfma_f32_16x16x32_bf16 v[96:99], v[180:183], v[196:199], v[96:99]
	v_mfma_f32_16x16x32_bf16 v[84:87], v[172:175], v[204:207], v[84:87]
	v_mfma_f32_16x16x32_bf16 v[80:83], v[180:183], v[204:207], v[80:83]
	v_mfma_f32_16x16x32_bf16 v[68:71], v[172:175], v[212:215], v[68:71]
	v_mfma_f32_16x16x32_bf16 v[64:67], v[180:183], v[212:215], v[64:67]
	s_barrier
	s_add_i32 s64, s55, s43
	v_lshl_add_u64 v[216:217], s[36:37], 0, v[132:133]
	s_mov_b32 m0, s64
	ds_read_b128 v[184:187], v151 offset:16384
	ds_read_b128 v[188:191], v151 offset:17408
	ds_read_b128 v[192:195], v151 offset:18432
	ds_read_b128 v[196:199], v151 offset:19456
	ds_read_b128 v[200:203], v151 offset:20480
	ds_read_b128 v[204:207], v151 offset:21504
	ds_read_b128 v[208:211], v151 offset:22528
	ds_read_b128 v[212:215], v151 offset:23552
	global_load_lds_dwordx4 v[216:217], off
	s_add_i32 m0, s64, 0x2000
	s_add_u32 s64, s36, 0x40000
	v_lshl_add_u64 v[218:219], s[36:37], 0, v[128:129]
	s_addc_u32 s65, s37, 0
	s_add_i32 s66, s56, s43
	global_load_lds_dwordx4 v[218:219], off
	v_lshl_add_u64 v[220:221], s[64:65], 0, v[132:133]
	s_mov_b32 m0, s66
	v_lshl_add_u64 v[222:223], s[38:39], 0, v[130:131]
	global_load_lds_dwordx4 v[220:221], off
	v_lshl_add_u64 v[220:221], s[64:65], 0, v[128:129]
	s_add_i32 m0, s66, 0x2000
	s_nop 0
	global_load_lds_dwordx4 v[220:221], off
	v_lshl_add_u64 v[220:221], s[38:39], 0, v[134:135]
	s_mov_b32 m0, s35
	s_nop 0
	global_load_lds_dwordx4 v[220:221], off
	s_mov_b32 m0, s46
	s_nop 0
	global_load_lds_dwordx4 v[222:223], off
	s_waitcnt vmcnt(8)
	s_waitcnt lgkmcnt(0)
	s_barrier
	s_waitcnt lgkmcnt(0)
	v_mfma_f32_16x16x32_bf16 v[60:63], v[144:147], v[184:187], v[60:63]
	v_mfma_f32_16x16x32_bf16 v[56:59], v[160:163], v[184:187], v[56:59]
	v_mfma_f32_16x16x32_bf16 v[44:47], v[144:147], v[192:195], v[44:47]
	v_mfma_f32_16x16x32_bf16 v[40:43], v[160:163], v[192:195], v[40:43]
	v_mfma_f32_16x16x32_bf16 v[28:31], v[144:147], v[200:203], v[28:31]
	v_mfma_f32_16x16x32_bf16 v[24:27], v[160:163], v[200:203], v[24:27]
	v_mfma_f32_16x16x32_bf16 v[12:15], v[144:147], v[208:211], v[12:15]
	v_mfma_f32_16x16x32_bf16 v[8:11], v[160:163], v[208:211], v[8:11]
	v_mfma_f32_16x16x32_bf16 v[60:63], v[156:159], v[188:191], v[60:63]
	v_mfma_f32_16x16x32_bf16 v[56:59], v[164:167], v[188:191], v[56:59]
	v_mfma_f32_16x16x32_bf16 v[44:47], v[156:159], v[196:199], v[44:47]
	v_mfma_f32_16x16x32_bf16 v[40:43], v[164:167], v[196:199], v[40:43]
	v_mfma_f32_16x16x32_bf16 v[28:31], v[156:159], v[204:207], v[28:31]
	v_mfma_f32_16x16x32_bf16 v[24:27], v[164:167], v[204:207], v[24:27]
	v_mfma_f32_16x16x32_bf16 v[12:15], v[156:159], v[212:215], v[12:15]
	v_mfma_f32_16x16x32_bf16 v[8:11], v[164:167], v[212:215], v[8:11]
	v_mfma_f32_16x16x32_bf16 v[52:55], v[168:171], v[184:187], v[52:55]
	v_mfma_f32_16x16x32_bf16 v[48:51], v[176:179], v[184:187], v[48:51]
	v_mfma_f32_16x16x32_bf16 v[36:39], v[168:171], v[192:195], v[36:39]
	v_mfma_f32_16x16x32_bf16 v[32:35], v[176:179], v[192:195], v[32:35]
	v_mfma_f32_16x16x32_bf16 v[20:23], v[168:171], v[200:203], v[20:23]
	v_mfma_f32_16x16x32_bf16 v[16:19], v[176:179], v[200:203], v[16:19]
	v_mfma_f32_16x16x32_bf16 v[4:7], v[168:171], v[208:211], v[4:7]
	v_mfma_f32_16x16x32_bf16 v[0:3], v[176:179], v[208:211], v[0:3]
	v_mfma_f32_16x16x32_bf16 v[52:55], v[172:175], v[188:191], v[52:55]
	v_mfma_f32_16x16x32_bf16 v[48:51], v[180:183], v[188:191], v[48:51]
	v_mfma_f32_16x16x32_bf16 v[36:39], v[172:175], v[196:199], v[36:39]
	v_mfma_f32_16x16x32_bf16 v[32:35], v[180:183], v[196:199], v[32:35]
	v_mfma_f32_16x16x32_bf16 v[20:23], v[172:175], v[204:207], v[20:23]
	v_mfma_f32_16x16x32_bf16 v[16:19], v[180:183], v[204:207], v[16:19]
	v_mfma_f32_16x16x32_bf16 v[4:7], v[172:175], v[212:215], v[4:7]
	v_mfma_f32_16x16x32_bf16 v[0:3], v[180:183], v[212:215], v[0:3]
	s_barrier
	s_add_i32 s64, 0, 0x18000
	v_add_u32_e32 v153, s64, v148
	s_add_i32 s65, 0, 0x1c000
	ds_read_b128 v[144:147], v153
	ds_read_b128 v[156:159], v153 offset:1024
	ds_read_b128 v[160:163], v153 offset:2048
	ds_read_b128 v[164:167], v153 offset:3072
	v_add_u32_e32 v153, s65, v148
	ds_read_b128 v[168:171], v153
	ds_read_b128 v[172:175], v153 offset:1024
	ds_read_b128 v[176:179], v153 offset:2048
	ds_read_b128 v[180:183], v153 offset:3072
	s_add_u32 s38, s38, 0x40000
	s_addc_u32 s39, s39, 0
	s_mov_b32 m0, s47
	v_lshl_add_u64 v[224:225], s[38:39], 0, v[134:135]
	ds_read_b128 v[184:187], v151 offset:32768
	ds_read_b128 v[188:191], v151 offset:33792
	ds_read_b128 v[192:195], v151 offset:34816
	ds_read_b128 v[196:199], v151 offset:35840
	ds_read_b128 v[200:203], v151 offset:36864
	ds_read_b128 v[204:207], v151 offset:37888
	ds_read_b128 v[208:211], v151 offset:38912
	ds_read_b128 v[212:215], v151 offset:39936
	global_load_lds_dwordx4 v[224:225], off
	v_lshl_add_u64 v[224:225], s[38:39], 0, v[130:131]
	s_mov_b32 m0, s48
	s_nop 0
	global_load_lds_dwordx4 v[224:225], off
	s_waitcnt vmcnt(8)
	s_waitcnt lgkmcnt(0)
	s_barrier
	s_waitcnt lgkmcnt(0)
	v_mfma_f32_16x16x32_bf16 v[124:127], v[144:147], v[184:187], v[124:127]
	v_mfma_f32_16x16x32_bf16 v[120:123], v[160:163], v[184:187], v[120:123]
	v_mfma_f32_16x16x32_bf16 v[108:111], v[144:147], v[192:195], v[108:111]
	v_mfma_f32_16x16x32_bf16 v[104:107], v[160:163], v[192:195], v[104:107]
	v_mfma_f32_16x16x32_bf16 v[92:95], v[144:147], v[200:203], v[92:95]
	v_mfma_f32_16x16x32_bf16 v[88:91], v[160:163], v[200:203], v[88:91]
	v_mfma_f32_16x16x32_bf16 v[76:79], v[144:147], v[208:211], v[76:79]
	v_mfma_f32_16x16x32_bf16 v[72:75], v[160:163], v[208:211], v[72:75]
	v_mfma_f32_16x16x32_bf16 v[124:127], v[156:159], v[188:191], v[124:127]
	v_mfma_f32_16x16x32_bf16 v[120:123], v[164:167], v[188:191], v[120:123]
	v_mfma_f32_16x16x32_bf16 v[108:111], v[156:159], v[196:199], v[108:111]
	v_mfma_f32_16x16x32_bf16 v[104:107], v[164:167], v[196:199], v[104:107]
	v_mfma_f32_16x16x32_bf16 v[92:95], v[156:159], v[204:207], v[92:95]
	v_mfma_f32_16x16x32_bf16 v[88:91], v[164:167], v[204:207], v[88:91]
	v_mfma_f32_16x16x32_bf16 v[76:79], v[156:159], v[212:215], v[76:79]
	v_mfma_f32_16x16x32_bf16 v[72:75], v[164:167], v[212:215], v[72:75]
	v_mfma_f32_16x16x32_bf16 v[116:119], v[168:171], v[184:187], v[116:119]
	v_mfma_f32_16x16x32_bf16 v[112:115], v[176:179], v[184:187], v[112:115]
	v_mfma_f32_16x16x32_bf16 v[100:103], v[168:171], v[192:195], v[100:103]
	v_mfma_f32_16x16x32_bf16 v[96:99], v[176:179], v[192:195], v[96:99]
	v_mfma_f32_16x16x32_bf16 v[84:87], v[168:171], v[200:203], v[84:87]
	v_mfma_f32_16x16x32_bf16 v[80:83], v[176:179], v[200:203], v[80:83]
	v_mfma_f32_16x16x32_bf16 v[68:71], v[168:171], v[208:211], v[68:71]
	v_mfma_f32_16x16x32_bf16 v[64:67], v[176:179], v[208:211], v[64:67]
	v_mfma_f32_16x16x32_bf16 v[116:119], v[172:175], v[188:191], v[116:119]
	v_mfma_f32_16x16x32_bf16 v[112:115], v[180:183], v[188:191], v[112:115]
	v_mfma_f32_16x16x32_bf16 v[100:103], v[172:175], v[196:199], v[100:103]
	v_mfma_f32_16x16x32_bf16 v[96:99], v[180:183], v[196:199], v[96:99]
	v_mfma_f32_16x16x32_bf16 v[84:87], v[172:175], v[204:207], v[84:87]
	v_mfma_f32_16x16x32_bf16 v[80:83], v[180:183], v[204:207], v[80:83]
	v_mfma_f32_16x16x32_bf16 v[68:71], v[172:175], v[212:215], v[68:71]
	v_mfma_f32_16x16x32_bf16 v[64:67], v[180:183], v[212:215], v[64:67]
	s_barrier
	s_add_i32 s38, s64, s43
	v_lshl_add_u64 v[216:217], v[216:217], 0, s[10:11]
	s_mov_b32 m0, s38
	ds_read_b128 v[184:187], v151 offset:49152
	ds_read_b128 v[188:191], v151 offset:50176
	ds_read_b128 v[192:195], v151 offset:51200
	ds_read_b128 v[196:199], v151 offset:52224
	ds_read_b128 v[200:203], v151 offset:53248
	ds_read_b128 v[204:207], v151 offset:54272
	ds_read_b128 v[208:211], v151 offset:55296
	ds_read_b128 v[212:215], v151 offset:56320
	global_load_lds_dwordx4 v[216:217], off
	s_add_i32 m0, s38, 0x2000
	s_add_u32 s36, s36, 0x40080
	v_lshl_add_u64 v[216:217], v[218:219], 0, s[10:11]
	s_addc_u32 s37, s37, 0
	s_add_i32 s38, s65, s43
	global_load_lds_dwordx4 v[216:217], off
	v_lshl_add_u64 v[216:217], s[36:37], 0, v[132:133]
	s_mov_b32 m0, s38
	s_nop 0
	global_load_lds_dwordx4 v[216:217], off
	v_lshl_add_u64 v[216:217], s[36:37], 0, v[128:129]
	s_add_i32 m0, s38, 0x2000
	s_nop 0
	global_load_lds_dwordx4 v[216:217], off
	v_lshl_add_u64 v[216:217], v[220:221], 0, s[10:11]
	s_mov_b32 m0, s51
	s_nop 0
	global_load_lds_dwordx4 v[216:217], off
	v_lshl_add_u64 v[216:217], v[222:223], 0, s[10:11]
	s_mov_b32 m0, s52
	s_nop 0
	global_load_lds_dwordx4 v[216:217], off
	s_waitcnt vmcnt(8)
	s_waitcnt lgkmcnt(0)
	s_barrier
	s_waitcnt lgkmcnt(0)
	v_mfma_f32_16x16x32_bf16 v[60:63], v[144:147], v[184:187], v[60:63]
	v_mfma_f32_16x16x32_bf16 v[56:59], v[160:163], v[184:187], v[56:59]
	v_mfma_f32_16x16x32_bf16 v[44:47], v[144:147], v[192:195], v[44:47]
	v_mfma_f32_16x16x32_bf16 v[40:43], v[160:163], v[192:195], v[40:43]
	v_mfma_f32_16x16x32_bf16 v[28:31], v[144:147], v[200:203], v[28:31]
	v_mfma_f32_16x16x32_bf16 v[24:27], v[160:163], v[200:203], v[24:27]
	v_mfma_f32_16x16x32_bf16 v[12:15], v[144:147], v[208:211], v[12:15]
	v_mfma_f32_16x16x32_bf16 v[8:11], v[160:163], v[208:211], v[8:11]
	v_mfma_f32_16x16x32_bf16 v[60:63], v[156:159], v[188:191], v[60:63]
	v_mfma_f32_16x16x32_bf16 v[56:59], v[164:167], v[188:191], v[56:59]
	v_mfma_f32_16x16x32_bf16 v[44:47], v[156:159], v[196:199], v[44:47]
	v_mfma_f32_16x16x32_bf16 v[40:43], v[164:167], v[196:199], v[40:43]
	v_mfma_f32_16x16x32_bf16 v[28:31], v[156:159], v[204:207], v[28:31]
	v_mfma_f32_16x16x32_bf16 v[24:27], v[164:167], v[204:207], v[24:27]
	v_mfma_f32_16x16x32_bf16 v[12:15], v[156:159], v[212:215], v[12:15]
	v_mfma_f32_16x16x32_bf16 v[8:11], v[164:167], v[212:215], v[8:11]
	v_mfma_f32_16x16x32_bf16 v[52:55], v[168:171], v[184:187], v[52:55]
	v_mfma_f32_16x16x32_bf16 v[48:51], v[176:179], v[184:187], v[48:51]
	v_mfma_f32_16x16x32_bf16 v[36:39], v[168:171], v[192:195], v[36:39]
	v_mfma_f32_16x16x32_bf16 v[32:35], v[176:179], v[192:195], v[32:35]
	v_mfma_f32_16x16x32_bf16 v[20:23], v[168:171], v[200:203], v[20:23]
	v_mfma_f32_16x16x32_bf16 v[16:19], v[176:179], v[200:203], v[16:19]
	v_mfma_f32_16x16x32_bf16 v[4:7], v[168:171], v[208:211], v[4:7]
	v_mfma_f32_16x16x32_bf16 v[0:3], v[176:179], v[208:211], v[0:3]
	v_mfma_f32_16x16x32_bf16 v[52:55], v[172:175], v[188:191], v[52:55]
	v_mfma_f32_16x16x32_bf16 v[48:51], v[180:183], v[188:191], v[48:51]
	v_mfma_f32_16x16x32_bf16 v[36:39], v[172:175], v[196:199], v[36:39]
	v_mfma_f32_16x16x32_bf16 v[32:35], v[180:183], v[196:199], v[32:35]
	v_mfma_f32_16x16x32_bf16 v[20:23], v[172:175], v[204:207], v[20:23]
	v_mfma_f32_16x16x32_bf16 v[16:19], v[180:183], v[204:207], v[16:19]
	v_mfma_f32_16x16x32_bf16 v[4:7], v[172:175], v[212:215], v[4:7]
	v_mfma_f32_16x16x32_bf16 v[0:3], v[180:183], v[212:215], v[0:3]
	s_barrier
	s_add_i32 s63, s63, 2
	s_add_u32 s61, s61, 0x100
	s_addc_u32 s62, s62, 0
	s_add_u32 s30, s30, 0x100
	s_addc_u32 s31, s31, 0
	s_cmp_gt_u32 s63, 13
	s_cbranch_scc0 .LBB0_683
	s_and_b64 vcc, exec, s[12:13]
	s_cbranch_vccz .LBB0_686
	s_barrier

.LBB0_707:
	s_add_u32 s49, s38, s48
	s_addc_u32 s54, s39, 0
	s_add_u32 s52, s49, 0x100
	s_addc_u32 s53, s54, 0
	s_and_b64 s[50:51], s[46:47], exec
	s_cselect_b32 s51, s35, s53
	s_cselect_b32 s50, s81, s52
	s_add_u32 s48, s36, s48
	s_addc_u32 s52, s37, 0
	s_add_u32 s48, s48, 0x100
	s_addc_u32 s52, s52, 0
	s_and_b64 s[46:47], s[46:47], exec
	s_cselect_b32 s53, s31, s52
	s_cselect_b32 s52, s82, s48
	s_add_u32 s56, s49, 0x10080
	ds_read_b128 v[144:147], v141
	ds_read_b128 v[148:151], v141 offset:1024
	ds_read_b128 v[156:159], v141 offset:2048
	ds_read_b128 v[160:163], v141 offset:3072
	ds_read_b128 v[164:167], v142
	ds_read_b128 v[168:171], v142 offset:1024
	ds_read_b128 v[172:175], v142 offset:2048
	ds_read_b128 v[176:179], v142 offset:3072
	s_addc_u32 s57, s54, 0
	s_add_i32 s90, s74, s63
	s_add_i32 m0, s29, 0xc000
	s_add_i32 s93, s29, 0xe000
	s_add_i32 s87, s90, 0x2000
	s_add_u32 s54, s52, 0x10000
	s_addc_u32 s55, s53, 0
	s_add_i32 s89, s75, s63
	s_add_i32 s88, s89, 0x2000
	s_add_i32 s86, 0, 0x18000
	s_add_i32 s85, 0, 0x1c000
	s_add_u32 s48, s50, 0x10000
	s_addc_u32 s49, s51, 0
	s_add_i32 s84, s86, s63
	s_add_i32 s83, s84, 0x2000
	s_add_u32 s46, s52, 0x10080
	s_addc_u32 s47, s53, 0
	s_add_i32 s92, s85, s63
	s_add_i32 s91, s92, 0x2000
	v_lshl_add_u64 v[152:153], s[56:57], 0, v[128:129]
	ds_read_b128 v[180:183], v143
	ds_read_b128 v[184:187], v143 offset:1024
	ds_read_b128 v[188:191], v143 offset:2048
	ds_read_b128 v[192:195], v143 offset:3072
	ds_read_b128 v[196:199], v143 offset:4096
	ds_read_b128 v[200:203], v143 offset:5120
	ds_read_b128 v[204:207], v143 offset:6144
	ds_read_b128 v[208:211], v143 offset:7168
	global_load_lds_dwordx4 v[152:153], off
	v_lshl_add_u64 v[152:153], s[56:57], 0, v[132:133]
	s_mov_b32 m0, s93
	s_nop 0
	global_load_lds_dwordx4 v[152:153], off
	s_waitcnt vmcnt(8)
	s_waitcnt lgkmcnt(0)
	s_barrier
	s_waitcnt lgkmcnt(0)
	v_mfma_f32_16x16x32_bf16 v[124:127], v[144:147], v[180:183], v[124:127]
	v_mfma_f32_16x16x32_bf16 v[120:123], v[156:159], v[180:183], v[120:123]
	v_mfma_f32_16x16x32_bf16 v[116:119], v[144:147], v[188:191], v[116:119]
	v_mfma_f32_16x16x32_bf16 v[112:115], v[156:159], v[188:191], v[112:115]
	v_mfma_f32_16x16x32_bf16 v[100:103], v[144:147], v[196:199], v[100:103]
	v_mfma_f32_16x16x32_bf16 v[96:99], v[156:159], v[196:199], v[96:99]
	v_mfma_f32_16x16x32_bf16 v[84:87], v[144:147], v[204:207], v[84:87]
	v_mfma_f32_16x16x32_bf16 v[80:83], v[156:159], v[204:207], v[80:83]
	v_mfma_f32_16x16x32_bf16 v[124:127], v[148:151], v[184:187], v[124:127]
	v_mfma_f32_16x16x32_bf16 v[120:123], v[160:163], v[184:187], v[120:123]
	v_mfma_f32_16x16x32_bf16 v[116:119], v[148:151], v[192:195], v[116:119]
	v_mfma_f32_16x16x32_bf16 v[112:115], v[160:163], v[192:195], v[112:115]
	v_mfma_f32_16x16x32_bf16 v[100:103], v[148:151], v[200:203], v[100:103]
	v_mfma_f32_16x16x32_bf16 v[96:99], v[160:163], v[200:203], v[96:99]
	v_mfma_f32_16x16x32_bf16 v[84:87], v[148:151], v[208:211], v[84:87]
	v_mfma_f32_16x16x32_bf16 v[80:83], v[160:163], v[208:211], v[80:83]
	v_mfma_f32_16x16x32_bf16 v[108:111], v[164:167], v[180:183], v[108:111]
	v_mfma_f32_16x16x32_bf16 v[104:107], v[172:175], v[180:183], v[104:107]
	v_mfma_f32_16x16x32_bf16 v[92:95], v[164:167], v[188:191], v[92:95]
	v_mfma_f32_16x16x32_bf16 v[88:91], v[172:175], v[188:191], v[88:91]
	v_mfma_f32_16x16x32_bf16 v[76:79], v[164:167], v[196:199], v[76:79]
	v_mfma_f32_16x16x32_bf16 v[72:75], v[172:175], v[196:199], v[72:75]
	v_mfma_f32_16x16x32_bf16 v[68:71], v[164:167], v[204:207], v[68:71]
	v_mfma_f32_16x16x32_bf16 v[64:67], v[172:175], v[204:207], v[64:67]
	v_mfma_f32_16x16x32_bf16 v[108:111], v[168:171], v[184:187], v[108:111]
	v_mfma_f32_16x16x32_bf16 v[104:107], v[176:179], v[184:187], v[104:107]
	v_mfma_f32_16x16x32_bf16 v[92:95], v[168:171], v[192:195], v[92:95]
	v_mfma_f32_16x16x32_bf16 v[88:91], v[176:179], v[192:195], v[88:91]
	v_mfma_f32_16x16x32_bf16 v[76:79], v[168:171], v[200:203], v[76:79]
	v_mfma_f32_16x16x32_bf16 v[72:75], v[176:179], v[200:203], v[72:75]
	v_mfma_f32_16x16x32_bf16 v[68:71], v[168:171], v[208:211], v[68:71]
	v_mfma_f32_16x16x32_bf16 v[64:67], v[176:179], v[208:211], v[64:67]
	s_barrier
	s_mov_b32 m0, s90
	v_lshl_add_u64 v[152:153], s[52:53], 0, v[130:131]
	ds_read_b128 v[180:183], v143 offset:16384
	ds_read_b128 v[184:187], v143 offset:17408
	ds_read_b128 v[188:191], v143 offset:18432
	ds_read_b128 v[192:195], v143 offset:19456
	ds_read_b128 v[196:199], v143 offset:20480
	ds_read_b128 v[200:203], v143 offset:21504
	ds_read_b128 v[204:207], v143 offset:22528
	ds_read_b128 v[208:211], v143 offset:23552
	global_load_lds_dwordx4 v[152:153], off
	v_lshl_add_u64 v[212:213], s[52:53], 0, v[134:135]
	s_mov_b32 m0, s87
	v_lshl_add_u64 v[214:215], s[54:55], 0, v[130:131]
	global_load_lds_dwordx4 v[212:213], off
	s_mov_b32 m0, s89
	v_lshl_add_u64 v[216:217], s[50:51], 0, v[132:133]
	global_load_lds_dwordx4 v[214:215], off
	v_lshl_add_u64 v[214:215], s[54:55], 0, v[134:135]
	s_mov_b32 m0, s88
	s_nop 0
	global_load_lds_dwordx4 v[214:215], off
	v_lshl_add_u64 v[214:215], s[50:51], 0, v[128:129]
	s_mov_b32 m0, s29
	s_nop 0
	global_load_lds_dwordx4 v[214:215], off
	s_mov_b32 m0, s64
	s_nop 0
	global_load_lds_dwordx4 v[216:217], off
	s_waitcnt vmcnt(8)
	s_waitcnt lgkmcnt(0)
	s_barrier
	s_waitcnt lgkmcnt(0)
	v_mfma_f32_16x16x32_bf16 v[60:63], v[144:147], v[180:183], v[60:63]
	v_mfma_f32_16x16x32_bf16 v[56:59], v[156:159], v[180:183], v[56:59]
	v_mfma_f32_16x16x32_bf16 v[52:55], v[144:147], v[188:191], v[52:55]
	v_mfma_f32_16x16x32_bf16 v[48:51], v[156:159], v[188:191], v[48:51]
	v_mfma_f32_16x16x32_bf16 v[36:39], v[144:147], v[196:199], v[36:39]
	v_mfma_f32_16x16x32_bf16 v[32:35], v[156:159], v[196:199], v[32:35]
	v_mfma_f32_16x16x32_bf16 v[20:23], v[144:147], v[204:207], v[20:23]
	v_mfma_f32_16x16x32_bf16 v[16:19], v[156:159], v[204:207], v[16:19]
	v_mfma_f32_16x16x32_bf16 v[60:63], v[148:151], v[184:187], v[60:63]
	v_mfma_f32_16x16x32_bf16 v[56:59], v[160:163], v[184:187], v[56:59]
	v_mfma_f32_16x16x32_bf16 v[52:55], v[148:151], v[192:195], v[52:55]
	v_mfma_f32_16x16x32_bf16 v[48:51], v[160:163], v[192:195], v[48:51]
	v_mfma_f32_16x16x32_bf16 v[36:39], v[148:151], v[200:203], v[36:39]
	v_mfma_f32_16x16x32_bf16 v[32:35], v[160:163], v[200:203], v[32:35]
	v_mfma_f32_16x16x32_bf16 v[20:23], v[148:151], v[208:211], v[20:23]
	v_mfma_f32_16x16x32_bf16 v[16:19], v[160:163], v[208:211], v[16:19]
	v_mfma_f32_16x16x32_bf16 v[44:47], v[164:167], v[180:183], v[44:47]
	v_mfma_f32_16x16x32_bf16 v[40:43], v[172:175], v[180:183], v[40:43]
	v_mfma_f32_16x16x32_bf16 v[28:31], v[164:167], v[188:191], v[28:31]
	v_mfma_f32_16x16x32_bf16 v[24:27], v[172:175], v[188:191], v[24:27]
	v_mfma_f32_16x16x32_bf16 v[12:15], v[164:167], v[196:199], v[12:15]
	v_mfma_f32_16x16x32_bf16 v[8:11], v[172:175], v[196:199], v[8:11]
	v_mfma_f32_16x16x32_bf16 v[4:7], v[164:167], v[204:207], v[4:7]
	v_mfma_f32_16x16x32_bf16 v[0:3], v[172:175], v[204:207], v[0:3]
	v_mfma_f32_16x16x32_bf16 v[44:47], v[168:171], v[184:187], v[44:47]
	v_mfma_f32_16x16x32_bf16 v[40:43], v[176:179], v[184:187], v[40:43]
	v_mfma_f32_16x16x32_bf16 v[28:31], v[168:171], v[192:195], v[28:31]
	v_mfma_f32_16x16x32_bf16 v[24:27], v[176:179], v[192:195], v[24:27]
	v_mfma_f32_16x16x32_bf16 v[12:15], v[168:171], v[200:203], v[12:15]
	v_mfma_f32_16x16x32_bf16 v[8:11], v[176:179], v[200:203], v[8:11]
	v_mfma_f32_16x16x32_bf16 v[4:7], v[168:171], v[208:211], v[4:7]
	v_mfma_f32_16x16x32_bf16 v[0:3], v[176:179], v[208:211], v[0:3]
	s_barrier
	v_add_u32_e32 v160, s86, v140
	v_add_u32_e32 v176, s85, v140
	ds_read_b128 v[144:147], v160
	ds_read_b128 v[148:151], v160 offset:1024
	ds_read_b128 v[156:159], v160 offset:2048
	ds_read_b128 v[160:163], v160 offset:3072
	ds_read_b128 v[164:167], v176
	ds_read_b128 v[168:171], v176 offset:1024
	ds_read_b128 v[172:175], v176 offset:2048
	ds_read_b128 v[176:179], v176 offset:3072
	s_mov_b32 m0, s65
	v_lshl_add_u64 v[218:219], s[48:49], 0, v[128:129]
	ds_read_b128 v[180:183], v143 offset:32768
	ds_read_b128 v[184:187], v143 offset:33792
	ds_read_b128 v[188:191], v143 offset:34816
	ds_read_b128 v[192:195], v143 offset:35840
	ds_read_b128 v[196:199], v143 offset:36864
	ds_read_b128 v[200:203], v143 offset:37888
	ds_read_b128 v[204:207], v143 offset:38912
	ds_read_b128 v[208:211], v143 offset:39936
	global_load_lds_dwordx4 v[218:219], off
	v_lshl_add_u64 v[218:219], s[48:49], 0, v[132:133]
	s_mov_b32 m0, s66
	s_nop 0
	global_load_lds_dwordx4 v[218:219], off
	s_waitcnt vmcnt(8)
	s_waitcnt lgkmcnt(0)
	s_barrier
	s_waitcnt lgkmcnt(0)
	v_mfma_f32_16x16x32_bf16 v[124:127], v[144:147], v[180:183], v[124:127]
	v_mfma_f32_16x16x32_bf16 v[120:123], v[156:159], v[180:183], v[120:123]
	v_mfma_f32_16x16x32_bf16 v[116:119], v[144:147], v[188:191], v[116:119]
	v_mfma_f32_16x16x32_bf16 v[112:115], v[156:159], v[188:191], v[112:115]
	v_mfma_f32_16x16x32_bf16 v[100:103], v[144:147], v[196:199], v[100:103]
	v_mfma_f32_16x16x32_bf16 v[96:99], v[156:159], v[196:199], v[96:99]
	v_mfma_f32_16x16x32_bf16 v[84:87], v[144:147], v[204:207], v[84:87]
	v_mfma_f32_16x16x32_bf16 v[80:83], v[156:159], v[204:207], v[80:83]
	v_mfma_f32_16x16x32_bf16 v[124:127], v[148:151], v[184:187], v[124:127]
	v_mfma_f32_16x16x32_bf16 v[120:123], v[160:163], v[184:187], v[120:123]
	v_mfma_f32_16x16x32_bf16 v[116:119], v[148:151], v[192:195], v[116:119]
	v_mfma_f32_16x16x32_bf16 v[112:115], v[160:163], v[192:195], v[112:115]
	v_mfma_f32_16x16x32_bf16 v[100:103], v[148:151], v[200:203], v[100:103]
	v_mfma_f32_16x16x32_bf16 v[96:99], v[160:163], v[200:203], v[96:99]
	v_mfma_f32_16x16x32_bf16 v[84:87], v[148:151], v[208:211], v[84:87]
	v_mfma_f32_16x16x32_bf16 v[80:83], v[160:163], v[208:211], v[80:83]
	v_mfma_f32_16x16x32_bf16 v[108:111], v[164:167], v[180:183], v[108:111]
	v_mfma_f32_16x16x32_bf16 v[104:107], v[172:175], v[180:183], v[104:107]
	v_mfma_f32_16x16x32_bf16 v[92:95], v[164:167], v[188:191], v[92:95]
	v_mfma_f32_16x16x32_bf16 v[88:91], v[172:175], v[188:191], v[88:91]
	v_mfma_f32_16x16x32_bf16 v[76:79], v[164:167], v[196:199], v[76:79]
	v_mfma_f32_16x16x32_bf16 v[72:75], v[172:175], v[196:199], v[72:75]
	v_mfma_f32_16x16x32_bf16 v[68:71], v[164:167], v[204:207], v[68:71]
	v_mfma_f32_16x16x32_bf16 v[64:67], v[172:175], v[204:207], v[64:67]
	v_mfma_f32_16x16x32_bf16 v[108:111], v[168:171], v[184:187], v[108:111]
	v_mfma_f32_16x16x32_bf16 v[104:107], v[176:179], v[184:187], v[104:107]
	v_mfma_f32_16x16x32_bf16 v[92:95], v[168:171], v[192:195], v[92:95]
	v_mfma_f32_16x16x32_bf16 v[88:91], v[176:179], v[192:195], v[88:91]
	v_mfma_f32_16x16x32_bf16 v[76:79], v[168:171], v[200:203], v[76:79]
	v_mfma_f32_16x16x32_bf16 v[72:75], v[176:179], v[200:203], v[72:75]
	v_mfma_f32_16x16x32_bf16 v[68:71], v[168:171], v[208:211], v[68:71]
	v_mfma_f32_16x16x32_bf16 v[64:67], v[176:179], v[208:211], v[64:67]
	s_barrier
	s_mov_b32 m0, s84
	v_lshl_add_u64 v[152:153], v[152:153], 0, s[8:9]
	ds_read_b128 v[180:183], v143 offset:49152
	ds_read_b128 v[184:187], v143 offset:50176
	ds_read_b128 v[188:191], v143 offset:51200
	ds_read_b128 v[192:195], v143 offset:52224
	ds_read_b128 v[196:199], v143 offset:53248
	ds_read_b128 v[200:203], v143 offset:54272
	ds_read_b128 v[204:207], v143 offset:55296
	ds_read_b128 v[208:211], v143 offset:56320
	global_load_lds_dwordx4 v[152:153], off
	v_lshl_add_u64 v[152:153], v[212:213], 0, s[8:9]
	s_mov_b32 m0, s83
	s_nop 0
	global_load_lds_dwordx4 v[152:153], off
	v_lshl_add_u64 v[152:153], s[46:47], 0, v[130:131]
	s_mov_b32 m0, s92
	s_nop 0
	global_load_lds_dwordx4 v[152:153], off
	v_lshl_add_u64 v[152:153], s[46:47], 0, v[134:135]
	s_mov_b32 m0, s91
	s_nop 0
	global_load_lds_dwordx4 v[152:153], off
	v_lshl_add_u64 v[152:153], v[214:215], 0, s[8:9]
	s_mov_b32 m0, s71
	s_nop 0
	global_load_lds_dwordx4 v[152:153], off
	v_lshl_add_u64 v[152:153], v[216:217], 0, s[8:9]
	s_mov_b32 m0, s72
	s_nop 0
	global_load_lds_dwordx4 v[152:153], off
	s_waitcnt vmcnt(8)
	s_waitcnt lgkmcnt(0)
	s_barrier
	s_waitcnt lgkmcnt(0)
	v_mfma_f32_16x16x32_bf16 v[60:63], v[144:147], v[180:183], v[60:63]
	v_mfma_f32_16x16x32_bf16 v[56:59], v[156:159], v[180:183], v[56:59]
	v_mfma_f32_16x16x32_bf16 v[52:55], v[144:147], v[188:191], v[52:55]
	v_mfma_f32_16x16x32_bf16 v[48:51], v[156:159], v[188:191], v[48:51]
	v_mfma_f32_16x16x32_bf16 v[36:39], v[144:147], v[196:199], v[36:39]
	v_mfma_f32_16x16x32_bf16 v[32:35], v[156:159], v[196:199], v[32:35]
	v_mfma_f32_16x16x32_bf16 v[20:23], v[144:147], v[204:207], v[20:23]
	v_mfma_f32_16x16x32_bf16 v[16:19], v[156:159], v[204:207], v[16:19]
	v_mfma_f32_16x16x32_bf16 v[60:63], v[148:151], v[184:187], v[60:63]
	v_mfma_f32_16x16x32_bf16 v[56:59], v[160:163], v[184:187], v[56:59]
	v_mfma_f32_16x16x32_bf16 v[52:55], v[148:151], v[192:195], v[52:55]
	v_mfma_f32_16x16x32_bf16 v[48:51], v[160:163], v[192:195], v[48:51]
	v_mfma_f32_16x16x32_bf16 v[36:39], v[148:151], v[200:203], v[36:39]
	v_mfma_f32_16x16x32_bf16 v[32:35], v[160:163], v[200:203], v[32:35]
	v_mfma_f32_16x16x32_bf16 v[20:23], v[148:151], v[208:211], v[20:23]
	v_mfma_f32_16x16x32_bf16 v[16:19], v[160:163], v[208:211], v[16:19]
	v_mfma_f32_16x16x32_bf16 v[44:47], v[164:167], v[180:183], v[44:47]
	v_mfma_f32_16x16x32_bf16 v[40:43], v[172:175], v[180:183], v[40:43]
	v_mfma_f32_16x16x32_bf16 v[28:31], v[164:167], v[188:191], v[28:31]
	v_mfma_f32_16x16x32_bf16 v[24:27], v[172:175], v[188:191], v[24:27]
	v_mfma_f32_16x16x32_bf16 v[12:15], v[164:167], v[196:199], v[12:15]
	v_mfma_f32_16x16x32_bf16 v[8:11], v[172:175], v[196:199], v[8:11]
	v_mfma_f32_16x16x32_bf16 v[4:7], v[164:167], v[204:207], v[4:7]
	v_mfma_f32_16x16x32_bf16 v[0:3], v[172:175], v[204:207], v[0:3]
	v_mfma_f32_16x16x32_bf16 v[44:47], v[168:171], v[184:187], v[44:47]
	v_mfma_f32_16x16x32_bf16 v[40:43], v[176:179], v[184:187], v[40:43]
	v_mfma_f32_16x16x32_bf16 v[28:31], v[168:171], v[192:195], v[28:31]
	v_mfma_f32_16x16x32_bf16 v[24:27], v[176:179], v[192:195], v[24:27]
	v_mfma_f32_16x16x32_bf16 v[12:15], v[168:171], v[200:203], v[12:15]
	v_mfma_f32_16x16x32_bf16 v[8:11], v[176:179], v[200:203], v[8:11]
	v_mfma_f32_16x16x32_bf16 v[4:7], v[168:171], v[208:211], v[4:7]
	v_mfma_f32_16x16x32_bf16 v[0:3], v[176:179], v[208:211], v[0:3]
	s_barrier
	s_movk_i32 s48, 0x100
	s_andn2_b64 vcc, exec, s[44:45]
	s_mov_b64 s[46:47], -1
	s_mov_b64 s[44:45], 0
	s_cbranch_vccz .LBB0_707
	s_and_b64 vcc, exec, s[10:11]
	s_cbranch_vccz .LBB0_710
	s_barrier

.Lprio_skip_7:
	s_load_dwordx2 s[4:5], s[4:5], 0x138
	s_mov_b32 s3, s33
	s_mov_b32 s30, s2
	v_mov_b32_e32 v8, v154
	s_cmpk_lt_i32 s30, 0x100
	s_cselect_b64 s[6:7], -1, 0
	s_cmpk_gt_i32 s30, 0xff
	v_readfirstlane_b32 s16, v8
	s_cbranch_scc1 .LBB0_772
	s_ashr_i32 s8, s30, 31
	s_lshr_b32 s8, s8, 29
	s_add_i32 s12, s30, s8
	s_and_b32 s8, s12, -8
	s_sub_i32 s10, s30, s8
	s_cmp_gt_i32 s10, -1
	s_cbranch_scc0 .LBB0_769
	s_lshl_b32 s11, s10, 5
	s_ashr_i32 s8, s12, 3
	s_cbranch_execz .LBB0_770
	s_branch .LBB0_771

.LBB0_789:
	ds_read_b128 v[144:147], v149
	ds_read_b128 v[156:159], v149 offset:1024
	ds_read_b128 v[160:163], v149 offset:2048
	ds_read_b128 v[164:167], v149 offset:3072
	ds_read_b128 v[168:171], v150
	ds_read_b128 v[172:175], v150 offset:1024
	ds_read_b128 v[176:179], v150 offset:2048
	ds_read_b128 v[180:183], v150 offset:3072
	s_add_u32 s10, s8, 0x100
	s_addc_u32 s11, s9, 0
	s_cmp_eq_u32 s58, 40
	s_cselect_b32 s29, s7, s11
	s_cselect_b32 s28, s6, s10
	s_cselect_b32 s27, s19, s57
	s_cselect_b32 s26, s18, s56
	v_lshl_add_u64 v[216:217], s[8:9], 0, v[138:139]
	s_add_i32 m0, s38, 0xc000
	ds_read_b128 v[184:187], v151
	ds_read_b128 v[188:191], v151 offset:1024
	ds_read_b128 v[192:195], v151 offset:2048
	ds_read_b128 v[196:199], v151 offset:3072
	ds_read_b128 v[200:203], v151 offset:4096
	ds_read_b128 v[204:207], v151 offset:5120
	ds_read_b128 v[208:211], v151 offset:6144
	ds_read_b128 v[212:215], v151 offset:7168
	global_load_lds_dwordx4 v[216:217], off
	v_lshl_add_u64 v[216:217], s[8:9], 0, v[136:137]
	s_add_i32 m0, s38, 0xe000
	s_nop 0
	global_load_lds_dwordx4 v[216:217], off
	s_waitcnt vmcnt(8)
	s_waitcnt lgkmcnt(0)
	s_barrier
	s_waitcnt lgkmcnt(0)
	v_mfma_f32_16x16x32_bf16 v[124:127], v[144:147], v[184:187], v[124:127]
	v_mfma_f32_16x16x32_bf16 v[120:123], v[160:163], v[184:187], v[120:123]
	v_mfma_f32_16x16x32_bf16 v[108:111], v[144:147], v[192:195], v[108:111]
	v_mfma_f32_16x16x32_bf16 v[104:107], v[160:163], v[192:195], v[104:107]
	v_mfma_f32_16x16x32_bf16 v[92:95], v[144:147], v[200:203], v[92:95]
	v_mfma_f32_16x16x32_bf16 v[88:91], v[160:163], v[200:203], v[88:91]
	v_mfma_f32_16x16x32_bf16 v[76:79], v[144:147], v[208:211], v[76:79]
	v_mfma_f32_16x16x32_bf16 v[72:75], v[160:163], v[208:211], v[72:75]
	v_mfma_f32_16x16x32_bf16 v[124:127], v[156:159], v[188:191], v[124:127]
	v_mfma_f32_16x16x32_bf16 v[120:123], v[164:167], v[188:191], v[120:123]
	v_mfma_f32_16x16x32_bf16 v[108:111], v[156:159], v[196:199], v[108:111]
	v_mfma_f32_16x16x32_bf16 v[104:107], v[164:167], v[196:199], v[104:107]
	v_mfma_f32_16x16x32_bf16 v[92:95], v[156:159], v[204:207], v[92:95]
	v_mfma_f32_16x16x32_bf16 v[88:91], v[164:167], v[204:207], v[88:91]
	v_mfma_f32_16x16x32_bf16 v[76:79], v[156:159], v[212:215], v[76:79]
	v_mfma_f32_16x16x32_bf16 v[72:75], v[164:167], v[212:215], v[72:75]
	v_mfma_f32_16x16x32_bf16 v[116:119], v[168:171], v[184:187], v[116:119]
	v_mfma_f32_16x16x32_bf16 v[112:115], v[176:179], v[184:187], v[112:115]
	v_mfma_f32_16x16x32_bf16 v[100:103], v[168:171], v[192:195], v[100:103]
	v_mfma_f32_16x16x32_bf16 v[96:99], v[176:179], v[192:195], v[96:99]
	v_mfma_f32_16x16x32_bf16 v[84:87], v[168:171], v[200:203], v[84:87]
	v_mfma_f32_16x16x32_bf16 v[80:83], v[176:179], v[200:203], v[80:83]
	v_mfma_f32_16x16x32_bf16 v[68:71], v[168:171], v[208:211], v[68:71]
	v_mfma_f32_16x16x32_bf16 v[64:67], v[176:179], v[208:211], v[64:67]
	v_mfma_f32_16x16x32_bf16 v[116:119], v[172:175], v[188:191], v[116:119]
	v_mfma_f32_16x16x32_bf16 v[112:115], v[180:183], v[188:191], v[112:115]
	v_mfma_f32_16x16x32_bf16 v[100:103], v[172:175], v[196:199], v[100:103]
	v_mfma_f32_16x16x32_bf16 v[96:99], v[180:183], v[196:199], v[96:99]
	v_mfma_f32_16x16x32_bf16 v[84:87], v[172:175], v[204:207], v[84:87]
	v_mfma_f32_16x16x32_bf16 v[80:83], v[180:183], v[204:207], v[80:83]
	v_mfma_f32_16x16x32_bf16 v[68:71], v[172:175], v[212:215], v[68:71]
	v_mfma_f32_16x16x32_bf16 v[64:67], v[180:183], v[212:215], v[64:67]
	s_barrier
	s_add_i32 s8, s50, s37
	v_lshl_add_u64 v[216:217], s[26:27], 0, v[130:131]
	s_mov_b32 m0, s8
	ds_read_b128 v[184:187], v151 offset:16384
	ds_read_b128 v[188:191], v151 offset:17408
	ds_read_b128 v[192:195], v151 offset:18432
	ds_read_b128 v[196:199], v151 offset:19456
	ds_read_b128 v[200:203], v151 offset:20480
	ds_read_b128 v[204:207], v151 offset:21504
	ds_read_b128 v[208:211], v151 offset:22528
	ds_read_b128 v[212:215], v151 offset:23552
	global_load_lds_dwordx4 v[216:217], off
	s_add_i32 m0, s8, 0x2000
	s_add_u32 s8, s26, 0xb0000
	v_lshl_add_u64 v[218:219], s[26:27], 0, v[134:135]
	s_addc_u32 s9, s27, 0
	s_add_i32 s59, s51, s37
	global_load_lds_dwordx4 v[218:219], off
	v_lshl_add_u64 v[220:221], s[8:9], 0, v[130:131]
	s_mov_b32 m0, s59
	v_lshl_add_u64 v[222:223], s[28:29], 0, v[132:133]
	global_load_lds_dwordx4 v[220:221], off
	v_lshl_add_u64 v[220:221], s[8:9], 0, v[134:135]
	s_add_i32 m0, s59, 0x2000
	s_nop 0
	global_load_lds_dwordx4 v[220:221], off
	v_lshl_add_u64 v[220:221], s[28:29], 0, v[128:129]
	s_mov_b32 m0, s38
	s_nop 0
	global_load_lds_dwordx4 v[220:221], off
	s_mov_b32 m0, s39
	s_nop 0
	global_load_lds_dwordx4 v[222:223], off
	s_waitcnt vmcnt(8)
	s_waitcnt lgkmcnt(0)
	s_barrier
	s_waitcnt lgkmcnt(0)
	v_mfma_f32_16x16x32_bf16 v[60:63], v[144:147], v[184:187], v[60:63]
	v_mfma_f32_16x16x32_bf16 v[56:59], v[160:163], v[184:187], v[56:59]
	v_mfma_f32_16x16x32_bf16 v[44:47], v[144:147], v[192:195], v[44:47]
	v_mfma_f32_16x16x32_bf16 v[40:43], v[160:163], v[192:195], v[40:43]
	v_mfma_f32_16x16x32_bf16 v[28:31], v[144:147], v[200:203], v[28:31]
	v_mfma_f32_16x16x32_bf16 v[24:27], v[160:163], v[200:203], v[24:27]
	v_mfma_f32_16x16x32_bf16 v[12:15], v[144:147], v[208:211], v[12:15]
	v_mfma_f32_16x16x32_bf16 v[8:11], v[160:163], v[208:211], v[8:11]
	v_mfma_f32_16x16x32_bf16 v[60:63], v[156:159], v[188:191], v[60:63]
	v_mfma_f32_16x16x32_bf16 v[56:59], v[164:167], v[188:191], v[56:59]
	v_mfma_f32_16x16x32_bf16 v[44:47], v[156:159], v[196:199], v[44:47]
	v_mfma_f32_16x16x32_bf16 v[40:43], v[164:167], v[196:199], v[40:43]
	v_mfma_f32_16x16x32_bf16 v[28:31], v[156:159], v[204:207], v[28:31]
	v_mfma_f32_16x16x32_bf16 v[24:27], v[164:167], v[204:207], v[24:27]
	v_mfma_f32_16x16x32_bf16 v[12:15], v[156:159], v[212:215], v[12:15]
	v_mfma_f32_16x16x32_bf16 v[8:11], v[164:167], v[212:215], v[8:11]
	v_mfma_f32_16x16x32_bf16 v[52:55], v[168:171], v[184:187], v[52:55]
	v_mfma_f32_16x16x32_bf16 v[48:51], v[176:179], v[184:187], v[48:51]
	v_mfma_f32_16x16x32_bf16 v[36:39], v[168:171], v[192:195], v[36:39]
	v_mfma_f32_16x16x32_bf16 v[32:35], v[176:179], v[192:195], v[32:35]
	v_mfma_f32_16x16x32_bf16 v[20:23], v[168:171], v[200:203], v[20:23]
	v_mfma_f32_16x16x32_bf16 v[16:19], v[176:179], v[200:203], v[16:19]
	v_mfma_f32_16x16x32_bf16 v[4:7], v[168:171], v[208:211], v[4:7]
	v_mfma_f32_16x16x32_bf16 v[0:3], v[176:179], v[208:211], v[0:3]
	v_mfma_f32_16x16x32_bf16 v[52:55], v[172:175], v[188:191], v[52:55]
	v_mfma_f32_16x16x32_bf16 v[48:51], v[180:183], v[188:191], v[48:51]
	v_mfma_f32_16x16x32_bf16 v[36:39], v[172:175], v[196:199], v[36:39]
	v_mfma_f32_16x16x32_bf16 v[32:35], v[180:183], v[196:199], v[32:35]
	v_mfma_f32_16x16x32_bf16 v[20:23], v[172:175], v[204:207], v[20:23]
	v_mfma_f32_16x16x32_bf16 v[16:19], v[180:183], v[204:207], v[16:19]
	v_mfma_f32_16x16x32_bf16 v[4:7], v[172:175], v[212:215], v[4:7]
	v_mfma_f32_16x16x32_bf16 v[0:3], v[180:183], v[212:215], v[0:3]
	s_barrier
	s_add_i32 s59, 0, 0x18000
	v_add_u32_e32 v153, s59, v148
	s_add_i32 s60, 0, 0x1c000
	ds_read_b128 v[144:147], v153
	ds_read_b128 v[156:159], v153 offset:1024
	ds_read_b128 v[160:163], v153 offset:2048
	ds_read_b128 v[164:167], v153 offset:3072
	v_add_u32_e32 v153, s60, v148
	ds_read_b128 v[168:171], v153
	ds_read_b128 v[172:175], v153 offset:1024
	ds_read_b128 v[176:179], v153 offset:2048
	ds_read_b128 v[180:183], v153 offset:3072
	s_add_u32 s8, s28, 0xb0000
	s_addc_u32 s9, s29, 0
	s_mov_b32 m0, s40
	v_lshl_add_u64 v[224:225], s[8:9], 0, v[128:129]
	ds_read_b128 v[184:187], v151 offset:32768
	ds_read_b128 v[188:191], v151 offset:33792
	ds_read_b128 v[192:195], v151 offset:34816
	ds_read_b128 v[196:199], v151 offset:35840
	ds_read_b128 v[200:203], v151 offset:36864
	ds_read_b128 v[204:207], v151 offset:37888
	ds_read_b128 v[208:211], v151 offset:38912
	ds_read_b128 v[212:215], v151 offset:39936
	global_load_lds_dwordx4 v[224:225], off
	v_lshl_add_u64 v[224:225], s[8:9], 0, v[132:133]
	s_mov_b32 m0, s41
	s_nop 0
	global_load_lds_dwordx4 v[224:225], off
	s_waitcnt vmcnt(8)
	s_waitcnt lgkmcnt(0)
	s_barrier
	s_waitcnt lgkmcnt(0)
	v_mfma_f32_16x16x32_bf16 v[124:127], v[144:147], v[184:187], v[124:127]
	v_mfma_f32_16x16x32_bf16 v[120:123], v[160:163], v[184:187], v[120:123]
	v_mfma_f32_16x16x32_bf16 v[108:111], v[144:147], v[192:195], v[108:111]
	v_mfma_f32_16x16x32_bf16 v[104:107], v[160:163], v[192:195], v[104:107]
	v_mfma_f32_16x16x32_bf16 v[92:95], v[144:147], v[200:203], v[92:95]
	v_mfma_f32_16x16x32_bf16 v[88:91], v[160:163], v[200:203], v[88:91]
	v_mfma_f32_16x16x32_bf16 v[76:79], v[144:147], v[208:211], v[76:79]
	v_mfma_f32_16x16x32_bf16 v[72:75], v[160:163], v[208:211], v[72:75]
	v_mfma_f32_16x16x32_bf16 v[124:127], v[156:159], v[188:191], v[124:127]
	v_mfma_f32_16x16x32_bf16 v[120:123], v[164:167], v[188:191], v[120:123]
	v_mfma_f32_16x16x32_bf16 v[108:111], v[156:159], v[196:199], v[108:111]
	v_mfma_f32_16x16x32_bf16 v[104:107], v[164:167], v[196:199], v[104:107]
	v_mfma_f32_16x16x32_bf16 v[92:95], v[156:159], v[204:207], v[92:95]
	v_mfma_f32_16x16x32_bf16 v[88:91], v[164:167], v[204:207], v[88:91]
	v_mfma_f32_16x16x32_bf16 v[76:79], v[156:159], v[212:215], v[76:79]
	v_mfma_f32_16x16x32_bf16 v[72:75], v[164:167], v[212:215], v[72:75]
	v_mfma_f32_16x16x32_bf16 v[116:119], v[168:171], v[184:187], v[116:119]
	v_mfma_f32_16x16x32_bf16 v[112:115], v[176:179], v[184:187], v[112:115]
	v_mfma_f32_16x16x32_bf16 v[100:103], v[168:171], v[192:195], v[100:103]
	v_mfma_f32_16x16x32_bf16 v[96:99], v[176:179], v[192:195], v[96:99]
	v_mfma_f32_16x16x32_bf16 v[84:87], v[168:171], v[200:203], v[84:87]
	v_mfma_f32_16x16x32_bf16 v[80:83], v[176:179], v[200:203], v[80:83]
	v_mfma_f32_16x16x32_bf16 v[68:71], v[168:171], v[208:211], v[68:71]
	v_mfma_f32_16x16x32_bf16 v[64:67], v[176:179], v[208:211], v[64:67]
	v_mfma_f32_16x16x32_bf16 v[116:119], v[172:175], v[188:191], v[116:119]
	v_mfma_f32_16x16x32_bf16 v[112:115], v[180:183], v[188:191], v[112:115]
	v_mfma_f32_16x16x32_bf16 v[100:103], v[172:175], v[196:199], v[100:103]
	v_mfma_f32_16x16x32_bf16 v[96:99], v[180:183], v[196:199], v[96:99]
	v_mfma_f32_16x16x32_bf16 v[84:87], v[172:175], v[204:207], v[84:87]
	v_mfma_f32_16x16x32_bf16 v[80:83], v[180:183], v[204:207], v[80:83]
	v_mfma_f32_16x16x32_bf16 v[68:71], v[172:175], v[212:215], v[68:71]
	v_mfma_f32_16x16x32_bf16 v[64:67], v[180:183], v[212:215], v[64:67]
	s_barrier
	s_add_i32 s8, s59, s37
	v_lshl_add_u64 v[216:217], v[216:217], 0, s[14:15]
	s_mov_b32 m0, s8
	ds_read_b128 v[184:187], v151 offset:49152
	ds_read_b128 v[188:191], v151 offset:50176
	ds_read_b128 v[192:195], v151 offset:51200
	ds_read_b128 v[196:199], v151 offset:52224
	ds_read_b128 v[200:203], v151 offset:53248
	ds_read_b128 v[204:207], v151 offset:54272
	ds_read_b128 v[208:211], v151 offset:55296
	ds_read_b128 v[212:215], v151 offset:56320
	global_load_lds_dwordx4 v[216:217], off
	s_add_i32 m0, s8, 0x2000
	s_add_u32 s8, s26, 0xb0080
	v_lshl_add_u64 v[216:217], v[218:219], 0, s[14:15]
	s_addc_u32 s9, s27, 0
	s_add_i32 s26, s60, s37
	global_load_lds_dwordx4 v[216:217], off
	v_lshl_add_u64 v[216:217], s[8:9], 0, v[130:131]
	s_mov_b32 m0, s26
	s_nop 0
	global_load_lds_dwordx4 v[216:217], off
	v_lshl_add_u64 v[216:217], s[8:9], 0, v[134:135]
	s_add_i32 m0, s26, 0x2000
	s_nop 0
	global_load_lds_dwordx4 v[216:217], off
	v_lshl_add_u64 v[216:217], v[220:221], 0, s[14:15]
	s_mov_b32 m0, s46
	s_nop 0
	global_load_lds_dwordx4 v[216:217], off
	v_lshl_add_u64 v[216:217], v[222:223], 0, s[14:15]
	s_mov_b32 m0, s47
	s_nop 0
	global_load_lds_dwordx4 v[216:217], off
	s_waitcnt vmcnt(8)
	s_waitcnt lgkmcnt(0)
	s_barrier
	s_waitcnt lgkmcnt(0)
	v_mfma_f32_16x16x32_bf16 v[60:63], v[144:147], v[184:187], v[60:63]
	v_mfma_f32_16x16x32_bf16 v[56:59], v[160:163], v[184:187], v[56:59]
	v_mfma_f32_16x16x32_bf16 v[44:47], v[144:147], v[192:195], v[44:47]
	v_mfma_f32_16x16x32_bf16 v[40:43], v[160:163], v[192:195], v[40:43]
	v_mfma_f32_16x16x32_bf16 v[28:31], v[144:147], v[200:203], v[28:31]
	v_mfma_f32_16x16x32_bf16 v[24:27], v[160:163], v[200:203], v[24:27]
	v_mfma_f32_16x16x32_bf16 v[12:15], v[144:147], v[208:211], v[12:15]
	v_mfma_f32_16x16x32_bf16 v[8:11], v[160:163], v[208:211], v[8:11]
	v_mfma_f32_16x16x32_bf16 v[60:63], v[156:159], v[188:191], v[60:63]
	v_mfma_f32_16x16x32_bf16 v[56:59], v[164:167], v[188:191], v[56:59]
	v_mfma_f32_16x16x32_bf16 v[44:47], v[156:159], v[196:199], v[44:47]
	v_mfma_f32_16x16x32_bf16 v[40:43], v[164:167], v[196:199], v[40:43]
	v_mfma_f32_16x16x32_bf16 v[28:31], v[156:159], v[204:207], v[28:31]
	v_mfma_f32_16x16x32_bf16 v[24:27], v[164:167], v[204:207], v[24:27]
	v_mfma_f32_16x16x32_bf16 v[12:15], v[156:159], v[212:215], v[12:15]
	v_mfma_f32_16x16x32_bf16 v[8:11], v[164:167], v[212:215], v[8:11]
	v_mfma_f32_16x16x32_bf16 v[52:55], v[168:171], v[184:187], v[52:55]
	v_mfma_f32_16x16x32_bf16 v[48:51], v[176:179], v[184:187], v[48:51]
	v_mfma_f32_16x16x32_bf16 v[36:39], v[168:171], v[192:195], v[36:39]
	v_mfma_f32_16x16x32_bf16 v[32:35], v[176:179], v[192:195], v[32:35]
	v_mfma_f32_16x16x32_bf16 v[20:23], v[168:171], v[200:203], v[20:23]
	v_mfma_f32_16x16x32_bf16 v[16:19], v[176:179], v[200:203], v[16:19]
	v_mfma_f32_16x16x32_bf16 v[4:7], v[168:171], v[208:211], v[4:7]
	v_mfma_f32_16x16x32_bf16 v[0:3], v[176:179], v[208:211], v[0:3]
	v_mfma_f32_16x16x32_bf16 v[52:55], v[172:175], v[188:191], v[52:55]
	v_mfma_f32_16x16x32_bf16 v[48:51], v[180:183], v[188:191], v[48:51]
	v_mfma_f32_16x16x32_bf16 v[36:39], v[172:175], v[196:199], v[36:39]
	v_mfma_f32_16x16x32_bf16 v[32:35], v[180:183], v[196:199], v[32:35]
	v_mfma_f32_16x16x32_bf16 v[20:23], v[172:175], v[204:207], v[20:23]
	v_mfma_f32_16x16x32_bf16 v[16:19], v[180:183], v[204:207], v[16:19]
	v_mfma_f32_16x16x32_bf16 v[4:7], v[172:175], v[212:215], v[4:7]
	v_mfma_f32_16x16x32_bf16 v[0:3], v[180:183], v[212:215], v[0:3]
	s_barrier
	s_add_i32 s58, s58, 2
	s_add_u32 s56, s56, 0x100
	s_addc_u32 s57, s57, 0
	s_cmp_gt_u32 s58, 41
	s_mov_b64 s[8:9], s[10:11]
	s_cbranch_scc0 .LBB0_789
	s_and_b64 vcc, exec, s[16:17]
	s_cbranch_vccz .LBB0_792
	s_barrier

.LBB0_864:
	s_or_b64 exec, exec, s[4:5]
	s_mov_b64 s[4:5], s[0:1]
	s_mov_b32 s3, s33
	s_mov_b32 s46, s2
	s_waitcnt lgkmcnt(0)
	s_barrier
	v_readfirstlane_b32 s94, v154
	s_cmpk_ge_u32 s94, 0x100
	s_cbranch_scc1 .Lprio_skip_8
	s_setprio 1
.Lprio_skip_8:
	v_mov_b32_e32 v8, v154
	s_cmpk_lt_i32 s46, 0x100
	s_cselect_b64 s[6:7], -1, 0
	s_cmpk_gt_i32 s46, 0xff
	v_readfirstlane_b32 s16, v8
	s_cbranch_scc1 .LBB0_870
	s_ashr_i32 s8, s46, 31
	s_lshr_b32 s8, s8, 29
	s_add_i32 s12, s46, s8
	s_and_b32 s8, s12, -8
	s_sub_i32 s10, s46, s8
	s_cmp_gt_i32 s10, -1
	s_cbranch_scc0 .LBB0_867
	s_lshl_b32 s11, s10, 5
	s_ashr_i32 s8, s12, 3
	s_cbranch_execz .LBB0_868
	s_branch .LBB0_869

.LBB0_883:
	ds_read_b128 v[144:147], v157
	ds_read_b128 v[148:151], v157 offset:1024
	ds_read_b128 v[162:165], v157 offset:2048
	ds_read_b128 v[166:169], v157 offset:3072
	ds_read_b128 v[170:173], v158
	ds_read_b128 v[174:177], v158 offset:1024
	ds_read_b128 v[178:181], v158 offset:2048
	ds_read_b128 v[182:185], v158 offset:3072
	s_add_u32 s14, s12, 0xfffc0080
	s_addc_u32 s15, s13, -1
	s_cmp_eq_u32 s41, 12
	s_cselect_b32 s35, s27, s15
	s_cselect_b32 s34, s36, s14
	s_cselect_b32 s15, s19, s39
	s_cselect_b32 s14, s37, s38
	v_lshl_add_u64 v[152:153], s[12:13], 0, v[138:139]
	s_add_i32 m0, s43, 0xc000
	ds_read_b128 v[186:189], v159
	ds_read_b128 v[190:193], v159 offset:1024
	ds_read_b128 v[194:197], v159 offset:2048
	ds_read_b128 v[198:201], v159 offset:3072
	ds_read_b128 v[202:205], v159 offset:4096
	ds_read_b128 v[206:209], v159 offset:5120
	ds_read_b128 v[210:213], v159 offset:6144
	ds_read_b128 v[214:217], v159 offset:7168
	global_load_lds_dwordx4 v[152:153], off
	v_lshl_add_u64 v[152:153], s[12:13], 0, v[136:137]
	s_add_i32 m0, s43, 0xe000
	s_nop 0
	global_load_lds_dwordx4 v[152:153], off
	s_waitcnt vmcnt(8)
	s_waitcnt lgkmcnt(0)
	s_barrier
	s_waitcnt lgkmcnt(0)
	v_mfma_f32_16x16x32_bf16 v[124:127], v[144:147], v[186:189], v[124:127]
	v_mfma_f32_16x16x32_bf16 v[120:123], v[162:165], v[186:189], v[120:123]
	v_mfma_f32_16x16x32_bf16 v[108:111], v[144:147], v[194:197], v[108:111]
	v_mfma_f32_16x16x32_bf16 v[104:107], v[162:165], v[194:197], v[104:107]
	v_mfma_f32_16x16x32_bf16 v[92:95], v[144:147], v[202:205], v[92:95]
	v_mfma_f32_16x16x32_bf16 v[88:91], v[162:165], v[202:205], v[88:91]
	v_mfma_f32_16x16x32_bf16 v[76:79], v[144:147], v[210:213], v[76:79]
	v_mfma_f32_16x16x32_bf16 v[72:75], v[162:165], v[210:213], v[72:75]
	v_mfma_f32_16x16x32_bf16 v[124:127], v[148:151], v[190:193], v[124:127]
	v_mfma_f32_16x16x32_bf16 v[120:123], v[166:169], v[190:193], v[120:123]
	v_mfma_f32_16x16x32_bf16 v[108:111], v[148:151], v[198:201], v[108:111]
	v_mfma_f32_16x16x32_bf16 v[104:107], v[166:169], v[198:201], v[104:107]
	v_mfma_f32_16x16x32_bf16 v[92:95], v[148:151], v[206:209], v[92:95]
	v_mfma_f32_16x16x32_bf16 v[88:91], v[166:169], v[206:209], v[88:91]
	v_mfma_f32_16x16x32_bf16 v[76:79], v[148:151], v[214:217], v[76:79]
	v_mfma_f32_16x16x32_bf16 v[72:75], v[166:169], v[214:217], v[72:75]
	v_mfma_f32_16x16x32_bf16 v[116:119], v[170:173], v[186:189], v[116:119]
	v_mfma_f32_16x16x32_bf16 v[112:115], v[178:181], v[186:189], v[112:115]
	v_mfma_f32_16x16x32_bf16 v[100:103], v[170:173], v[194:197], v[100:103]
	v_mfma_f32_16x16x32_bf16 v[96:99], v[178:181], v[194:197], v[96:99]
	v_mfma_f32_16x16x32_bf16 v[84:87], v[170:173], v[202:205], v[84:87]
	v_mfma_f32_16x16x32_bf16 v[80:83], v[178:181], v[202:205], v[80:83]
	v_mfma_f32_16x16x32_bf16 v[68:71], v[170:173], v[210:213], v[68:71]
	v_mfma_f32_16x16x32_bf16 v[64:67], v[178:181], v[210:213], v[64:67]
	v_mfma_f32_16x16x32_bf16 v[116:119], v[174:177], v[190:193], v[116:119]
	v_mfma_f32_16x16x32_bf16 v[112:115], v[182:185], v[190:193], v[112:115]
	v_mfma_f32_16x16x32_bf16 v[100:103], v[174:177], v[198:201], v[100:103]
	v_mfma_f32_16x16x32_bf16 v[96:99], v[182:185], v[198:201], v[96:99]
	v_mfma_f32_16x16x32_bf16 v[84:87], v[174:177], v[206:209], v[84:87]
	v_mfma_f32_16x16x32_bf16 v[80:83], v[182:185], v[206:209], v[80:83]
	v_mfma_f32_16x16x32_bf16 v[68:71], v[174:177], v[214:217], v[68:71]
	v_mfma_f32_16x16x32_bf16 v[64:67], v[182:185], v[214:217], v[64:67]
	s_barrier
	s_add_i32 s44, s61, s49
	v_lshl_add_u64 v[152:153], s[14:15], 0, v[130:131]
	s_mov_b32 m0, s44
	ds_read_b128 v[186:189], v159 offset:16384
	ds_read_b128 v[190:193], v159 offset:17408
	ds_read_b128 v[194:197], v159 offset:18432
	ds_read_b128 v[198:201], v159 offset:19456
	ds_read_b128 v[202:205], v159 offset:20480
	ds_read_b128 v[206:209], v159 offset:21504
	ds_read_b128 v[210:213], v159 offset:22528
	ds_read_b128 v[214:217], v159 offset:23552
	global_load_lds_dwordx4 v[152:153], off
	s_add_i32 m0, s44, 0x2000
	s_add_u32 s44, s14, 0x40000
	v_lshl_add_u64 v[218:219], s[14:15], 0, v[134:135]
	s_addc_u32 s45, s15, 0
	s_add_i32 s63, s62, s49
	global_load_lds_dwordx4 v[218:219], off
	v_lshl_add_u64 v[220:221], s[44:45], 0, v[130:131]
	s_mov_b32 m0, s63
	v_lshl_add_u64 v[222:223], s[34:35], 0, v[132:133]
	global_load_lds_dwordx4 v[220:221], off
	v_lshl_add_u64 v[220:221], s[44:45], 0, v[134:135]
	s_add_i32 m0, s63, 0x2000
	s_nop 0
	global_load_lds_dwordx4 v[220:221], off
	v_lshl_add_u64 v[220:221], s[34:35], 0, v[128:129]
	s_mov_b32 m0, s43
	s_nop 0
	global_load_lds_dwordx4 v[220:221], off
	s_mov_b32 m0, s50
	s_nop 0
	global_load_lds_dwordx4 v[222:223], off
	s_waitcnt vmcnt(8)
	s_waitcnt lgkmcnt(0)
	s_barrier
	s_waitcnt lgkmcnt(0)
	v_mfma_f32_16x16x32_bf16 v[60:63], v[144:147], v[186:189], v[60:63]
	v_mfma_f32_16x16x32_bf16 v[56:59], v[162:165], v[186:189], v[56:59]
	v_mfma_f32_16x16x32_bf16 v[44:47], v[144:147], v[194:197], v[44:47]
	v_mfma_f32_16x16x32_bf16 v[40:43], v[162:165], v[194:197], v[40:43]
	v_mfma_f32_16x16x32_bf16 v[28:31], v[144:147], v[202:205], v[28:31]
	v_mfma_f32_16x16x32_bf16 v[24:27], v[162:165], v[202:205], v[24:27]
	v_mfma_f32_16x16x32_bf16 v[12:15], v[144:147], v[210:213], v[12:15]
	v_mfma_f32_16x16x32_bf16 v[8:11], v[162:165], v[210:213], v[8:11]
	v_mfma_f32_16x16x32_bf16 v[60:63], v[148:151], v[190:193], v[60:63]
	v_mfma_f32_16x16x32_bf16 v[56:59], v[166:169], v[190:193], v[56:59]
	v_mfma_f32_16x16x32_bf16 v[44:47], v[148:151], v[198:201], v[44:47]
	v_mfma_f32_16x16x32_bf16 v[40:43], v[166:169], v[198:201], v[40:43]
	v_mfma_f32_16x16x32_bf16 v[28:31], v[148:151], v[206:209], v[28:31]
	v_mfma_f32_16x16x32_bf16 v[24:27], v[166:169], v[206:209], v[24:27]
	v_mfma_f32_16x16x32_bf16 v[12:15], v[148:151], v[214:217], v[12:15]
	v_mfma_f32_16x16x32_bf16 v[8:11], v[166:169], v[214:217], v[8:11]
	v_mfma_f32_16x16x32_bf16 v[52:55], v[170:173], v[186:189], v[52:55]
	v_mfma_f32_16x16x32_bf16 v[48:51], v[178:181], v[186:189], v[48:51]
	v_mfma_f32_16x16x32_bf16 v[36:39], v[170:173], v[194:197], v[36:39]
	v_mfma_f32_16x16x32_bf16 v[32:35], v[178:181], v[194:197], v[32:35]
	v_mfma_f32_16x16x32_bf16 v[20:23], v[170:173], v[202:205], v[20:23]
	v_mfma_f32_16x16x32_bf16 v[16:19], v[178:181], v[202:205], v[16:19]
	v_mfma_f32_16x16x32_bf16 v[4:7], v[170:173], v[210:213], v[4:7]
	v_mfma_f32_16x16x32_bf16 v[0:3], v[178:181], v[210:213], v[0:3]
	v_mfma_f32_16x16x32_bf16 v[52:55], v[174:177], v[190:193], v[52:55]
	v_mfma_f32_16x16x32_bf16 v[48:51], v[182:185], v[190:193], v[48:51]
	v_mfma_f32_16x16x32_bf16 v[36:39], v[174:177], v[198:201], v[36:39]
	v_mfma_f32_16x16x32_bf16 v[32:35], v[182:185], v[198:201], v[32:35]
	v_mfma_f32_16x16x32_bf16 v[20:23], v[174:177], v[206:209], v[20:23]
	v_mfma_f32_16x16x32_bf16 v[16:19], v[182:185], v[206:209], v[16:19]
	v_mfma_f32_16x16x32_bf16 v[4:7], v[174:177], v[214:217], v[4:7]
	v_mfma_f32_16x16x32_bf16 v[0:3], v[182:185], v[214:217], v[0:3]
	s_barrier
	s_add_i32 s44, 0, 0x18000
	s_add_i32 s45, 0, 0x1c000
	v_add_u32_e32 v166, s44, v156
	v_add_u32_e32 v182, s45, v156
	ds_read_b128 v[144:147], v166
	ds_read_b128 v[148:151], v166 offset:1024
	ds_read_b128 v[162:165], v166 offset:2048
	ds_read_b128 v[166:169], v166 offset:3072
	ds_read_b128 v[170:173], v182
	ds_read_b128 v[174:177], v182 offset:1024
	ds_read_b128 v[178:181], v182 offset:2048
	ds_read_b128 v[182:185], v182 offset:3072
	s_add_u32 s34, s34, 0x40000
	s_addc_u32 s35, s35, 0
	s_mov_b32 m0, s51
	v_lshl_add_u64 v[224:225], s[34:35], 0, v[128:129]
	ds_read_b128 v[186:189], v159 offset:32768
	ds_read_b128 v[190:193], v159 offset:33792
	ds_read_b128 v[194:197], v159 offset:34816
	ds_read_b128 v[198:201], v159 offset:35840
	ds_read_b128 v[202:205], v159 offset:36864
	ds_read_b128 v[206:209], v159 offset:37888
	ds_read_b128 v[210:213], v159 offset:38912
	ds_read_b128 v[214:217], v159 offset:39936
	global_load_lds_dwordx4 v[224:225], off
	v_lshl_add_u64 v[224:225], s[34:35], 0, v[132:133]
	s_mov_b32 m0, s52
	s_nop 0
	global_load_lds_dwordx4 v[224:225], off
	s_waitcnt vmcnt(8)
	s_waitcnt lgkmcnt(0)
	s_barrier
	s_waitcnt lgkmcnt(0)
	v_mfma_f32_16x16x32_bf16 v[124:127], v[144:147], v[186:189], v[124:127]
	v_mfma_f32_16x16x32_bf16 v[120:123], v[162:165], v[186:189], v[120:123]
	v_mfma_f32_16x16x32_bf16 v[108:111], v[144:147], v[194:197], v[108:111]
	v_mfma_f32_16x16x32_bf16 v[104:107], v[162:165], v[194:197], v[104:107]
	v_mfma_f32_16x16x32_bf16 v[92:95], v[144:147], v[202:205], v[92:95]
	v_mfma_f32_16x16x32_bf16 v[88:91], v[162:165], v[202:205], v[88:91]
	v_mfma_f32_16x16x32_bf16 v[76:79], v[144:147], v[210:213], v[76:79]
	v_mfma_f32_16x16x32_bf16 v[72:75], v[162:165], v[210:213], v[72:75]
	v_mfma_f32_16x16x32_bf16 v[124:127], v[148:151], v[190:193], v[124:127]
	v_mfma_f32_16x16x32_bf16 v[120:123], v[166:169], v[190:193], v[120:123]
	v_mfma_f32_16x16x32_bf16 v[108:111], v[148:151], v[198:201], v[108:111]
	v_mfma_f32_16x16x32_bf16 v[104:107], v[166:169], v[198:201], v[104:107]
	v_mfma_f32_16x16x32_bf16 v[92:95], v[148:151], v[206:209], v[92:95]
	v_mfma_f32_16x16x32_bf16 v[88:91], v[166:169], v[206:209], v[88:91]
	v_mfma_f32_16x16x32_bf16 v[76:79], v[148:151], v[214:217], v[76:79]
	v_mfma_f32_16x16x32_bf16 v[72:75], v[166:169], v[214:217], v[72:75]
	v_mfma_f32_16x16x32_bf16 v[116:119], v[170:173], v[186:189], v[116:119]
	v_mfma_f32_16x16x32_bf16 v[112:115], v[178:181], v[186:189], v[112:115]
	v_mfma_f32_16x16x32_bf16 v[100:103], v[170:173], v[194:197], v[100:103]
	v_mfma_f32_16x16x32_bf16 v[96:99], v[178:181], v[194:197], v[96:99]
	v_mfma_f32_16x16x32_bf16 v[84:87], v[170:173], v[202:205], v[84:87]
	v_mfma_f32_16x16x32_bf16 v[80:83], v[178:181], v[202:205], v[80:83]
	v_mfma_f32_16x16x32_bf16 v[68:71], v[170:173], v[210:213], v[68:71]
	v_mfma_f32_16x16x32_bf16 v[64:67], v[178:181], v[210:213], v[64:67]
	v_mfma_f32_16x16x32_bf16 v[116:119], v[174:177], v[190:193], v[116:119]
	v_mfma_f32_16x16x32_bf16 v[112:115], v[182:185], v[190:193], v[112:115]
	v_mfma_f32_16x16x32_bf16 v[100:103], v[174:177], v[198:201], v[100:103]
	v_mfma_f32_16x16x32_bf16 v[96:99], v[182:185], v[198:201], v[96:99]
	v_mfma_f32_16x16x32_bf16 v[84:87], v[174:177], v[206:209], v[84:87]
	v_mfma_f32_16x16x32_bf16 v[80:83], v[182:185], v[206:209], v[80:83]
	v_mfma_f32_16x16x32_bf16 v[68:71], v[174:177], v[214:217], v[68:71]
	v_mfma_f32_16x16x32_bf16 v[64:67], v[182:185], v[214:217], v[64:67]
	s_barrier
	s_add_i32 s34, s44, s49
	v_lshl_add_u64 v[152:153], v[152:153], 0, s[10:11]
	s_mov_b32 m0, s34
	ds_read_b128 v[186:189], v159 offset:49152
	ds_read_b128 v[190:193], v159 offset:50176
	ds_read_b128 v[194:197], v159 offset:51200
	ds_read_b128 v[198:201], v159 offset:52224
	ds_read_b128 v[202:205], v159 offset:53248
	ds_read_b128 v[206:209], v159 offset:54272
	ds_read_b128 v[210:213], v159 offset:55296
	ds_read_b128 v[214:217], v159 offset:56320
	global_load_lds_dwordx4 v[152:153], off
	s_add_i32 m0, s34, 0x2000
	s_add_u32 s14, s14, 0x40080
	v_lshl_add_u64 v[152:153], v[218:219], 0, s[10:11]
	s_addc_u32 s15, s15, 0
	s_add_i32 s34, s45, s49
	global_load_lds_dwordx4 v[152:153], off
	v_lshl_add_u64 v[152:153], s[14:15], 0, v[130:131]
	s_mov_b32 m0, s34
	s_nop 0
	global_load_lds_dwordx4 v[152:153], off
	v_lshl_add_u64 v[152:153], s[14:15], 0, v[134:135]
	s_add_i32 m0, s34, 0x2000
	s_nop 0
	global_load_lds_dwordx4 v[152:153], off
	v_lshl_add_u64 v[152:153], v[220:221], 0, s[10:11]
	s_mov_b32 m0, s57
	s_nop 0
	global_load_lds_dwordx4 v[152:153], off
	v_lshl_add_u64 v[152:153], v[222:223], 0, s[10:11]
	s_mov_b32 m0, s58
	s_nop 0
	global_load_lds_dwordx4 v[152:153], off
	s_waitcnt vmcnt(8)
	s_waitcnt lgkmcnt(0)
	s_barrier
	s_waitcnt lgkmcnt(0)
	v_mfma_f32_16x16x32_bf16 v[60:63], v[144:147], v[186:189], v[60:63]
	v_mfma_f32_16x16x32_bf16 v[56:59], v[162:165], v[186:189], v[56:59]
	v_mfma_f32_16x16x32_bf16 v[44:47], v[144:147], v[194:197], v[44:47]
	v_mfma_f32_16x16x32_bf16 v[40:43], v[162:165], v[194:197], v[40:43]
	v_mfma_f32_16x16x32_bf16 v[28:31], v[144:147], v[202:205], v[28:31]
	v_mfma_f32_16x16x32_bf16 v[24:27], v[162:165], v[202:205], v[24:27]
	v_mfma_f32_16x16x32_bf16 v[12:15], v[144:147], v[210:213], v[12:15]
	v_mfma_f32_16x16x32_bf16 v[8:11], v[162:165], v[210:213], v[8:11]
	v_mfma_f32_16x16x32_bf16 v[60:63], v[148:151], v[190:193], v[60:63]
	v_mfma_f32_16x16x32_bf16 v[56:59], v[166:169], v[190:193], v[56:59]
	v_mfma_f32_16x16x32_bf16 v[44:47], v[148:151], v[198:201], v[44:47]
	v_mfma_f32_16x16x32_bf16 v[40:43], v[166:169], v[198:201], v[40:43]
	v_mfma_f32_16x16x32_bf16 v[28:31], v[148:151], v[206:209], v[28:31]
	v_mfma_f32_16x16x32_bf16 v[24:27], v[166:169], v[206:209], v[24:27]
	v_mfma_f32_16x16x32_bf16 v[12:15], v[148:151], v[214:217], v[12:15]
	v_mfma_f32_16x16x32_bf16 v[8:11], v[166:169], v[214:217], v[8:11]
	v_mfma_f32_16x16x32_bf16 v[52:55], v[170:173], v[186:189], v[52:55]
	v_mfma_f32_16x16x32_bf16 v[48:51], v[178:181], v[186:189], v[48:51]
	v_mfma_f32_16x16x32_bf16 v[36:39], v[170:173], v[194:197], v[36:39]
	v_mfma_f32_16x16x32_bf16 v[32:35], v[178:181], v[194:197], v[32:35]
	v_mfma_f32_16x16x32_bf16 v[20:23], v[170:173], v[202:205], v[20:23]
	v_mfma_f32_16x16x32_bf16 v[16:19], v[178:181], v[202:205], v[16:19]
	v_mfma_f32_16x16x32_bf16 v[4:7], v[170:173], v[210:213], v[4:7]
	v_mfma_f32_16x16x32_bf16 v[0:3], v[178:181], v[210:213], v[0:3]
	v_mfma_f32_16x16x32_bf16 v[52:55], v[174:177], v[190:193], v[52:55]
	v_mfma_f32_16x16x32_bf16 v[48:51], v[182:185], v[190:193], v[48:51]
	v_mfma_f32_16x16x32_bf16 v[36:39], v[174:177], v[198:201], v[36:39]
	v_mfma_f32_16x16x32_bf16 v[32:35], v[182:185], v[198:201], v[32:35]
	v_mfma_f32_16x16x32_bf16 v[20:23], v[174:177], v[206:209], v[20:23]
	v_mfma_f32_16x16x32_bf16 v[16:19], v[182:185], v[206:209], v[16:19]
	v_mfma_f32_16x16x32_bf16 v[4:7], v[174:177], v[214:217], v[4:7]
	v_mfma_f32_16x16x32_bf16 v[0:3], v[182:185], v[214:217], v[0:3]
	s_barrier
	s_add_i32 s41, s41, 2
	s_add_u32 s38, s38, 0x100
	s_addc_u32 s39, s39, 0
	s_add_u32 s12, s12, 0x100
	s_addc_u32 s13, s13, 0
	s_cmp_gt_u32 s41, 13
	s_cbranch_scc0 .LBB0_883
	s_and_b64 vcc, exec, s[16:17]
	s_cbranch_vccz .LBB0_886
	s_barrier

.LBB0_906:
	s_mov_b64 s[6:7], s[0:1]
	s_getreg_b32 s3, hwreg(HW_REG_XCC_ID, 0, 4)
	s_setprio 0
	s_waitcnt vmcnt(0)
	s_waitcnt lgkmcnt(0)
	s_barrier
	s_and_saveexec_b64 s[4:5], s[20:21]
	s_cbranch_execz .LBB0_958
	s_add_i32 s8, 0, 0x23fc0
	v_mov_b32_e32 v0, s8
	s_load_dwordx2 s[6:7], s[6:7], 0x138
	s_waitcnt vmcnt(0) expcnt(0) lgkmcnt(0)
	ds_read_b32 v2, v0
	s_add_i32 s8, 0, 0x23fc4
	v_mov_b32_e32 v0, s8
	ds_read_b32 v0, v0
	s_and_b32 s3, s3, 15
	s_waitcnt lgkmcnt(1)
	v_cmp_ne_u32_e32 vcc, 0, v2
	s_cbranch_vccnz .LBB0_922
	s_add_u32 s8, s6, 0x4200
	s_addc_u32 s9, s7, 0
	s_add_u32 s10, s6, 0x4400
	s_addc_u32 s11, s7, 0
	s_add_u32 s12, s6, 0x4500
	s_addc_u32 s13, s7, 0
	s_add_u32 s14, s6, 0x4600
	s_addc_u32 s15, s7, 0
	s_add_u32 s16, s6, 0x4700
	s_addc_u32 s17, s7, 0
	s_add_u32 s18, s6, 0x4800
	s_addc_u32 s19, s7, 0
	s_add_u32 s26, s6, 0x4900
	s_addc_u32 s27, s7, 0
	s_add_u32 s28, s6, 0x4a00
	s_addc_u32 s29, s7, 0
	s_add_u32 s30, s6, 0x4b00
	s_addc_u32 s31, s7, 0
	s_add_u32 s34, s6, 0x4c00
	s_addc_u32 s35, s7, 0
	s_add_u32 s36, s6, 0x4d00
	s_addc_u32 s37, s7, 0
	s_add_u32 s38, s6, 0x4e00
	s_addc_u32 s39, s7, 0
	s_add_u32 s40, s6, 0x4f00
	s_addc_u32 s41, s7, 0
	s_add_u32 s42, s6, 0x5000
	s_addc_u32 s43, s7, 0
	s_add_u32 s44, s6, 0x5100
	s_addc_u32 s45, s7, 0
	s_add_u32 s46, s6, 0x5200
	s_addc_u32 s47, s7, 0
	s_mul_i32 s56, s25, s33
	s_add_u32 s48, s6, 0x5300
	s_mul_i32 s56, s56, s24
	s_addc_u32 s49, s7, 0
	s_mov_b32 s57, 1
	v_mov_b32_e32 v16, 0
	s_branch .LBB0_910

.LBB0_958:
	s_or_b64 exec, exec, s[4:5]
	s_mov_b32 s100, 0
	s_mov_b64 s[4:5], s[0:1]
	s_mov_b64 s[6:7], s[0:1]
	s_mov_b32 s3, s33
	s_mov_b32 s38, s2
	v_mov_b32_e32 v8, v154
	s_waitcnt lgkmcnt(0)
	s_barrier
	v_readfirstlane_b32 s94, v154
	s_cmpk_ge_u32 s94, 0x100
	s_cbranch_scc1 .Lprio_skip_9
	s_setprio 1
.Lprio_skip_9:
	s_cmpk_gt_i32 s38, 0x3bf
	v_readfirstlane_b32 s10, v8
	s_cbranch_scc1 .LBB0_974
	v_lshlrev_b32_e32 v0, 4, v8
	v_add_u32_e32 v1, 0x2000, v0
	v_ashrrev_i32_e32 v2, 31, v1
	v_lshrrev_b32_e32 v2, 22, v2
	v_add_u32_e32 v2, v1, v2
	v_ashrrev_i32_e32 v9, 10, v2
	v_mul_i32_i24_e32 v2, 0x400, v9
	v_sub_u32_e32 v1, v1, v2
	v_lshrrev_b32_e32 v2, 4, v1
	v_bitop3_b32 v1, v2, v1, 32 bitop3:0x6c
	v_ashrrev_i32_e32 v2, 31, v1
	v_lshrrev_b32_e32 v2, 26, v2
	v_add_u32_e32 v2, v1, v2
	v_lshlrev_b32_e32 v3, 3, v9
	v_ashrrev_i32_e32 v10, 6, v2
	v_and_b32_e32 v3, -16, v3
	v_add_u32_e32 v3, v10, v3
	s_load_dwordx2 s[8:9], s[4:5], 0x130
	s_load_dwordx2 s[12:13], s[6:7], 0x138
	v_and_b32_e32 v4, 3, v10
	s_mov_b32 s4, 0x1fffe0
	v_lshrrev_b32_e32 v5, 2, v3
	v_lshlrev_b32_e32 v6, 1, v3
	v_and_b32_e32 v2, 0xc0, v2
	v_and_or_b32 v4, v3, s4, v4
	v_and_b32_e32 v5, 4, v5
	v_and_b32_e32 v6, 24, v6
	v_sub_u32_e32 v1, v1, v2
	v_mov_b32_e32 v2, 1
	v_or3_b32 v4, v4, v5, v6
	v_lshlrev_b32_e32 v5, 5, v9
	v_ashrrev_i16_sdwa v1, v2, sext(v1) dst_sel:DWORD dst_unused:UNUSED_PAD src0_sel:DWORD src1_sel:BYTE_0
	v_and_b32_e32 v5, 32, v5
	v_bfe_i32 v11, v1, 0, 16
	v_add_lshl_u32 v1, v5, v11, 1
	v_lshl_add_u32 v128, v4, 11, v1
	v_lshl_add_u32 v130, v3, 11, v1
	v_bfe_i32 v1, v8, 27, 1
	v_lshrrev_b32_e32 v1, 22, v1
	v_add_u32_e32 v1, v0, v1
	v_and_b32_e32 v1, 0xfffffc00, v1
	v_sub_u32_e32 v0, v0, v1
	v_lshrrev_b32_e32 v1, 4, v0
	v_ashrrev_i32_e32 v3, 31, v8
	v_bitop3_b32 v0, v1, v0, 32 bitop3:0x6c
	v_lshrrev_b32_e32 v3, 26, v3
	v_ashrrev_i32_e32 v1, 31, v0
	v_add_u32_e32 v3, v8, v3
	s_waitcnt lgkmcnt(0)
	s_add_u32 s39, s8, 0x2000000
	v_lshrrev_b32_e32 v1, 26, v1
	v_ashrrev_i32_e32 v13, 6, v3
	s_addc_u32 s40, s9, 0
	v_add_u32_e32 v1, v0, v1
	v_lshlrev_b32_e32 v3, 3, v13
	s_add_u32 s41, s12, 0x100000
	v_ashrrev_i32_e32 v12, 6, v1
	v_and_b32_e32 v3, -16, v3
	s_addc_u32 s42, s13, 0
	v_add_u32_e32 v3, v12, v3
	v_and_b32_e32 v4, 3, v12
	s_ashr_i32 s44, s38, 31
	v_and_or_b32 v4, v3, s4, v4
	s_lshr_b32 s4, s44, 29
	s_add_i32 s4, s38, s4
	s_ashr_i32 s5, s10, 6
	s_ashr_i32 s6, s4, 3
	s_and_b32 s4, s4, -8
	s_ashr_i32 s8, s10, 8
	s_lshl_b32 s43, s5, 10
	s_sub_i32 s4, s38, s4
	s_cmp_lt_i32 s4, 0
	s_movk_i32 s45, 0x79
	s_cselect_b32 s7, s45, 0x78
	s_mul_i32 s4, s7, s4
	s_add_i32 s4, s4, s6
	s_mul_hi_i32 s6, s4, 0x88888889
	s_add_i32 s6, s6, s4
	s_lshr_b32 s7, s6, 31
	s_ashr_i32 s6, s6, 6
	s_add_i32 s6, s6, s7
	s_lshl_b32 s7, s6, 3
	s_mulk_i32 s6, 0x78
	s_sub_i32 s6, s4, s6
	s_bfe_i32 s4, s6, 0x80000
	s_bfe_u32 s4, s4, 0x3000c
	s_add_i32 s9, s6, s4
	s_bfe_i32 s4, s9, 0x80000
	s_and_b32 s9, s9, 0xf8
	s_sub_i32 s6, s6, s9
	s_sext_i32_i16 s4, s4
	s_sext_i32_i8 s6, s6
	v_lshrrev_b32_e32 v5, 2, v3
	v_lshlrev_b32_e32 v6, 1, v3
	v_and_b32_e32 v1, 0xc0, v1
	s_lshr_b32 s4, s4, 3
	s_add_i32 s28, s7, s6
	v_and_b32_e32 v5, 4, v5
	v_and_b32_e32 v6, 24, v6
	v_sub_u32_e32 v0, v0, v1
	s_ashr_i32 s29, s28, 31
	s_bfe_i64 s[12:13], s[4:5], 0x100000
	v_or3_b32 v4, v4, v5, v6
	v_lshlrev_b32_e32 v5, 5, v13
	v_ashrrev_i16_sdwa v0, v2, sext(v0) dst_sel:DWORD dst_unused:UNUSED_PAD src0_sel:DWORD src1_sel:BYTE_0
	s_lshl_b64 s[6:7], s[28:29], 19
	s_lshl_b64 s[12:13], s[12:13], 19
	v_and_b32_e32 v5, 32, v5
	v_bfe_i32 v14, v0, 0, 16
	s_add_u32 s30, s41, s12
	v_add_lshl_u32 v0, v5, v14, 1
	s_addc_u32 s31, s42, s13
	s_add_i32 s46, s43, 0
	v_lshl_add_u32 v132, v4, 11, v0
	s_add_i32 m0, s46, 0x10000
	v_lshl_add_u32 v134, v3, 11, v0
	global_load_lds_dwordx4 v132, s[30:31]
	s_add_i32 m0, s46, 0x12000
	s_add_u32 s12, s30, 0x40000
	global_load_lds_dwordx4 v128, s[30:31]
	s_addc_u32 s13, s31, 0
	s_add_i32 m0, s46, 0x14000
	v_mov_b32_e32 v133, 0
	global_load_lds_dwordx4 v132, s[12:13]
	s_add_i32 m0, s46, 0x16000
	s_add_u32 s34, s39, s6
	s_addc_u32 s35, s40, s7
	s_add_i32 s47, s46, 0x2000
	global_load_lds_dwordx4 v128, s[12:13]
	s_mov_b32 m0, s46
	s_add_u32 s6, s34, 0x40000
	global_load_lds_dwordx4 v134, s[34:35]
	s_mov_b32 m0, s47
	s_addc_u32 s7, s35, 0
	s_add_i32 s48, s46, 0x4000
	global_load_lds_dwordx4 v130, s[34:35]
	s_mov_b32 m0, s48
	s_add_i32 s49, s46, 0x6000
	global_load_lds_dwordx4 v134, s[6:7]
	s_mov_b32 m0, s49
	v_mov_b32_e32 v129, v133
	global_load_lds_dwordx4 v130, s[6:7]
	v_mov_b32_e32 v135, v133
	v_mov_b32_e32 v131, v133
	s_cmp_eq_u32 s8, 1
	s_mov_b32 s50, 0
	v_lshl_add_u64 v[6:7], s[30:31], 0, v[132:133]
	v_lshl_add_u64 v[4:5], s[30:31], 0, v[128:129]
	v_lshl_add_u64 v[0:1], s[34:35], 0, v[134:135]
	s_cselect_b64 s[6:7], -1, 0
	s_cmp_lg_u32 s8, 1
	v_lshl_add_u64 v[2:3], s[34:35], 0, v[130:131]
	s_cbranch_scc1 .LBB0_961
	s_barrier

.LBB0_967:
	ds_read_b128 v[144:147], v149
	ds_read_b128 v[156:159], v149 offset:1024
	ds_read_b128 v[160:163], v149 offset:2048
	ds_read_b128 v[164:167], v149 offset:3072
	ds_read_b128 v[168:171], v150
	ds_read_b128 v[172:175], v150 offset:1024
	ds_read_b128 v[176:179], v150 offset:2048
	ds_read_b128 v[180:183], v150 offset:3072
	s_add_u32 s34, s30, 0xfffc0080
	s_addc_u32 s35, s31, -1
	s_cmp_eq_u32 s63, 12
	s_cselect_b32 s37, s17, s35
	s_cselect_b32 s36, s29, s34
	s_cselect_b32 s35, s15, s62
	s_cselect_b32 s34, s60, s61
	v_lshl_add_u64 v[216:217], s[30:31], 0, v[138:139]
	s_add_i32 m0, s46, 0xc000
	ds_read_b128 v[184:187], v151
	ds_read_b128 v[188:191], v151 offset:1024
	ds_read_b128 v[192:195], v151 offset:2048
	ds_read_b128 v[196:199], v151 offset:3072
	ds_read_b128 v[200:203], v151 offset:4096
	ds_read_b128 v[204:207], v151 offset:5120
	ds_read_b128 v[208:211], v151 offset:6144
	ds_read_b128 v[212:215], v151 offset:7168
	global_load_lds_dwordx4 v[216:217], off
	v_lshl_add_u64 v[216:217], s[30:31], 0, v[136:137]
	s_add_i32 m0, s46, 0xe000
	s_nop 0
	global_load_lds_dwordx4 v[216:217], off
	s_waitcnt vmcnt(8)
	s_waitcnt lgkmcnt(0)
	s_barrier
	s_waitcnt lgkmcnt(0)
	v_mfma_f32_16x16x32_bf16 v[124:127], v[144:147], v[184:187], v[124:127]
	v_mfma_f32_16x16x32_bf16 v[120:123], v[160:163], v[184:187], v[120:123]
	v_mfma_f32_16x16x32_bf16 v[108:111], v[144:147], v[192:195], v[108:111]
	v_mfma_f32_16x16x32_bf16 v[104:107], v[160:163], v[192:195], v[104:107]
	v_mfma_f32_16x16x32_bf16 v[92:95], v[144:147], v[200:203], v[92:95]
	v_mfma_f32_16x16x32_bf16 v[88:91], v[160:163], v[200:203], v[88:91]
	v_mfma_f32_16x16x32_bf16 v[76:79], v[144:147], v[208:211], v[76:79]
	v_mfma_f32_16x16x32_bf16 v[72:75], v[160:163], v[208:211], v[72:75]
	v_mfma_f32_16x16x32_bf16 v[124:127], v[156:159], v[188:191], v[124:127]
	v_mfma_f32_16x16x32_bf16 v[120:123], v[164:167], v[188:191], v[120:123]
	v_mfma_f32_16x16x32_bf16 v[108:111], v[156:159], v[196:199], v[108:111]
	v_mfma_f32_16x16x32_bf16 v[104:107], v[164:167], v[196:199], v[104:107]
	v_mfma_f32_16x16x32_bf16 v[92:95], v[156:159], v[204:207], v[92:95]
	v_mfma_f32_16x16x32_bf16 v[88:91], v[164:167], v[204:207], v[88:91]
	v_mfma_f32_16x16x32_bf16 v[76:79], v[156:159], v[212:215], v[76:79]
	v_mfma_f32_16x16x32_bf16 v[72:75], v[164:167], v[212:215], v[72:75]
	v_mfma_f32_16x16x32_bf16 v[116:119], v[168:171], v[184:187], v[116:119]
	v_mfma_f32_16x16x32_bf16 v[112:115], v[176:179], v[184:187], v[112:115]
	v_mfma_f32_16x16x32_bf16 v[100:103], v[168:171], v[192:195], v[100:103]
	v_mfma_f32_16x16x32_bf16 v[96:99], v[176:179], v[192:195], v[96:99]
	v_mfma_f32_16x16x32_bf16 v[84:87], v[168:171], v[200:203], v[84:87]
	v_mfma_f32_16x16x32_bf16 v[80:83], v[176:179], v[200:203], v[80:83]
	v_mfma_f32_16x16x32_bf16 v[68:71], v[168:171], v[208:211], v[68:71]
	v_mfma_f32_16x16x32_bf16 v[64:67], v[176:179], v[208:211], v[64:67]
	v_mfma_f32_16x16x32_bf16 v[116:119], v[172:175], v[188:191], v[116:119]
	v_mfma_f32_16x16x32_bf16 v[112:115], v[180:183], v[188:191], v[112:115]
	v_mfma_f32_16x16x32_bf16 v[100:103], v[172:175], v[196:199], v[100:103]
	v_mfma_f32_16x16x32_bf16 v[96:99], v[180:183], v[196:199], v[96:99]
	v_mfma_f32_16x16x32_bf16 v[84:87], v[172:175], v[204:207], v[84:87]
	v_mfma_f32_16x16x32_bf16 v[80:83], v[180:183], v[204:207], v[80:83]
	v_mfma_f32_16x16x32_bf16 v[68:71], v[172:175], v[212:215], v[68:71]
	v_mfma_f32_16x16x32_bf16 v[64:67], v[180:183], v[212:215], v[64:67]
	s_barrier
	s_add_i32 s64, s56, s43
	v_lshl_add_u64 v[216:217], s[34:35], 0, v[132:133]
	s_mov_b32 m0, s64
	ds_read_b128 v[184:187], v151 offset:16384
	ds_read_b128 v[188:191], v151 offset:17408
	ds_read_b128 v[192:195], v151 offset:18432
	ds_read_b128 v[196:199], v151 offset:19456
	ds_read_b128 v[200:203], v151 offset:20480
	ds_read_b128 v[204:207], v151 offset:21504
	ds_read_b128 v[208:211], v151 offset:22528
	ds_read_b128 v[212:215], v151 offset:23552
	global_load_lds_dwordx4 v[216:217], off
	s_add_i32 m0, s64, 0x2000
	s_add_u32 s64, s34, 0x40000
	v_lshl_add_u64 v[218:219], s[34:35], 0, v[128:129]
	s_addc_u32 s65, s35, 0
	s_add_i32 s66, s57, s43
	global_load_lds_dwordx4 v[218:219], off
	v_lshl_add_u64 v[220:221], s[64:65], 0, v[132:133]
	s_mov_b32 m0, s66
	v_lshl_add_u64 v[222:223], s[36:37], 0, v[130:131]
	global_load_lds_dwordx4 v[220:221], off
	v_lshl_add_u64 v[220:221], s[64:65], 0, v[128:129]
	s_add_i32 m0, s66, 0x2000
	s_nop 0
	global_load_lds_dwordx4 v[220:221], off
	v_lshl_add_u64 v[220:221], s[36:37], 0, v[134:135]
	s_mov_b32 m0, s46
	s_nop 0
	global_load_lds_dwordx4 v[220:221], off
	s_mov_b32 m0, s47
	s_nop 0
	global_load_lds_dwordx4 v[222:223], off
	s_waitcnt vmcnt(8)
	s_waitcnt lgkmcnt(0)
	s_barrier
	s_waitcnt lgkmcnt(0)
	v_mfma_f32_16x16x32_bf16 v[60:63], v[144:147], v[184:187], v[60:63]
	v_mfma_f32_16x16x32_bf16 v[56:59], v[160:163], v[184:187], v[56:59]
	v_mfma_f32_16x16x32_bf16 v[44:47], v[144:147], v[192:195], v[44:47]
	v_mfma_f32_16x16x32_bf16 v[40:43], v[160:163], v[192:195], v[40:43]
	v_mfma_f32_16x16x32_bf16 v[28:31], v[144:147], v[200:203], v[28:31]
	v_mfma_f32_16x16x32_bf16 v[24:27], v[160:163], v[200:203], v[24:27]
	v_mfma_f32_16x16x32_bf16 v[12:15], v[144:147], v[208:211], v[12:15]
	v_mfma_f32_16x16x32_bf16 v[8:11], v[160:163], v[208:211], v[8:11]
	v_mfma_f32_16x16x32_bf16 v[60:63], v[156:159], v[188:191], v[60:63]
	v_mfma_f32_16x16x32_bf16 v[56:59], v[164:167], v[188:191], v[56:59]
	v_mfma_f32_16x16x32_bf16 v[44:47], v[156:159], v[196:199], v[44:47]
	v_mfma_f32_16x16x32_bf16 v[40:43], v[164:167], v[196:199], v[40:43]
	v_mfma_f32_16x16x32_bf16 v[28:31], v[156:159], v[204:207], v[28:31]
	v_mfma_f32_16x16x32_bf16 v[24:27], v[164:167], v[204:207], v[24:27]
	v_mfma_f32_16x16x32_bf16 v[12:15], v[156:159], v[212:215], v[12:15]
	v_mfma_f32_16x16x32_bf16 v[8:11], v[164:167], v[212:215], v[8:11]
	v_mfma_f32_16x16x32_bf16 v[52:55], v[168:171], v[184:187], v[52:55]
	v_mfma_f32_16x16x32_bf16 v[48:51], v[176:179], v[184:187], v[48:51]
	v_mfma_f32_16x16x32_bf16 v[36:39], v[168:171], v[192:195], v[36:39]
	v_mfma_f32_16x16x32_bf16 v[32:35], v[176:179], v[192:195], v[32:35]
	v_mfma_f32_16x16x32_bf16 v[20:23], v[168:171], v[200:203], v[20:23]
	v_mfma_f32_16x16x32_bf16 v[16:19], v[176:179], v[200:203], v[16:19]
	v_mfma_f32_16x16x32_bf16 v[4:7], v[168:171], v[208:211], v[4:7]
	v_mfma_f32_16x16x32_bf16 v[0:3], v[176:179], v[208:211], v[0:3]
	v_mfma_f32_16x16x32_bf16 v[52:55], v[172:175], v[188:191], v[52:55]
	v_mfma_f32_16x16x32_bf16 v[48:51], v[180:183], v[188:191], v[48:51]
	v_mfma_f32_16x16x32_bf16 v[36:39], v[172:175], v[196:199], v[36:39]
	v_mfma_f32_16x16x32_bf16 v[32:35], v[180:183], v[196:199], v[32:35]
	v_mfma_f32_16x16x32_bf16 v[20:23], v[172:175], v[204:207], v[20:23]
	v_mfma_f32_16x16x32_bf16 v[16:19], v[180:183], v[204:207], v[16:19]
	v_mfma_f32_16x16x32_bf16 v[4:7], v[172:175], v[212:215], v[4:7]
	v_mfma_f32_16x16x32_bf16 v[0:3], v[180:183], v[212:215], v[0:3]
	s_barrier
	s_add_i32 s64, 0, 0x18000
	v_add_u32_e32 v153, s64, v148
	s_add_i32 s65, 0, 0x1c000
	ds_read_b128 v[144:147], v153
	ds_read_b128 v[156:159], v153 offset:1024
	ds_read_b128 v[160:163], v153 offset:2048
	ds_read_b128 v[164:167], v153 offset:3072
	v_add_u32_e32 v153, s65, v148
	ds_read_b128 v[168:171], v153
	ds_read_b128 v[172:175], v153 offset:1024
	ds_read_b128 v[176:179], v153 offset:2048
	ds_read_b128 v[180:183], v153 offset:3072
	s_add_u32 s36, s36, 0x40000
	s_addc_u32 s37, s37, 0
	s_mov_b32 m0, s48
	v_lshl_add_u64 v[224:225], s[36:37], 0, v[134:135]
	ds_read_b128 v[184:187], v151 offset:32768
	ds_read_b128 v[188:191], v151 offset:33792
	ds_read_b128 v[192:195], v151 offset:34816
	ds_read_b128 v[196:199], v151 offset:35840
	ds_read_b128 v[200:203], v151 offset:36864
	ds_read_b128 v[204:207], v151 offset:37888
	ds_read_b128 v[208:211], v151 offset:38912
	ds_read_b128 v[212:215], v151 offset:39936
	global_load_lds_dwordx4 v[224:225], off
	v_lshl_add_u64 v[224:225], s[36:37], 0, v[130:131]
	s_mov_b32 m0, s49
	s_nop 0
	global_load_lds_dwordx4 v[224:225], off
	s_waitcnt vmcnt(8)
	s_waitcnt lgkmcnt(0)
	s_barrier
	s_waitcnt lgkmcnt(0)
	v_mfma_f32_16x16x32_bf16 v[124:127], v[144:147], v[184:187], v[124:127]
	v_mfma_f32_16x16x32_bf16 v[120:123], v[160:163], v[184:187], v[120:123]
	v_mfma_f32_16x16x32_bf16 v[108:111], v[144:147], v[192:195], v[108:111]
	v_mfma_f32_16x16x32_bf16 v[104:107], v[160:163], v[192:195], v[104:107]
	v_mfma_f32_16x16x32_bf16 v[92:95], v[144:147], v[200:203], v[92:95]
	v_mfma_f32_16x16x32_bf16 v[88:91], v[160:163], v[200:203], v[88:91]
	v_mfma_f32_16x16x32_bf16 v[76:79], v[144:147], v[208:211], v[76:79]
	v_mfma_f32_16x16x32_bf16 v[72:75], v[160:163], v[208:211], v[72:75]
	v_mfma_f32_16x16x32_bf16 v[124:127], v[156:159], v[188:191], v[124:127]
	v_mfma_f32_16x16x32_bf16 v[120:123], v[164:167], v[188:191], v[120:123]
	v_mfma_f32_16x16x32_bf16 v[108:111], v[156:159], v[196:199], v[108:111]
	v_mfma_f32_16x16x32_bf16 v[104:107], v[164:167], v[196:199], v[104:107]
	v_mfma_f32_16x16x32_bf16 v[92:95], v[156:159], v[204:207], v[92:95]
	v_mfma_f32_16x16x32_bf16 v[88:91], v[164:167], v[204:207], v[88:91]
	v_mfma_f32_16x16x32_bf16 v[76:79], v[156:159], v[212:215], v[76:79]
	v_mfma_f32_16x16x32_bf16 v[72:75], v[164:167], v[212:215], v[72:75]
	v_mfma_f32_16x16x32_bf16 v[116:119], v[168:171], v[184:187], v[116:119]
	v_mfma_f32_16x16x32_bf16 v[112:115], v[176:179], v[184:187], v[112:115]
	v_mfma_f32_16x16x32_bf16 v[100:103], v[168:171], v[192:195], v[100:103]
	v_mfma_f32_16x16x32_bf16 v[96:99], v[176:179], v[192:195], v[96:99]
	v_mfma_f32_16x16x32_bf16 v[84:87], v[168:171], v[200:203], v[84:87]
	v_mfma_f32_16x16x32_bf16 v[80:83], v[176:179], v[200:203], v[80:83]
	v_mfma_f32_16x16x32_bf16 v[68:71], v[168:171], v[208:211], v[68:71]
	v_mfma_f32_16x16x32_bf16 v[64:67], v[176:179], v[208:211], v[64:67]
	v_mfma_f32_16x16x32_bf16 v[116:119], v[172:175], v[188:191], v[116:119]
	v_mfma_f32_16x16x32_bf16 v[112:115], v[180:183], v[188:191], v[112:115]
	v_mfma_f32_16x16x32_bf16 v[100:103], v[172:175], v[196:199], v[100:103]
	v_mfma_f32_16x16x32_bf16 v[96:99], v[180:183], v[196:199], v[96:99]
	v_mfma_f32_16x16x32_bf16 v[84:87], v[172:175], v[204:207], v[84:87]
	v_mfma_f32_16x16x32_bf16 v[80:83], v[180:183], v[204:207], v[80:83]
	v_mfma_f32_16x16x32_bf16 v[68:71], v[172:175], v[212:215], v[68:71]
	v_mfma_f32_16x16x32_bf16 v[64:67], v[180:183], v[212:215], v[64:67]
	s_barrier
	s_add_i32 s36, s64, s43
	v_lshl_add_u64 v[216:217], v[216:217], 0, s[8:9]
	s_mov_b32 m0, s36
	ds_read_b128 v[184:187], v151 offset:49152
	ds_read_b128 v[188:191], v151 offset:50176
	ds_read_b128 v[192:195], v151 offset:51200
	ds_read_b128 v[196:199], v151 offset:52224
	ds_read_b128 v[200:203], v151 offset:53248
	ds_read_b128 v[204:207], v151 offset:54272
	ds_read_b128 v[208:211], v151 offset:55296
	ds_read_b128 v[212:215], v151 offset:56320
	global_load_lds_dwordx4 v[216:217], off
	s_add_i32 m0, s36, 0x2000
	s_add_u32 s34, s34, 0x40080
	v_lshl_add_u64 v[216:217], v[218:219], 0, s[8:9]
	s_addc_u32 s35, s35, 0
	s_add_i32 s36, s65, s43
	global_load_lds_dwordx4 v[216:217], off
	v_lshl_add_u64 v[216:217], s[34:35], 0, v[132:133]
	s_mov_b32 m0, s36
	s_nop 0
	global_load_lds_dwordx4 v[216:217], off
	v_lshl_add_u64 v[216:217], s[34:35], 0, v[128:129]
	s_add_i32 m0, s36, 0x2000
	s_nop 0
	global_load_lds_dwordx4 v[216:217], off
	v_lshl_add_u64 v[216:217], v[220:221], 0, s[8:9]
	s_mov_b32 m0, s53
	s_nop 0
	global_load_lds_dwordx4 v[216:217], off
	v_lshl_add_u64 v[216:217], v[222:223], 0, s[8:9]
	s_mov_b32 m0, s54
	s_nop 0
	global_load_lds_dwordx4 v[216:217], off
	s_waitcnt vmcnt(8)
	s_waitcnt lgkmcnt(0)
	s_barrier
	s_waitcnt lgkmcnt(0)
	v_mfma_f32_16x16x32_bf16 v[60:63], v[144:147], v[184:187], v[60:63]
	v_mfma_f32_16x16x32_bf16 v[56:59], v[160:163], v[184:187], v[56:59]
	v_mfma_f32_16x16x32_bf16 v[44:47], v[144:147], v[192:195], v[44:47]
	v_mfma_f32_16x16x32_bf16 v[40:43], v[160:163], v[192:195], v[40:43]
	v_mfma_f32_16x16x32_bf16 v[28:31], v[144:147], v[200:203], v[28:31]
	v_mfma_f32_16x16x32_bf16 v[24:27], v[160:163], v[200:203], v[24:27]
	v_mfma_f32_16x16x32_bf16 v[12:15], v[144:147], v[208:211], v[12:15]
	v_mfma_f32_16x16x32_bf16 v[8:11], v[160:163], v[208:211], v[8:11]
	v_mfma_f32_16x16x32_bf16 v[60:63], v[156:159], v[188:191], v[60:63]
	v_mfma_f32_16x16x32_bf16 v[56:59], v[164:167], v[188:191], v[56:59]
	v_mfma_f32_16x16x32_bf16 v[44:47], v[156:159], v[196:199], v[44:47]
	v_mfma_f32_16x16x32_bf16 v[40:43], v[164:167], v[196:199], v[40:43]
	v_mfma_f32_16x16x32_bf16 v[28:31], v[156:159], v[204:207], v[28:31]
	v_mfma_f32_16x16x32_bf16 v[24:27], v[164:167], v[204:207], v[24:27]
	v_mfma_f32_16x16x32_bf16 v[12:15], v[156:159], v[212:215], v[12:15]
	v_mfma_f32_16x16x32_bf16 v[8:11], v[164:167], v[212:215], v[8:11]
	v_mfma_f32_16x16x32_bf16 v[52:55], v[168:171], v[184:187], v[52:55]
	v_mfma_f32_16x16x32_bf16 v[48:51], v[176:179], v[184:187], v[48:51]
	v_mfma_f32_16x16x32_bf16 v[36:39], v[168:171], v[192:195], v[36:39]
	v_mfma_f32_16x16x32_bf16 v[32:35], v[176:179], v[192:195], v[32:35]
	v_mfma_f32_16x16x32_bf16 v[20:23], v[168:171], v[200:203], v[20:23]
	v_mfma_f32_16x16x32_bf16 v[16:19], v[176:179], v[200:203], v[16:19]
	v_mfma_f32_16x16x32_bf16 v[4:7], v[168:171], v[208:211], v[4:7]
	v_mfma_f32_16x16x32_bf16 v[0:3], v[176:179], v[208:211], v[0:3]
	v_mfma_f32_16x16x32_bf16 v[52:55], v[172:175], v[188:191], v[52:55]
	v_mfma_f32_16x16x32_bf16 v[48:51], v[180:183], v[188:191], v[48:51]
	v_mfma_f32_16x16x32_bf16 v[36:39], v[172:175], v[196:199], v[36:39]
	v_mfma_f32_16x16x32_bf16 v[32:35], v[180:183], v[196:199], v[32:35]
	v_mfma_f32_16x16x32_bf16 v[20:23], v[172:175], v[204:207], v[20:23]
	v_mfma_f32_16x16x32_bf16 v[16:19], v[180:183], v[204:207], v[16:19]
	v_mfma_f32_16x16x32_bf16 v[4:7], v[172:175], v[212:215], v[4:7]
	v_mfma_f32_16x16x32_bf16 v[0:3], v[180:183], v[212:215], v[0:3]
	s_barrier
	s_add_i32 s63, s63, 2
	s_add_u32 s61, s61, 0x100
	s_addc_u32 s62, s62, 0
	s_add_u32 s30, s30, 0x100
	s_addc_u32 s31, s31, 0
	s_cmp_gt_u32 s63, 13
	s_cbranch_scc0 .LBB0_967
	s_and_b64 vcc, exec, s[10:11]
	s_cbranch_vccz .LBB0_970
	s_barrier

.LBB0_1066:
	s_or_b64 exec, exec, s[6:7]
	s_mov_b64 s[6:7], s[0:1]
	s_getreg_b32 s3, hwreg(HW_REG_XCC_ID, 0, 4)
	s_setprio 0
	s_waitcnt vmcnt(0)
	s_barrier
	s_and_saveexec_b64 s[4:5], s[20:21]
	s_cbranch_execz .LBB0_1118
	s_add_i32 s8, 0, 0x23fc0
	v_mov_b32_e32 v0, s8
	s_load_dwordx2 s[6:7], s[6:7], 0x138
	s_waitcnt vmcnt(0) expcnt(0) lgkmcnt(0)
	ds_read_b32 v2, v0
	s_add_i32 s8, 0, 0x23fc4
	v_mov_b32_e32 v0, s8
	ds_read_b32 v0, v0
	s_and_b32 s3, s3, 15
	s_waitcnt lgkmcnt(1)
	v_cmp_ne_u32_e32 vcc, 0, v2
	s_cbranch_vccnz .LBB0_1082
	s_load_dword s8, s[22:23], 0x14
	s_mov_b32 s56, 1
	v_mov_b32_e32 v16, 0
	s_waitcnt lgkmcnt(0)
	s_lshr_b32 s10, s8, 16
	s_and_b32 s8, s8, 0xffff
	s_cmp_lg_u32 s8, 0
	s_cselect_b64 s[8:9], -1, 0
	s_cmp_lg_u64 s[8:9], 0
	s_addc_u32 s8, s24, 0
	s_cmp_lg_u32 s10, 0
	s_mul_i32 s57, s8, s33
	s_cselect_b64 s[8:9], -1, 0
	s_cmp_lg_u64 s[8:9], 0
	s_addc_u32 s8, s25, 0
	s_mul_i32 s57, s57, s8
	s_add_u32 s8, s6, 0x4200
	s_addc_u32 s9, s7, 0
	s_add_u32 s10, s6, 0x4400
	s_addc_u32 s11, s7, 0
	s_add_u32 s12, s6, 0x4500
	s_addc_u32 s13, s7, 0
	s_add_u32 s14, s6, 0x4600
	s_addc_u32 s15, s7, 0
	s_add_u32 s16, s6, 0x4700
	s_addc_u32 s17, s7, 0
	s_add_u32 s18, s6, 0x4800
	s_addc_u32 s19, s7, 0
	s_add_u32 s26, s6, 0x4900
	s_addc_u32 s27, s7, 0
	s_add_u32 s28, s6, 0x4a00
	s_addc_u32 s29, s7, 0
	s_add_u32 s30, s6, 0x4b00
	s_addc_u32 s31, s7, 0
	s_add_u32 s34, s6, 0x4c00
	s_addc_u32 s35, s7, 0
	s_add_u32 s36, s6, 0x4d00
	s_addc_u32 s37, s7, 0
	s_add_u32 s38, s6, 0x4e00
	s_addc_u32 s39, s7, 0
	s_add_u32 s40, s6, 0x4f00
	s_addc_u32 s41, s7, 0
	s_add_u32 s42, s6, 0x5000
	s_addc_u32 s43, s7, 0
	s_add_u32 s44, s6, 0x5100
	s_addc_u32 s45, s7, 0
	s_add_u32 s46, s6, 0x5200
	s_addc_u32 s47, s7, 0
	s_add_u32 s48, s6, 0x5300
	s_addc_u32 s49, s7, 0
	s_branch .LBB0_1070

.LBB0_1118:
	s_or_b64 exec, exec, s[4:5]
	s_mov_b64 s[4:5], s[0:1]
	s_mov_b32 s3, s2
	s_waitcnt lgkmcnt(0)
	v_mov_b32_e32 v0, v154
	s_barrier
	v_readfirstlane_b32 s94, v154
	s_cmpk_ge_u32 s94, 0x100
	s_cbranch_scc1 .Lprio_skip_11
	s_setprio 1
.Lprio_skip_11:
	s_mov_b32 s6, 0x40000
	v_lshl_add_u32 v2, s3, 9, v0
	s_mov_b32 s3, s33
	v_cmp_gt_i32_e32 vcc, s6, v2
	s_and_saveexec_b64 s[6:7], vcc
	s_cbranch_execz .LBB0_1121
	s_load_dwordx2 s[4:5], s[4:5], 0x138
	s_lshl_b32 s3, s3, 9
	s_mov_b64 s[8:9], 0
	s_mov_b32 s12, 0xc2fc0000
	v_mov_b32_e32 v3, 0
	s_waitcnt lgkmcnt(0)
	s_add_u32 s10, s4, 0x2300000
	s_addc_u32 s11, s5, 0
	v_mov_b32_e32 v4, 0x42800000
	v_not_b32_e32 v5, 63
	s_mov_b32 s13, 0x3f2aaaab
	v_mov_b32_e32 v6, 0x3ecc95a3
	s_mov_b32 s14, 0x3f317218
	v_mov_b32_e32 v7, 0x7fc00000
	v_mov_b32_e32 v8, 0xff800000
	s_mov_b32 s15, 0x33800000
	s_mov_b32 s16, 0x3ffff
	v_mov_b32_e32 v0, 0x3f317218

.LBB0_1137:
	s_ashr_i32 s35, s34, 31
	s_lshl_b64 s[12:13], s[34:35], 17
	s_add_u32 s36, s44, s12
	s_addc_u32 s37, s45, s13
	s_and_b64 s[12:13], s[4:5], exec
	s_cselect_b32 s13, s37, s11
	s_cselect_b32 s12, s36, s10
	s_ashr_i32 s31, s30, 31
	s_lshl_b64 s[38:39], s[30:31], 16
	s_add_u32 s38, s46, s38
	s_addc_u32 s39, s47, s39
	s_add_u32 s40, s10, 0x10080
	ds_read_b128 v[0:3], v153
	ds_read_b128 v[4:7], v153 offset:1024
	ds_read_b128 v[8:11], v153 offset:2048
	ds_read_b128 v[12:15], v153 offset:3072
	ds_read_b128 v[16:19], v156
	ds_read_b128 v[20:23], v156 offset:1024
	ds_read_b128 v[24:27], v156 offset:2048
	ds_read_b128 v[28:31], v156 offset:3072
	s_addc_u32 s41, s11, 0
	s_add_u32 s10, s12, 0x10000
	s_addc_u32 s11, s13, 0
	s_and_b64 s[42:43], s[4:5], exec
	s_cselect_b32 s8, s38, s8
	s_cselect_b32 s9, s39, s9
	s_add_u32 s42, s8, 0x8000
	s_addc_u32 s43, s9, 0
	v_lshl_add_u64 v[64:65], s[40:41], 0, v[136:137]
	s_add_i32 m0, s49, 0xc000
	ds_read_b128 v[32:35], v157
	ds_read_b128 v[36:39], v157 offset:1024
	ds_read_b128 v[40:43], v157 offset:2048
	ds_read_b128 v[44:47], v157 offset:3072
	ds_read_b128 v[48:51], v157 offset:4096
	ds_read_b128 v[52:55], v157 offset:5120
	ds_read_b128 v[56:59], v157 offset:6144
	ds_read_b128 v[60:63], v157 offset:7168
	global_load_lds_dwordx4 v[64:65], off
	v_lshl_add_u64 v[64:65], s[40:41], 0, v[140:141]
	s_add_i32 m0, s49, 0xe000
	s_nop 0
	global_load_lds_dwordx4 v[64:65], off
	s_waitcnt vmcnt(8)
	s_waitcnt lgkmcnt(0)
	s_barrier
	s_waitcnt lgkmcnt(0)
	v_mfma_f32_16x16x32_bf16 v[64:67], v[0:3], v[32:35], 0
	v_mfma_f32_16x16x32_bf16 v[68:71], v[8:11], v[32:35], 0
	v_mfma_f32_16x16x32_bf16 v[72:75], v[0:3], v[40:43], 0
	v_mfma_f32_16x16x32_bf16 v[76:79], v[8:11], v[40:43], 0
	v_mfma_f32_16x16x32_bf16 v[80:83], v[0:3], v[48:51], 0
	v_mfma_f32_16x16x32_bf16 v[84:87], v[8:11], v[48:51], 0
	v_mfma_f32_16x16x32_bf16 v[88:91], v[0:3], v[56:59], 0
	v_mfma_f32_16x16x32_bf16 v[92:95], v[8:11], v[56:59], 0
	v_mfma_f32_16x16x32_bf16 v[64:67], v[4:7], v[36:39], v[64:67]
	v_mfma_f32_16x16x32_bf16 v[68:71], v[12:15], v[36:39], v[68:71]
	v_mfma_f32_16x16x32_bf16 v[72:75], v[4:7], v[44:47], v[72:75]
	v_mfma_f32_16x16x32_bf16 v[76:79], v[12:15], v[44:47], v[76:79]
	v_mfma_f32_16x16x32_bf16 v[80:83], v[4:7], v[52:55], v[80:83]
	v_mfma_f32_16x16x32_bf16 v[84:87], v[12:15], v[52:55], v[84:87]
	v_mfma_f32_16x16x32_bf16 v[88:91], v[4:7], v[60:63], v[88:91]
	v_mfma_f32_16x16x32_bf16 v[92:95], v[12:15], v[60:63], v[92:95]
	v_mfma_f32_16x16x32_bf16 v[96:99], v[16:19], v[32:35], 0
	v_mfma_f32_16x16x32_bf16 v[32:35], v[24:27], v[32:35], 0
	v_mfma_f32_16x16x32_bf16 v[120:123], v[20:23], v[36:39], v[96:99]
	v_mfma_f32_16x16x32_bf16 v[32:35], v[28:31], v[36:39], v[32:35]
	v_mfma_f32_16x16x32_bf16 v[36:39], v[16:19], v[40:43], 0
	v_mfma_f32_16x16x32_bf16 v[40:43], v[24:27], v[40:43], 0
	v_mfma_f32_16x16x32_bf16 v[36:39], v[20:23], v[44:47], v[36:39]
	v_mfma_f32_16x16x32_bf16 v[40:43], v[28:31], v[44:47], v[40:43]
	v_mfma_f32_16x16x32_bf16 v[44:47], v[16:19], v[48:51], 0
	v_mfma_f32_16x16x32_bf16 v[48:51], v[24:27], v[48:51], 0
	v_mfma_f32_16x16x32_bf16 v[124:127], v[28:31], v[52:55], v[48:51]
	v_mfma_f32_16x16x32_bf16 v[48:51], v[16:19], v[56:59], 0
	v_mfma_f32_16x16x32_bf16 v[44:47], v[20:23], v[52:55], v[44:47]
	v_mfma_f32_16x16x32_bf16 v[148:151], v[20:23], v[60:63], v[48:51]
	v_mfma_f32_16x16x32_bf16 v[48:51], v[24:27], v[56:59], 0
	v_mfma_f32_16x16x32_bf16 v[160:163], v[28:31], v[60:63], v[48:51]
	s_barrier
	s_add_i32 s31, s58, s48
	v_lshl_add_u64 v[252:253], s[8:9], 0, v[138:139]
	s_mov_b32 m0, s31
	s_nop 1
	ds_read_b128 v[48:51], v157 offset:16384
	ds_read_b128 v[52:55], v157 offset:17408
	ds_read_b128 v[56:59], v157 offset:18432
	ds_read_b128 v[60:63], v157 offset:19456
	ds_read_b128 v[96:99], v157 offset:20480
	ds_read_b128 v[100:103], v157 offset:21504
	ds_read_b128 v[104:107], v157 offset:22528
	ds_read_b128 v[108:111], v157 offset:23552
	global_load_lds_dwordx4 v[252:253], off
	v_lshl_add_u64 v[254:255], s[8:9], 0, v[142:143]
	s_add_i32 m0, s31, 0x2000
	s_add_i32 s31, s59, s48
	global_load_lds_dwordx4 v[254:255], off
	v_lshl_add_u64 v[112:113], s[42:43], 0, v[138:139]
	s_mov_b32 m0, s31
	v_lshl_add_u64 v[144:145], s[12:13], 0, v[136:137]
	global_load_lds_dwordx4 v[112:113], off
	v_lshl_add_u64 v[112:113], s[42:43], 0, v[142:143]
	s_add_i32 m0, s31, 0x2000
	v_lshl_add_u64 v[146:147], s[12:13], 0, v[140:141]
	global_load_lds_dwordx4 v[112:113], off
	s_mov_b32 m0, s49
	s_nop 0
	global_load_lds_dwordx4 v[144:145], off
	s_mov_b32 m0, s50
	s_nop 0
	global_load_lds_dwordx4 v[146:147], off
	s_waitcnt vmcnt(8)
	s_waitcnt lgkmcnt(0)
	s_barrier
	s_waitcnt lgkmcnt(0)
	v_mfma_f32_16x16x32_bf16 v[112:115], v[0:3], v[48:51], 0
	v_mfma_f32_16x16x32_bf16 v[164:167], v[4:7], v[52:55], v[112:115]
	v_mfma_f32_16x16x32_bf16 v[112:115], v[8:11], v[48:51], 0
	v_mfma_f32_16x16x32_bf16 v[168:171], v[12:15], v[52:55], v[112:115]
	v_mfma_f32_16x16x32_bf16 v[112:115], v[0:3], v[56:59], 0
	v_mfma_f32_16x16x32_bf16 v[172:175], v[4:7], v[60:63], v[112:115]
	v_mfma_f32_16x16x32_bf16 v[112:115], v[8:11], v[56:59], 0
	v_mfma_f32_16x16x32_bf16 v[176:179], v[12:15], v[60:63], v[112:115]
	v_mfma_f32_16x16x32_bf16 v[112:115], v[0:3], v[96:99], 0
	v_mfma_f32_16x16x32_bf16 v[0:3], v[0:3], v[104:107], 0
	v_mfma_f32_16x16x32_bf16 v[180:183], v[4:7], v[100:103], v[112:115]
	v_mfma_f32_16x16x32_bf16 v[0:3], v[4:7], v[108:111], v[0:3]
	v_mfma_f32_16x16x32_bf16 v[4:7], v[8:11], v[104:107], 0
	v_mfma_f32_16x16x32_bf16 v[112:115], v[8:11], v[96:99], 0
	v_mfma_f32_16x16x32_bf16 v[4:7], v[12:15], v[108:111], v[4:7]
	v_mfma_f32_16x16x32_bf16 v[184:187], v[12:15], v[100:103], v[112:115]
	v_mfma_f32_16x16x32_bf16 v[8:11], v[16:19], v[48:51], 0
	v_mfma_f32_16x16x32_bf16 v[12:15], v[24:27], v[48:51], 0
	v_mfma_f32_16x16x32_bf16 v[48:51], v[16:19], v[56:59], 0
	v_mfma_f32_16x16x32_bf16 v[188:191], v[20:23], v[60:63], v[48:51]
	v_mfma_f32_16x16x32_bf16 v[48:51], v[24:27], v[56:59], 0
	v_mfma_f32_16x16x32_bf16 v[192:195], v[28:31], v[60:63], v[48:51]
	v_mfma_f32_16x16x32_bf16 v[48:51], v[16:19], v[96:99], 0
	v_mfma_f32_16x16x32_bf16 v[16:19], v[16:19], v[104:107], 0
	v_mfma_f32_16x16x32_bf16 v[8:11], v[20:23], v[52:55], v[8:11]
	v_mfma_f32_16x16x32_bf16 v[12:15], v[28:31], v[52:55], v[12:15]
	v_mfma_f32_16x16x32_bf16 v[196:199], v[20:23], v[100:103], v[48:51]
	v_mfma_f32_16x16x32_bf16 v[48:51], v[24:27], v[96:99], 0
	v_mfma_f32_16x16x32_bf16 v[204:207], v[20:23], v[108:111], v[16:19]
	v_mfma_f32_16x16x32_bf16 v[16:19], v[24:27], v[104:107], 0
	v_mfma_f32_16x16x32_bf16 v[200:203], v[28:31], v[100:103], v[48:51]
	v_mfma_f32_16x16x32_bf16 v[208:211], v[28:31], v[108:111], v[16:19]
	s_barrier
	s_add_i32 s12, 0, 0x18000
	s_add_i32 s13, 0, 0x1c000
	v_add_u32_e32 v28, s12, v152
	v_add_u32_e32 v48, s13, v152
	ds_read_b128 v[16:19], v28
	ds_read_b128 v[20:23], v28 offset:1024
	ds_read_b128 v[24:27], v28 offset:2048
	ds_read_b128 v[28:31], v28 offset:3072
	ds_read_b128 v[212:215], v48
	ds_read_b128 v[216:219], v48 offset:1024
	ds_read_b128 v[220:223], v48 offset:2048
	ds_read_b128 v[224:227], v48 offset:3072
	s_mov_b32 m0, s51
	v_lshl_add_u64 v[56:57], s[10:11], 0, v[136:137]
	ds_read_b128 v[48:51], v157 offset:32768
	ds_read_b128 v[52:55], v157 offset:33792
	ds_read_b128 v[228:231], v157 offset:34816
	ds_read_b128 v[232:235], v157 offset:35840
	ds_read_b128 v[236:239], v157 offset:36864
	ds_read_b128 v[240:243], v157 offset:37888
	ds_read_b128 v[244:247], v157 offset:38912
	ds_read_b128 v[248:251], v157 offset:39936
	global_load_lds_dwordx4 v[56:57], off
	v_lshl_add_u64 v[56:57], s[10:11], 0, v[140:141]
	s_mov_b32 m0, s52
	s_nop 0
	global_load_lds_dwordx4 v[56:57], off
	s_waitcnt vmcnt(8)
	s_waitcnt lgkmcnt(0)
	s_barrier
	s_waitcnt lgkmcnt(0)
	v_mfma_f32_16x16x32_bf16 v[56:59], v[16:19], v[48:51], v[64:67]
	v_mfma_f32_16x16x32_bf16 v[132:135], v[20:23], v[52:55], v[56:59]
	v_mfma_f32_16x16x32_bf16 v[56:59], v[24:27], v[48:51], v[68:71]
	v_mfma_f32_16x16x32_bf16 v[128:131], v[28:31], v[52:55], v[56:59]
	v_mfma_f32_16x16x32_bf16 v[56:59], v[16:19], v[228:231], v[72:75]
	v_mfma_f32_16x16x32_bf16 v[116:119], v[20:23], v[232:235], v[56:59]
	v_mfma_f32_16x16x32_bf16 v[56:59], v[24:27], v[228:231], v[76:79]
	v_mfma_f32_16x16x32_bf16 v[112:115], v[28:31], v[232:235], v[56:59]
	v_mfma_f32_16x16x32_bf16 v[56:59], v[16:19], v[236:239], v[80:83]
	v_mfma_f32_16x16x32_bf16 v[108:111], v[20:23], v[240:243], v[56:59]
	v_mfma_f32_16x16x32_bf16 v[56:59], v[24:27], v[236:239], v[84:87]
	v_mfma_f32_16x16x32_bf16 v[104:107], v[28:31], v[240:243], v[56:59]
	v_mfma_f32_16x16x32_bf16 v[56:59], v[16:19], v[244:247], v[88:91]
	v_mfma_f32_16x16x32_bf16 v[100:103], v[20:23], v[248:251], v[56:59]
	v_mfma_f32_16x16x32_bf16 v[56:59], v[24:27], v[244:247], v[92:95]
	v_mfma_f32_16x16x32_bf16 v[96:99], v[28:31], v[248:251], v[56:59]
	v_mfma_f32_16x16x32_bf16 v[56:59], v[212:215], v[48:51], v[120:123]
	v_mfma_f32_16x16x32_bf16 v[32:35], v[220:223], v[48:51], v[32:35]
	v_mfma_f32_16x16x32_bf16 v[60:63], v[216:219], v[52:55], v[56:59]
	v_mfma_f32_16x16x32_bf16 v[56:59], v[224:227], v[52:55], v[32:35]
	v_mfma_f32_16x16x32_bf16 v[32:35], v[212:215], v[228:231], v[36:39]
	v_mfma_f32_16x16x32_bf16 v[52:55], v[216:219], v[232:235], v[32:35]
	v_mfma_f32_16x16x32_bf16 v[32:35], v[220:223], v[228:231], v[40:43]
	v_mfma_f32_16x16x32_bf16 v[48:51], v[224:227], v[232:235], v[32:35]
	v_mfma_f32_16x16x32_bf16 v[32:35], v[212:215], v[236:239], v[44:47]
	v_mfma_f32_16x16x32_bf16 v[44:47], v[216:219], v[240:243], v[32:35]
	v_mfma_f32_16x16x32_bf16 v[32:35], v[220:223], v[236:239], v[124:127]
	v_mfma_f32_16x16x32_bf16 v[40:43], v[224:227], v[240:243], v[32:35]
	v_mfma_f32_16x16x32_bf16 v[32:35], v[212:215], v[244:247], v[148:151]
	v_mfma_f32_16x16x32_bf16 v[36:39], v[216:219], v[248:251], v[32:35]
	v_mfma_f32_16x16x32_bf16 v[32:35], v[220:223], v[244:247], v[160:163]
	v_mfma_f32_16x16x32_bf16 v[32:35], v[224:227], v[248:251], v[32:35]
	s_barrier
	s_add_i32 s10, s12, s48
	v_lshl_add_u64 v[64:65], v[252:253], 0, s[16:17]
	s_mov_b32 m0, s10
	ds_read_b128 v[120:123], v157 offset:49152
	ds_read_b128 v[124:127], v157 offset:50176
	ds_read_b128 v[148:151], v157 offset:51200
	ds_read_b128 v[160:163], v157 offset:52224
	ds_read_b128 v[228:231], v157 offset:53248
	ds_read_b128 v[232:235], v157 offset:54272
	ds_read_b128 v[236:239], v157 offset:55296
	ds_read_b128 v[240:243], v157 offset:56320
	global_load_lds_dwordx4 v[64:65], off
	s_add_i32 m0, s10, 0x2000
	s_add_u32 s8, s8, 0x8080
	v_lshl_add_u64 v[64:65], v[254:255], 0, s[16:17]
	s_addc_u32 s9, s9, 0
	s_add_i32 s10, s13, s48
	global_load_lds_dwordx4 v[64:65], off
	v_lshl_add_u64 v[64:65], s[8:9], 0, v[138:139]
	s_mov_b32 m0, s10
	s_nop 0
	global_load_lds_dwordx4 v[64:65], off
	v_lshl_add_u64 v[64:65], s[8:9], 0, v[142:143]
	s_add_i32 m0, s10, 0x2000
	s_nop 0
	global_load_lds_dwordx4 v[64:65], off
	v_lshl_add_u64 v[64:65], v[144:145], 0, s[16:17]
	s_mov_b32 m0, s55
	s_nop 0
	global_load_lds_dwordx4 v[64:65], off
	v_lshl_add_u64 v[64:65], v[146:147], 0, s[16:17]
	s_mov_b32 m0, s56
	s_nop 0
	global_load_lds_dwordx4 v[64:65], off
	s_waitcnt vmcnt(8)
	s_waitcnt lgkmcnt(0)
	s_barrier
	s_waitcnt lgkmcnt(0)
	v_mfma_f32_16x16x32_bf16 v[64:67], v[16:19], v[120:123], v[164:167]
	v_mfma_f32_16x16x32_bf16 v[92:95], v[20:23], v[124:127], v[64:67]
	v_mfma_f32_16x16x32_bf16 v[64:67], v[24:27], v[120:123], v[168:171]
	v_mfma_f32_16x16x32_bf16 v[88:91], v[28:31], v[124:127], v[64:67]
	v_mfma_f32_16x16x32_bf16 v[64:67], v[16:19], v[148:151], v[172:175]
	v_mfma_f32_16x16x32_bf16 v[84:87], v[20:23], v[160:163], v[64:67]
	v_mfma_f32_16x16x32_bf16 v[64:67], v[24:27], v[148:151], v[176:179]
	v_mfma_f32_16x16x32_bf16 v[80:83], v[28:31], v[160:163], v[64:67]
	v_mfma_f32_16x16x32_bf16 v[64:67], v[16:19], v[228:231], v[180:183]
	v_mfma_f32_16x16x32_bf16 v[0:3], v[16:19], v[236:239], v[0:3]
	v_mfma_f32_16x16x32_bf16 v[76:79], v[20:23], v[232:235], v[64:67]
	v_mfma_f32_16x16x32_bf16 v[64:67], v[24:27], v[228:231], v[184:187]
	v_mfma_f32_16x16x32_bf16 v[68:71], v[20:23], v[240:243], v[0:3]
	v_mfma_f32_16x16x32_bf16 v[0:3], v[24:27], v[236:239], v[4:7]
	v_mfma_f32_16x16x32_bf16 v[72:75], v[28:31], v[232:235], v[64:67]
	v_mfma_f32_16x16x32_bf16 v[64:67], v[28:31], v[240:243], v[0:3]
	v_mfma_f32_16x16x32_bf16 v[0:3], v[212:215], v[120:123], v[8:11]
	v_mfma_f32_16x16x32_bf16 v[28:31], v[216:219], v[124:127], v[0:3]
	v_mfma_f32_16x16x32_bf16 v[0:3], v[220:223], v[120:123], v[12:15]
	v_mfma_f32_16x16x32_bf16 v[24:27], v[224:227], v[124:127], v[0:3]
	v_mfma_f32_16x16x32_bf16 v[0:3], v[212:215], v[148:151], v[188:191]
	v_mfma_f32_16x16x32_bf16 v[20:23], v[216:219], v[160:163], v[0:3]
	v_mfma_f32_16x16x32_bf16 v[0:3], v[220:223], v[148:151], v[192:195]
	v_mfma_f32_16x16x32_bf16 v[16:19], v[224:227], v[160:163], v[0:3]
	v_mfma_f32_16x16x32_bf16 v[0:3], v[212:215], v[228:231], v[196:199]
	v_mfma_f32_16x16x32_bf16 v[12:15], v[216:219], v[232:235], v[0:3]
	v_mfma_f32_16x16x32_bf16 v[0:3], v[220:223], v[228:231], v[200:203]
	v_mfma_f32_16x16x32_bf16 v[8:11], v[224:227], v[232:235], v[0:3]
	v_mfma_f32_16x16x32_bf16 v[0:3], v[212:215], v[236:239], v[204:207]
	v_mfma_f32_16x16x32_bf16 v[4:7], v[216:219], v[240:243], v[0:3]
	v_mfma_f32_16x16x32_bf16 v[0:3], v[220:223], v[236:239], v[208:211]
	v_mfma_f32_16x16x32_bf16 v[0:3], v[224:227], v[240:243], v[0:3]
	s_barrier
	s_andn2_b64 vcc, exec, s[18:19]
	s_cbranch_vccnz .LBB0_1139
	s_barrier

.LBB0_1169:
	s_ashr_i32 s19, s18, 31
	s_lshl_b64 s[26:27], s[18:19], 17
	s_add_u32 s26, s40, s26
	s_addc_u32 s27, s41, s27
	s_and_b64 s[28:29], s[4:5], exec
	s_cselect_b32 s39, s27, s37
	s_cselect_b32 s38, s26, s36
	s_ashr_i32 s17, s16, 31
	s_lshl_b64 s[28:29], s[16:17], 16
	s_add_u32 s28, s42, s28
	s_addc_u32 s29, s43, s29
	s_add_u32 s60, s36, 0x10080
	ds_read_b128 v[0:3], v141
	ds_read_b128 v[4:7], v141 offset:1024
	ds_read_b128 v[8:11], v141 offset:2048
	ds_read_b128 v[12:15], v141 offset:3072
	ds_read_b128 v[16:19], v142
	ds_read_b128 v[20:23], v142 offset:1024
	ds_read_b128 v[24:27], v142 offset:2048
	ds_read_b128 v[28:31], v142 offset:3072
	s_addc_u32 s61, s37, 0
	s_add_u32 s36, s38, 0x10000
	s_addc_u32 s37, s39, 0
	s_and_b64 s[62:63], s[4:5], exec
	s_cselect_b32 s34, s28, s34
	s_cselect_b32 s35, s29, s35
	s_add_u32 s62, s34, 0x8000
	s_addc_u32 s63, s35, 0
	s_mov_b32 m0, s55
	v_lshl_add_u64 v[64:65], s[60:61], 0, v[128:129]
	ds_read_b128 v[32:35], v143
	ds_read_b128 v[36:39], v143 offset:1024
	ds_read_b128 v[40:43], v143 offset:2048
	ds_read_b128 v[44:47], v143 offset:3072
	ds_read_b128 v[48:51], v143 offset:4096
	ds_read_b128 v[52:55], v143 offset:5120
	ds_read_b128 v[56:59], v143 offset:6144
	ds_read_b128 v[60:63], v143 offset:7168
	global_load_lds_dwordx4 v[64:65], off
	v_lshl_add_u64 v[64:65], s[60:61], 0, v[132:133]
	s_mov_b32 m0, s56
	s_nop 0
	global_load_lds_dwordx4 v[64:65], off
	s_waitcnt vmcnt(8)
	s_waitcnt lgkmcnt(0)
	s_barrier
	s_waitcnt lgkmcnt(0)
	v_mfma_f32_16x16x32_bf16 v[88:91], v[0:3], v[56:59], 0
	v_mfma_f32_16x16x32_bf16 v[64:67], v[0:3], v[32:35], 0
	v_mfma_f32_16x16x32_bf16 v[68:71], v[8:11], v[32:35], 0
	v_mfma_f32_16x16x32_bf16 v[72:75], v[0:3], v[40:43], 0
	v_mfma_f32_16x16x32_bf16 v[76:79], v[8:11], v[40:43], 0
	v_mfma_f32_16x16x32_bf16 v[80:83], v[0:3], v[48:51], 0
	v_mfma_f32_16x16x32_bf16 v[84:87], v[8:11], v[48:51], 0
	v_mfma_f32_16x16x32_bf16 v[92:95], v[4:7], v[60:63], v[88:91]
	v_mfma_f32_16x16x32_bf16 v[88:91], v[8:11], v[56:59], 0
	v_mfma_f32_16x16x32_bf16 v[64:67], v[4:7], v[36:39], v[64:67]
	v_mfma_f32_16x16x32_bf16 v[68:71], v[12:15], v[36:39], v[68:71]
	v_mfma_f32_16x16x32_bf16 v[72:75], v[4:7], v[44:47], v[72:75]
	v_mfma_f32_16x16x32_bf16 v[76:79], v[12:15], v[44:47], v[76:79]
	v_mfma_f32_16x16x32_bf16 v[80:83], v[4:7], v[52:55], v[80:83]
	v_mfma_f32_16x16x32_bf16 v[84:87], v[12:15], v[52:55], v[84:87]
	v_mfma_f32_16x16x32_bf16 v[100:103], v[12:15], v[60:63], v[88:91]
	v_mfma_f32_16x16x32_bf16 v[88:91], v[16:19], v[32:35], 0
	v_mfma_f32_16x16x32_bf16 v[32:35], v[24:27], v[32:35], 0
	v_mfma_f32_16x16x32_bf16 v[108:111], v[20:23], v[36:39], v[88:91]
	v_mfma_f32_16x16x32_bf16 v[32:35], v[28:31], v[36:39], v[32:35]
	v_mfma_f32_16x16x32_bf16 v[36:39], v[16:19], v[40:43], 0
	v_mfma_f32_16x16x32_bf16 v[40:43], v[24:27], v[40:43], 0
	v_mfma_f32_16x16x32_bf16 v[36:39], v[20:23], v[44:47], v[36:39]
	v_mfma_f32_16x16x32_bf16 v[40:43], v[28:31], v[44:47], v[40:43]
	v_mfma_f32_16x16x32_bf16 v[44:47], v[16:19], v[48:51], 0
	v_mfma_f32_16x16x32_bf16 v[48:51], v[24:27], v[48:51], 0
	v_mfma_f32_16x16x32_bf16 v[116:119], v[28:31], v[52:55], v[48:51]
	v_mfma_f32_16x16x32_bf16 v[48:51], v[16:19], v[56:59], 0
	v_mfma_f32_16x16x32_bf16 v[124:127], v[20:23], v[60:63], v[48:51]
	v_mfma_f32_16x16x32_bf16 v[48:51], v[24:27], v[56:59], 0
	v_mfma_f32_16x16x32_bf16 v[44:47], v[20:23], v[52:55], v[44:47]
	v_mfma_f32_16x16x32_bf16 v[56:59], v[28:31], v[60:63], v[48:51]
	s_barrier
	s_mov_b32 m0, s57
	v_lshl_add_u64 v[152:153], s[34:35], 0, v[130:131]
	s_nop 1
	ds_read_b128 v[48:51], v143 offset:16384
	ds_read_b128 v[52:55], v143 offset:17408
	ds_read_b128 v[60:63], v143 offset:18432
	ds_read_b128 v[88:91], v143 offset:19456
	ds_read_b128 v[96:99], v143 offset:20480
	ds_read_b128 v[104:107], v143 offset:21504
	ds_read_b128 v[112:115], v143 offset:22528
	ds_read_b128 v[120:123], v143 offset:23552
	global_load_lds_dwordx4 v[152:153], off
	v_lshl_add_u64 v[248:249], s[34:35], 0, v[134:135]
	s_add_i32 m0, s57, 0x2000
	s_add_i32 s17, s53, s44
	global_load_lds_dwordx4 v[248:249], off
	v_lshl_add_u64 v[144:145], s[62:63], 0, v[130:131]
	s_mov_b32 m0, s17
	v_lshl_add_u64 v[250:251], s[38:39], 0, v[128:129]
	global_load_lds_dwordx4 v[144:145], off
	v_lshl_add_u64 v[144:145], s[62:63], 0, v[134:135]
	s_add_i32 m0, s17, 0x2000
	v_lshl_add_u64 v[252:253], s[38:39], 0, v[132:133]
	global_load_lds_dwordx4 v[144:145], off
	s_mov_b32 m0, s31
	s_nop 0
	global_load_lds_dwordx4 v[250:251], off
	s_mov_b32 m0, s45
	s_nop 0
	global_load_lds_dwordx4 v[252:253], off
	s_waitcnt vmcnt(8)
	s_waitcnt lgkmcnt(0)
	s_barrier
	s_waitcnt lgkmcnt(0)
	v_mfma_f32_16x16x32_bf16 v[144:147], v[0:3], v[48:51], 0
	v_mfma_f32_16x16x32_bf16 v[156:159], v[0:3], v[60:63], 0
	v_mfma_f32_16x16x32_bf16 v[164:167], v[0:3], v[96:99], 0
	v_mfma_f32_16x16x32_bf16 v[0:3], v[0:3], v[112:115], 0
	v_mfma_f32_16x16x32_bf16 v[172:175], v[4:7], v[120:123], v[0:3]
	v_mfma_f32_16x16x32_bf16 v[0:3], v[8:11], v[112:115], 0
	v_mfma_f32_16x16x32_bf16 v[148:151], v[8:11], v[48:51], 0
	v_mfma_f32_16x16x32_bf16 v[160:163], v[8:11], v[60:63], 0
	v_mfma_f32_16x16x32_bf16 v[168:171], v[8:11], v[96:99], 0
	v_mfma_f32_16x16x32_bf16 v[8:11], v[12:15], v[120:123], v[0:3]
	v_mfma_f32_16x16x32_bf16 v[144:147], v[4:7], v[52:55], v[144:147]
	v_mfma_f32_16x16x32_bf16 v[148:151], v[12:15], v[52:55], v[148:151]
	v_mfma_f32_16x16x32_bf16 v[156:159], v[4:7], v[88:91], v[156:159]
	v_mfma_f32_16x16x32_bf16 v[160:163], v[12:15], v[88:91], v[160:163]
	v_mfma_f32_16x16x32_bf16 v[164:167], v[4:7], v[104:107], v[164:167]
	v_mfma_f32_16x16x32_bf16 v[168:171], v[12:15], v[104:107], v[168:171]
	v_mfma_f32_16x16x32_bf16 v[0:3], v[16:19], v[48:51], 0
	v_mfma_f32_16x16x32_bf16 v[12:15], v[20:23], v[52:55], v[0:3]
	v_mfma_f32_16x16x32_bf16 v[0:3], v[24:27], v[48:51], 0
	v_mfma_f32_16x16x32_bf16 v[176:179], v[28:31], v[52:55], v[0:3]
	v_mfma_f32_16x16x32_bf16 v[0:3], v[16:19], v[60:63], 0
	v_mfma_f32_16x16x32_bf16 v[180:183], v[20:23], v[88:91], v[0:3]
	v_mfma_f32_16x16x32_bf16 v[0:3], v[24:27], v[60:63], 0
	v_mfma_f32_16x16x32_bf16 v[184:187], v[28:31], v[88:91], v[0:3]
	v_mfma_f32_16x16x32_bf16 v[0:3], v[16:19], v[96:99], 0
	v_mfma_f32_16x16x32_bf16 v[188:191], v[20:23], v[104:107], v[0:3]
	v_mfma_f32_16x16x32_bf16 v[0:3], v[24:27], v[96:99], 0
	v_mfma_f32_16x16x32_bf16 v[192:195], v[28:31], v[104:107], v[0:3]
	v_mfma_f32_16x16x32_bf16 v[0:3], v[16:19], v[112:115], 0
	v_mfma_f32_16x16x32_bf16 v[196:199], v[20:23], v[120:123], v[0:3]
	v_mfma_f32_16x16x32_bf16 v[0:3], v[24:27], v[112:115], 0
	v_mfma_f32_16x16x32_bf16 v[200:203], v[28:31], v[120:123], v[0:3]
	s_barrier
	s_add_i32 s17, 0, 0x18000
	s_nop 3
	v_add_u32_e32 v0, s17, v140
	s_add_i32 s19, 0, 0x1c000
	ds_read_b128 v[24:27], v0
	ds_read_b128 v[28:31], v0 offset:1024
	ds_read_b128 v[60:63], v0 offset:2048
	ds_read_b128 v[204:207], v0 offset:3072
	v_add_u32_e32 v0, s19, v140
	ds_read_b128 v[208:211], v0
	ds_read_b128 v[212:215], v0 offset:1024
	ds_read_b128 v[216:219], v0 offset:2048
	ds_read_b128 v[220:223], v0 offset:3072
	s_mov_b32 m0, s46
	v_lshl_add_u64 v[48:49], s[36:37], 0, v[128:129]
	ds_read_b128 v[0:3], v143 offset:32768
	ds_read_b128 v[4:7], v143 offset:33792
	ds_read_b128 v[16:19], v143 offset:34816
	ds_read_b128 v[20:23], v143 offset:35840
	ds_read_b128 v[224:227], v143 offset:36864
	ds_read_b128 v[228:231], v143 offset:37888
	ds_read_b128 v[232:235], v143 offset:38912
	ds_read_b128 v[236:239], v143 offset:39936
	global_load_lds_dwordx4 v[48:49], off
	v_lshl_add_u64 v[48:49], s[36:37], 0, v[132:133]
	s_mov_b32 m0, s47
	s_nop 0
	global_load_lds_dwordx4 v[48:49], off
	s_waitcnt vmcnt(8)
	s_waitcnt lgkmcnt(0)
	s_barrier
	s_waitcnt lgkmcnt(0)
	v_mfma_f32_16x16x32_bf16 v[48:51], v[24:27], v[0:3], v[64:67]
	v_mfma_f32_16x16x32_bf16 v[120:123], v[28:31], v[4:7], v[48:51]
	v_mfma_f32_16x16x32_bf16 v[48:51], v[60:63], v[0:3], v[68:71]
	v_mfma_f32_16x16x32_bf16 v[112:115], v[204:207], v[4:7], v[48:51]
	v_mfma_f32_16x16x32_bf16 v[48:51], v[24:27], v[16:19], v[72:75]
	v_mfma_f32_16x16x32_bf16 v[104:107], v[28:31], v[20:23], v[48:51]
	v_mfma_f32_16x16x32_bf16 v[48:51], v[60:63], v[16:19], v[76:79]
	v_mfma_f32_16x16x32_bf16 v[96:99], v[204:207], v[20:23], v[48:51]
	v_mfma_f32_16x16x32_bf16 v[48:51], v[24:27], v[224:227], v[80:83]
	v_mfma_f32_16x16x32_bf16 v[88:91], v[28:31], v[228:231], v[48:51]
	v_mfma_f32_16x16x32_bf16 v[48:51], v[60:63], v[224:227], v[84:87]
	v_mfma_f32_16x16x32_bf16 v[80:83], v[204:207], v[228:231], v[48:51]
	v_mfma_f32_16x16x32_bf16 v[48:51], v[24:27], v[232:235], v[92:95]
	v_mfma_f32_16x16x32_bf16 v[72:75], v[28:31], v[236:239], v[48:51]
	v_mfma_f32_16x16x32_bf16 v[48:51], v[60:63], v[232:235], v[100:103]
	v_mfma_f32_16x16x32_bf16 v[64:67], v[204:207], v[236:239], v[48:51]
	v_mfma_f32_16x16x32_bf16 v[48:51], v[208:211], v[0:3], v[108:111]
	v_mfma_f32_16x16x32_bf16 v[0:3], v[216:219], v[0:3], v[32:35]
	v_mfma_f32_16x16x32_bf16 v[52:55], v[212:215], v[4:7], v[48:51]
	v_mfma_f32_16x16x32_bf16 v[48:51], v[220:223], v[4:7], v[0:3]
	v_mfma_f32_16x16x32_bf16 v[0:3], v[208:211], v[16:19], v[36:39]
	v_mfma_f32_16x16x32_bf16 v[36:39], v[212:215], v[20:23], v[0:3]
	v_mfma_f32_16x16x32_bf16 v[0:3], v[216:219], v[16:19], v[40:43]
	v_mfma_f32_16x16x32_bf16 v[32:35], v[220:223], v[20:23], v[0:3]
	v_mfma_f32_16x16x32_bf16 v[0:3], v[208:211], v[224:227], v[44:47]
	v_mfma_f32_16x16x32_bf16 v[20:23], v[212:215], v[228:231], v[0:3]
	v_mfma_f32_16x16x32_bf16 v[0:3], v[216:219], v[224:227], v[116:119]
	v_mfma_f32_16x16x32_bf16 v[16:19], v[220:223], v[228:231], v[0:3]
	v_mfma_f32_16x16x32_bf16 v[0:3], v[208:211], v[232:235], v[124:127]
	v_mfma_f32_16x16x32_bf16 v[4:7], v[212:215], v[236:239], v[0:3]
	v_mfma_f32_16x16x32_bf16 v[0:3], v[216:219], v[232:235], v[56:59]
	v_mfma_f32_16x16x32_bf16 v[0:3], v[220:223], v[236:239], v[0:3]
	s_barrier
	s_add_i32 s17, s17, s44
	v_lshl_add_u64 v[56:57], v[152:153], 0, s[8:9]
	s_mov_b32 m0, s17
	ds_read_b128 v[40:43], v143 offset:49152
	ds_read_b128 v[44:47], v143 offset:50176
	ds_read_b128 v[224:227], v143 offset:51200
	ds_read_b128 v[228:231], v143 offset:52224
	ds_read_b128 v[232:235], v143 offset:53248
	ds_read_b128 v[236:239], v143 offset:54272
	ds_read_b128 v[240:243], v143 offset:55296
	ds_read_b128 v[244:247], v143 offset:56320
	global_load_lds_dwordx4 v[56:57], off
	s_add_i32 m0, s17, 0x2000
	s_add_u32 s34, s34, 0x8080
	v_lshl_add_u64 v[56:57], v[248:249], 0, s[8:9]
	s_addc_u32 s35, s35, 0
	s_add_i32 s17, s19, s44
	global_load_lds_dwordx4 v[56:57], off
	v_lshl_add_u64 v[56:57], s[34:35], 0, v[130:131]
	s_mov_b32 m0, s17
	s_nop 0
	global_load_lds_dwordx4 v[56:57], off
	v_lshl_add_u64 v[56:57], s[34:35], 0, v[134:135]
	s_add_i32 m0, s17, 0x2000
	s_nop 0
	global_load_lds_dwordx4 v[56:57], off
	v_lshl_add_u64 v[56:57], v[250:251], 0, s[8:9]
	s_mov_b32 m0, s49
	s_nop 0
	global_load_lds_dwordx4 v[56:57], off
	v_lshl_add_u64 v[56:57], v[252:253], 0, s[8:9]
	s_mov_b32 m0, s50
	s_nop 0
	global_load_lds_dwordx4 v[56:57], off
	s_waitcnt vmcnt(8)
	s_waitcnt lgkmcnt(0)
	s_barrier
	s_waitcnt lgkmcnt(0)
	v_mfma_f32_16x16x32_bf16 v[56:59], v[24:27], v[40:43], v[144:147]
	v_mfma_f32_16x16x32_bf16 v[124:127], v[28:31], v[44:47], v[56:59]
	v_mfma_f32_16x16x32_bf16 v[56:59], v[60:63], v[40:43], v[148:151]
	v_mfma_f32_16x16x32_bf16 v[116:119], v[204:207], v[44:47], v[56:59]
	v_mfma_f32_16x16x32_bf16 v[56:59], v[24:27], v[224:227], v[156:159]
	v_mfma_f32_16x16x32_bf16 v[108:111], v[28:31], v[228:231], v[56:59]
	v_mfma_f32_16x16x32_bf16 v[56:59], v[60:63], v[224:227], v[160:163]
	v_mfma_f32_16x16x32_bf16 v[100:103], v[204:207], v[228:231], v[56:59]
	v_mfma_f32_16x16x32_bf16 v[56:59], v[24:27], v[232:235], v[164:167]
	v_mfma_f32_16x16x32_bf16 v[92:95], v[28:31], v[236:239], v[56:59]
	v_mfma_f32_16x16x32_bf16 v[56:59], v[60:63], v[232:235], v[168:171]
	v_mfma_f32_16x16x32_bf16 v[24:27], v[24:27], v[240:243], v[172:175]
	v_mfma_f32_16x16x32_bf16 v[8:11], v[60:63], v[240:243], v[8:11]
	v_mfma_f32_16x16x32_bf16 v[84:87], v[204:207], v[236:239], v[56:59]
	v_mfma_f32_16x16x32_bf16 v[76:79], v[28:31], v[244:247], v[24:27]
	v_mfma_f32_16x16x32_bf16 v[68:71], v[204:207], v[244:247], v[8:11]
	v_mfma_f32_16x16x32_bf16 v[8:11], v[208:211], v[40:43], v[12:15]
	v_mfma_f32_16x16x32_bf16 v[60:63], v[212:215], v[44:47], v[8:11]
	v_mfma_f32_16x16x32_bf16 v[8:11], v[216:219], v[40:43], v[176:179]
	v_mfma_f32_16x16x32_bf16 v[56:59], v[220:223], v[44:47], v[8:11]
	v_mfma_f32_16x16x32_bf16 v[8:11], v[208:211], v[224:227], v[180:183]
	v_mfma_f32_16x16x32_bf16 v[44:47], v[212:215], v[228:231], v[8:11]
	v_mfma_f32_16x16x32_bf16 v[8:11], v[216:219], v[224:227], v[184:187]
	v_mfma_f32_16x16x32_bf16 v[40:43], v[220:223], v[228:231], v[8:11]
	v_mfma_f32_16x16x32_bf16 v[8:11], v[208:211], v[232:235], v[188:191]
	v_mfma_f32_16x16x32_bf16 v[28:31], v[212:215], v[236:239], v[8:11]
	v_mfma_f32_16x16x32_bf16 v[8:11], v[216:219], v[232:235], v[192:195]
	v_mfma_f32_16x16x32_bf16 v[24:27], v[220:223], v[236:239], v[8:11]
	v_mfma_f32_16x16x32_bf16 v[8:11], v[208:211], v[240:243], v[196:199]
	v_mfma_f32_16x16x32_bf16 v[12:15], v[212:215], v[244:247], v[8:11]
	v_mfma_f32_16x16x32_bf16 v[8:11], v[216:219], v[240:243], v[200:203]
	v_mfma_f32_16x16x32_bf16 v[8:11], v[220:223], v[244:247], v[8:11]
	s_barrier
	s_andn2_b64 vcc, exec, s[10:11]
	s_cbranch_vccnz .LBB0_1171
	s_barrier

.LBB0_1399:
	s_mov_b64 s[6:7], s[0:1]
	s_getreg_b32 s3, hwreg(HW_REG_XCC_ID, 0, 4)
	s_setprio 0
	s_waitcnt vmcnt(0)
	s_barrier
	s_and_saveexec_b64 s[4:5], s[20:21]
	s_cbranch_execz .LBB0_1451
	s_add_i32 s8, 0, 0x23fc0
	s_waitcnt vmcnt(7)
	v_mov_b32_e32 v0, s8
	s_load_dwordx2 s[6:7], s[6:7], 0x138
	s_waitcnt vmcnt(0) expcnt(0) lgkmcnt(0)
	ds_read_b32 v2, v0
	s_add_i32 s8, 0, 0x23fc4
	v_mov_b32_e32 v0, s8
	ds_read_b32 v0, v0
	s_and_b32 s3, s3, 15
	s_waitcnt lgkmcnt(1)
	v_cmp_ne_u32_e32 vcc, 0, v2
	s_cbranch_vccnz .LBB0_1415
	s_load_dword s8, s[22:23], 0x14
	s_mov_b32 s56, 1
	v_mov_b32_e32 v16, 0
	s_waitcnt lgkmcnt(0)
	s_lshr_b32 s10, s8, 16
	s_and_b32 s8, s8, 0xffff
	s_cmp_lg_u32 s8, 0
	s_cselect_b64 s[8:9], -1, 0
	s_cmp_lg_u64 s[8:9], 0
	s_addc_u32 s8, s24, 0
	s_cmp_lg_u32 s10, 0
	s_mul_i32 s57, s8, s33
	s_cselect_b64 s[8:9], -1, 0
	s_cmp_lg_u64 s[8:9], 0
	s_addc_u32 s8, s25, 0
	s_mul_i32 s57, s57, s8
	s_add_u32 s8, s6, 0x4200
	s_addc_u32 s9, s7, 0
	s_add_u32 s10, s6, 0x4400
	s_addc_u32 s11, s7, 0
	s_add_u32 s12, s6, 0x4500
	s_addc_u32 s13, s7, 0
	s_add_u32 s14, s6, 0x4600
	s_addc_u32 s15, s7, 0
	s_add_u32 s16, s6, 0x4700
	s_addc_u32 s17, s7, 0
	s_add_u32 s18, s6, 0x4800
	s_addc_u32 s19, s7, 0
	s_add_u32 s26, s6, 0x4900
	s_addc_u32 s27, s7, 0
	s_add_u32 s28, s6, 0x4a00
	s_addc_u32 s29, s7, 0
	s_add_u32 s30, s6, 0x4b00
	s_addc_u32 s31, s7, 0
	s_add_u32 s34, s6, 0x4c00
	s_addc_u32 s35, s7, 0
	s_add_u32 s36, s6, 0x4d00
	s_addc_u32 s37, s7, 0
	s_add_u32 s38, s6, 0x4e00
	s_addc_u32 s39, s7, 0
	s_add_u32 s40, s6, 0x4f00
	s_addc_u32 s41, s7, 0
	s_add_u32 s42, s6, 0x5000
	s_addc_u32 s43, s7, 0
	s_add_u32 s44, s6, 0x5100
	s_addc_u32 s45, s7, 0
	s_add_u32 s46, s6, 0x5200
	s_addc_u32 s47, s7, 0
	s_add_u32 s48, s6, 0x5300
	s_addc_u32 s49, s7, 0
	s_branch .LBB0_1403

.Lprio_skip_14:
	s_load_dwordx2 s[4:5], s[4:5], 0x138
	s_mov_b32 s3, s33
	s_mov_b32 s36, s2
	s_waitcnt vmcnt(2)
	v_mov_b32_e32 v8, v154
	s_cmpk_lt_i32 s36, 0x100
	s_cselect_b64 s[6:7], -1, 0
	s_cmpk_gt_i32 s36, 0xff
	v_readfirstlane_b32 s16, v8
	s_cbranch_scc1 .LBB0_1514
	s_ashr_i32 s8, s36, 31
	s_lshr_b32 s8, s8, 29
	s_add_i32 s12, s36, s8
	s_and_b32 s8, s12, -8
	s_sub_i32 s10, s36, s8
	s_cmp_gt_i32 s10, -1
	s_cbranch_scc0 .LBB0_1511
	s_lshl_b32 s11, s10, 5
	s_ashr_i32 s8, s12, 3
	s_cbranch_execz .LBB0_1512
	s_branch .LBB0_1513

.LBB0_1529:
	ds_read_b128 v[144:147], v149
	ds_read_b128 v[156:159], v149 offset:1024
	ds_read_b128 v[160:163], v149 offset:2048
	ds_read_b128 v[164:167], v149 offset:3072
	ds_read_b128 v[168:171], v150
	ds_read_b128 v[172:175], v150 offset:1024
	ds_read_b128 v[176:179], v150 offset:2048
	ds_read_b128 v[180:183], v150 offset:3072
	s_add_u32 s6, s8, 0x100
	s_addc_u32 s7, s9, 0
	s_cmp_eq_u32 s60, 12
	s_cselect_b32 s35, s27, s7
	s_cselect_b32 s34, s26, s6
	s_cselect_b32 s11, s19, s59
	s_cselect_b32 s10, s57, s58
	v_lshl_add_u64 v[216:217], s[8:9], 0, v[138:139]
	s_add_i32 m0, s31, 0xc000
	ds_read_b128 v[184:187], v151
	ds_read_b128 v[188:191], v151 offset:1024
	ds_read_b128 v[192:195], v151 offset:2048
	ds_read_b128 v[196:199], v151 offset:3072
	ds_read_b128 v[200:203], v151 offset:4096
	ds_read_b128 v[204:207], v151 offset:5120
	ds_read_b128 v[208:211], v151 offset:6144
	ds_read_b128 v[212:215], v151 offset:7168
	global_load_lds_dwordx4 v[216:217], off
	v_lshl_add_u64 v[216:217], s[8:9], 0, v[136:137]
	s_add_i32 m0, s31, 0xe000
	s_nop 0
	global_load_lds_dwordx4 v[216:217], off
	s_waitcnt vmcnt(8)
	s_waitcnt lgkmcnt(0)
	s_barrier
	s_waitcnt lgkmcnt(0)
	v_mfma_f32_16x16x32_bf16 v[124:127], v[144:147], v[184:187], v[124:127]
	v_mfma_f32_16x16x32_bf16 v[120:123], v[160:163], v[184:187], v[120:123]
	v_mfma_f32_16x16x32_bf16 v[108:111], v[144:147], v[192:195], v[108:111]
	v_mfma_f32_16x16x32_bf16 v[104:107], v[160:163], v[192:195], v[104:107]
	v_mfma_f32_16x16x32_bf16 v[92:95], v[144:147], v[200:203], v[92:95]
	v_mfma_f32_16x16x32_bf16 v[88:91], v[160:163], v[200:203], v[88:91]
	v_mfma_f32_16x16x32_bf16 v[76:79], v[144:147], v[208:211], v[76:79]
	v_mfma_f32_16x16x32_bf16 v[72:75], v[160:163], v[208:211], v[72:75]
	v_mfma_f32_16x16x32_bf16 v[124:127], v[156:159], v[188:191], v[124:127]
	v_mfma_f32_16x16x32_bf16 v[120:123], v[164:167], v[188:191], v[120:123]
	v_mfma_f32_16x16x32_bf16 v[108:111], v[156:159], v[196:199], v[108:111]
	v_mfma_f32_16x16x32_bf16 v[104:107], v[164:167], v[196:199], v[104:107]
	v_mfma_f32_16x16x32_bf16 v[92:95], v[156:159], v[204:207], v[92:95]
	v_mfma_f32_16x16x32_bf16 v[88:91], v[164:167], v[204:207], v[88:91]
	v_mfma_f32_16x16x32_bf16 v[76:79], v[156:159], v[212:215], v[76:79]
	v_mfma_f32_16x16x32_bf16 v[72:75], v[164:167], v[212:215], v[72:75]
	v_mfma_f32_16x16x32_bf16 v[116:119], v[168:171], v[184:187], v[116:119]
	v_mfma_f32_16x16x32_bf16 v[112:115], v[176:179], v[184:187], v[112:115]
	v_mfma_f32_16x16x32_bf16 v[100:103], v[168:171], v[192:195], v[100:103]
	v_mfma_f32_16x16x32_bf16 v[96:99], v[176:179], v[192:195], v[96:99]
	v_mfma_f32_16x16x32_bf16 v[84:87], v[168:171], v[200:203], v[84:87]
	v_mfma_f32_16x16x32_bf16 v[80:83], v[176:179], v[200:203], v[80:83]
	v_mfma_f32_16x16x32_bf16 v[68:71], v[168:171], v[208:211], v[68:71]
	v_mfma_f32_16x16x32_bf16 v[64:67], v[176:179], v[208:211], v[64:67]
	v_mfma_f32_16x16x32_bf16 v[116:119], v[172:175], v[188:191], v[116:119]
	v_mfma_f32_16x16x32_bf16 v[112:115], v[180:183], v[188:191], v[112:115]
	v_mfma_f32_16x16x32_bf16 v[100:103], v[172:175], v[196:199], v[100:103]
	v_mfma_f32_16x16x32_bf16 v[96:99], v[180:183], v[196:199], v[96:99]
	v_mfma_f32_16x16x32_bf16 v[84:87], v[172:175], v[204:207], v[84:87]
	v_mfma_f32_16x16x32_bf16 v[80:83], v[180:183], v[204:207], v[80:83]
	v_mfma_f32_16x16x32_bf16 v[68:71], v[172:175], v[212:215], v[68:71]
	v_mfma_f32_16x16x32_bf16 v[64:67], v[180:183], v[212:215], v[64:67]
	s_barrier
	s_add_i32 s8, s53, s41
	v_lshl_add_u64 v[216:217], s[10:11], 0, v[130:131]
	s_mov_b32 m0, s8
	ds_read_b128 v[184:187], v151 offset:16384
	ds_read_b128 v[188:191], v151 offset:17408
	ds_read_b128 v[192:195], v151 offset:18432
	ds_read_b128 v[196:199], v151 offset:19456
	ds_read_b128 v[200:203], v151 offset:20480
	ds_read_b128 v[204:207], v151 offset:21504
	ds_read_b128 v[208:211], v151 offset:22528
	ds_read_b128 v[212:215], v151 offset:23552
	global_load_lds_dwordx4 v[216:217], off
	s_add_i32 m0, s8, 0x2000
	s_add_u32 s8, s10, 0x40000
	v_lshl_add_u64 v[218:219], s[10:11], 0, v[134:135]
	s_addc_u32 s9, s11, 0
	s_add_i32 s61, s54, s41
	global_load_lds_dwordx4 v[218:219], off
	v_lshl_add_u64 v[220:221], s[8:9], 0, v[130:131]
	s_mov_b32 m0, s61
	v_lshl_add_u64 v[222:223], s[34:35], 0, v[132:133]
	global_load_lds_dwordx4 v[220:221], off
	v_lshl_add_u64 v[220:221], s[8:9], 0, v[134:135]
	s_add_i32 m0, s61, 0x2000
	s_nop 0
	global_load_lds_dwordx4 v[220:221], off
	v_lshl_add_u64 v[220:221], s[34:35], 0, v[128:129]
	s_mov_b32 m0, s31
	s_nop 0
	global_load_lds_dwordx4 v[220:221], off
	s_mov_b32 m0, s42
	s_nop 0
	global_load_lds_dwordx4 v[222:223], off
	s_waitcnt vmcnt(8)
	s_waitcnt lgkmcnt(0)
	s_barrier
	s_waitcnt lgkmcnt(0)
	v_mfma_f32_16x16x32_bf16 v[60:63], v[144:147], v[184:187], v[60:63]
	v_mfma_f32_16x16x32_bf16 v[56:59], v[160:163], v[184:187], v[56:59]
	v_mfma_f32_16x16x32_bf16 v[44:47], v[144:147], v[192:195], v[44:47]
	v_mfma_f32_16x16x32_bf16 v[40:43], v[160:163], v[192:195], v[40:43]
	v_mfma_f32_16x16x32_bf16 v[28:31], v[144:147], v[200:203], v[28:31]
	v_mfma_f32_16x16x32_bf16 v[24:27], v[160:163], v[200:203], v[24:27]
	v_mfma_f32_16x16x32_bf16 v[12:15], v[144:147], v[208:211], v[12:15]
	v_mfma_f32_16x16x32_bf16 v[8:11], v[160:163], v[208:211], v[8:11]
	v_mfma_f32_16x16x32_bf16 v[60:63], v[156:159], v[188:191], v[60:63]
	v_mfma_f32_16x16x32_bf16 v[56:59], v[164:167], v[188:191], v[56:59]
	v_mfma_f32_16x16x32_bf16 v[44:47], v[156:159], v[196:199], v[44:47]
	v_mfma_f32_16x16x32_bf16 v[40:43], v[164:167], v[196:199], v[40:43]
	v_mfma_f32_16x16x32_bf16 v[28:31], v[156:159], v[204:207], v[28:31]
	v_mfma_f32_16x16x32_bf16 v[24:27], v[164:167], v[204:207], v[24:27]
	v_mfma_f32_16x16x32_bf16 v[12:15], v[156:159], v[212:215], v[12:15]
	v_mfma_f32_16x16x32_bf16 v[8:11], v[164:167], v[212:215], v[8:11]
	v_mfma_f32_16x16x32_bf16 v[52:55], v[168:171], v[184:187], v[52:55]
	v_mfma_f32_16x16x32_bf16 v[48:51], v[176:179], v[184:187], v[48:51]
	v_mfma_f32_16x16x32_bf16 v[36:39], v[168:171], v[192:195], v[36:39]
	v_mfma_f32_16x16x32_bf16 v[32:35], v[176:179], v[192:195], v[32:35]
	v_mfma_f32_16x16x32_bf16 v[20:23], v[168:171], v[200:203], v[20:23]
	v_mfma_f32_16x16x32_bf16 v[16:19], v[176:179], v[200:203], v[16:19]
	v_mfma_f32_16x16x32_bf16 v[4:7], v[168:171], v[208:211], v[4:7]
	v_mfma_f32_16x16x32_bf16 v[0:3], v[176:179], v[208:211], v[0:3]
	v_mfma_f32_16x16x32_bf16 v[52:55], v[172:175], v[188:191], v[52:55]
	v_mfma_f32_16x16x32_bf16 v[48:51], v[180:183], v[188:191], v[48:51]
	v_mfma_f32_16x16x32_bf16 v[36:39], v[172:175], v[196:199], v[36:39]
	v_mfma_f32_16x16x32_bf16 v[32:35], v[180:183], v[196:199], v[32:35]
	v_mfma_f32_16x16x32_bf16 v[20:23], v[172:175], v[204:207], v[20:23]
	v_mfma_f32_16x16x32_bf16 v[16:19], v[180:183], v[204:207], v[16:19]
	v_mfma_f32_16x16x32_bf16 v[4:7], v[172:175], v[212:215], v[4:7]
	v_mfma_f32_16x16x32_bf16 v[0:3], v[180:183], v[212:215], v[0:3]
	s_barrier
	s_add_i32 s61, 0, 0x18000
	v_add_u32_e32 v153, s61, v148
	s_add_i32 s62, 0, 0x1c000
	ds_read_b128 v[144:147], v153
	ds_read_b128 v[156:159], v153 offset:1024
	ds_read_b128 v[160:163], v153 offset:2048
	ds_read_b128 v[164:167], v153 offset:3072
	v_add_u32_e32 v153, s62, v148
	ds_read_b128 v[168:171], v153
	ds_read_b128 v[172:175], v153 offset:1024
	ds_read_b128 v[176:179], v153 offset:2048
	ds_read_b128 v[180:183], v153 offset:3072
	s_add_u32 s8, s34, 0xf0000
	s_addc_u32 s9, s35, 0
	s_mov_b32 m0, s43
	v_lshl_add_u64 v[224:225], s[8:9], 0, v[128:129]
	ds_read_b128 v[184:187], v151 offset:32768
	ds_read_b128 v[188:191], v151 offset:33792
	ds_read_b128 v[192:195], v151 offset:34816
	ds_read_b128 v[196:199], v151 offset:35840
	ds_read_b128 v[200:203], v151 offset:36864
	ds_read_b128 v[204:207], v151 offset:37888
	ds_read_b128 v[208:211], v151 offset:38912
	ds_read_b128 v[212:215], v151 offset:39936
	global_load_lds_dwordx4 v[224:225], off
	v_lshl_add_u64 v[224:225], s[8:9], 0, v[132:133]
	s_mov_b32 m0, s44
	s_nop 0
	global_load_lds_dwordx4 v[224:225], off
	s_waitcnt vmcnt(8)
	s_waitcnt lgkmcnt(0)
	s_barrier
	s_waitcnt lgkmcnt(0)
	v_mfma_f32_16x16x32_bf16 v[124:127], v[144:147], v[184:187], v[124:127]
	v_mfma_f32_16x16x32_bf16 v[120:123], v[160:163], v[184:187], v[120:123]
	v_mfma_f32_16x16x32_bf16 v[108:111], v[144:147], v[192:195], v[108:111]
	v_mfma_f32_16x16x32_bf16 v[104:107], v[160:163], v[192:195], v[104:107]
	v_mfma_f32_16x16x32_bf16 v[92:95], v[144:147], v[200:203], v[92:95]
	v_mfma_f32_16x16x32_bf16 v[88:91], v[160:163], v[200:203], v[88:91]
	v_mfma_f32_16x16x32_bf16 v[76:79], v[144:147], v[208:211], v[76:79]
	v_mfma_f32_16x16x32_bf16 v[72:75], v[160:163], v[208:211], v[72:75]
	v_mfma_f32_16x16x32_bf16 v[124:127], v[156:159], v[188:191], v[124:127]
	v_mfma_f32_16x16x32_bf16 v[120:123], v[164:167], v[188:191], v[120:123]
	v_mfma_f32_16x16x32_bf16 v[108:111], v[156:159], v[196:199], v[108:111]
	v_mfma_f32_16x16x32_bf16 v[104:107], v[164:167], v[196:199], v[104:107]
	v_mfma_f32_16x16x32_bf16 v[92:95], v[156:159], v[204:207], v[92:95]
	v_mfma_f32_16x16x32_bf16 v[88:91], v[164:167], v[204:207], v[88:91]
	v_mfma_f32_16x16x32_bf16 v[76:79], v[156:159], v[212:215], v[76:79]
	v_mfma_f32_16x16x32_bf16 v[72:75], v[164:167], v[212:215], v[72:75]
	v_mfma_f32_16x16x32_bf16 v[116:119], v[168:171], v[184:187], v[116:119]
	v_mfma_f32_16x16x32_bf16 v[112:115], v[176:179], v[184:187], v[112:115]
	v_mfma_f32_16x16x32_bf16 v[100:103], v[168:171], v[192:195], v[100:103]
	v_mfma_f32_16x16x32_bf16 v[96:99], v[176:179], v[192:195], v[96:99]
	v_mfma_f32_16x16x32_bf16 v[84:87], v[168:171], v[200:203], v[84:87]
	v_mfma_f32_16x16x32_bf16 v[80:83], v[176:179], v[200:203], v[80:83]
	v_mfma_f32_16x16x32_bf16 v[68:71], v[168:171], v[208:211], v[68:71]
	v_mfma_f32_16x16x32_bf16 v[64:67], v[176:179], v[208:211], v[64:67]
	v_mfma_f32_16x16x32_bf16 v[116:119], v[172:175], v[188:191], v[116:119]
	v_mfma_f32_16x16x32_bf16 v[112:115], v[180:183], v[188:191], v[112:115]
	v_mfma_f32_16x16x32_bf16 v[100:103], v[172:175], v[196:199], v[100:103]
	v_mfma_f32_16x16x32_bf16 v[96:99], v[180:183], v[196:199], v[96:99]
	v_mfma_f32_16x16x32_bf16 v[84:87], v[172:175], v[204:207], v[84:87]
	v_mfma_f32_16x16x32_bf16 v[80:83], v[180:183], v[204:207], v[80:83]
	v_mfma_f32_16x16x32_bf16 v[68:71], v[172:175], v[212:215], v[68:71]
	v_mfma_f32_16x16x32_bf16 v[64:67], v[180:183], v[212:215], v[64:67]
	s_barrier
	s_add_i32 s8, s61, s41
	v_lshl_add_u64 v[216:217], v[216:217], 0, s[14:15]
	s_mov_b32 m0, s8
	ds_read_b128 v[184:187], v151 offset:49152
	ds_read_b128 v[188:191], v151 offset:50176
	ds_read_b128 v[192:195], v151 offset:51200
	ds_read_b128 v[196:199], v151 offset:52224
	ds_read_b128 v[200:203], v151 offset:53248
	ds_read_b128 v[204:207], v151 offset:54272
	ds_read_b128 v[208:211], v151 offset:55296
	ds_read_b128 v[212:215], v151 offset:56320
	global_load_lds_dwordx4 v[216:217], off
	s_add_i32 m0, s8, 0x2000
	s_add_u32 s8, s10, 0x40080
	v_lshl_add_u64 v[216:217], v[218:219], 0, s[14:15]
	s_addc_u32 s9, s11, 0
	s_add_i32 s10, s62, s41
	global_load_lds_dwordx4 v[216:217], off
	v_lshl_add_u64 v[216:217], s[8:9], 0, v[130:131]
	s_mov_b32 m0, s10
	s_nop 0
	global_load_lds_dwordx4 v[216:217], off
	v_lshl_add_u64 v[216:217], s[8:9], 0, v[134:135]
	s_add_i32 m0, s10, 0x2000
	s_nop 0
	global_load_lds_dwordx4 v[216:217], off
	v_lshl_add_u64 v[216:217], v[220:221], 0, s[14:15]
	s_mov_b32 m0, s49
	s_nop 0
	global_load_lds_dwordx4 v[216:217], off
	v_lshl_add_u64 v[216:217], v[222:223], 0, s[14:15]
	s_mov_b32 m0, s50
	s_nop 0
	global_load_lds_dwordx4 v[216:217], off
	s_waitcnt vmcnt(8)
	s_waitcnt lgkmcnt(0)
	s_barrier
	s_waitcnt lgkmcnt(0)
	v_mfma_f32_16x16x32_bf16 v[60:63], v[144:147], v[184:187], v[60:63]
	v_mfma_f32_16x16x32_bf16 v[56:59], v[160:163], v[184:187], v[56:59]
	v_mfma_f32_16x16x32_bf16 v[44:47], v[144:147], v[192:195], v[44:47]
	v_mfma_f32_16x16x32_bf16 v[40:43], v[160:163], v[192:195], v[40:43]
	v_mfma_f32_16x16x32_bf16 v[28:31], v[144:147], v[200:203], v[28:31]
	v_mfma_f32_16x16x32_bf16 v[24:27], v[160:163], v[200:203], v[24:27]
	v_mfma_f32_16x16x32_bf16 v[12:15], v[144:147], v[208:211], v[12:15]
	v_mfma_f32_16x16x32_bf16 v[8:11], v[160:163], v[208:211], v[8:11]
	v_mfma_f32_16x16x32_bf16 v[60:63], v[156:159], v[188:191], v[60:63]
	v_mfma_f32_16x16x32_bf16 v[56:59], v[164:167], v[188:191], v[56:59]
	v_mfma_f32_16x16x32_bf16 v[44:47], v[156:159], v[196:199], v[44:47]
	v_mfma_f32_16x16x32_bf16 v[40:43], v[164:167], v[196:199], v[40:43]
	v_mfma_f32_16x16x32_bf16 v[28:31], v[156:159], v[204:207], v[28:31]
	v_mfma_f32_16x16x32_bf16 v[24:27], v[164:167], v[204:207], v[24:27]
	v_mfma_f32_16x16x32_bf16 v[12:15], v[156:159], v[212:215], v[12:15]
	v_mfma_f32_16x16x32_bf16 v[8:11], v[164:167], v[212:215], v[8:11]
	v_mfma_f32_16x16x32_bf16 v[52:55], v[168:171], v[184:187], v[52:55]
	v_mfma_f32_16x16x32_bf16 v[48:51], v[176:179], v[184:187], v[48:51]
	v_mfma_f32_16x16x32_bf16 v[36:39], v[168:171], v[192:195], v[36:39]
	v_mfma_f32_16x16x32_bf16 v[32:35], v[176:179], v[192:195], v[32:35]
	v_mfma_f32_16x16x32_bf16 v[20:23], v[168:171], v[200:203], v[20:23]
	v_mfma_f32_16x16x32_bf16 v[16:19], v[176:179], v[200:203], v[16:19]
	v_mfma_f32_16x16x32_bf16 v[4:7], v[168:171], v[208:211], v[4:7]
	v_mfma_f32_16x16x32_bf16 v[0:3], v[176:179], v[208:211], v[0:3]
	v_mfma_f32_16x16x32_bf16 v[52:55], v[172:175], v[188:191], v[52:55]
	v_mfma_f32_16x16x32_bf16 v[48:51], v[180:183], v[188:191], v[48:51]
	v_mfma_f32_16x16x32_bf16 v[36:39], v[172:175], v[196:199], v[36:39]
	v_mfma_f32_16x16x32_bf16 v[32:35], v[180:183], v[196:199], v[32:35]
	v_mfma_f32_16x16x32_bf16 v[20:23], v[172:175], v[204:207], v[20:23]
	v_mfma_f32_16x16x32_bf16 v[16:19], v[180:183], v[204:207], v[16:19]
	v_mfma_f32_16x16x32_bf16 v[4:7], v[172:175], v[212:215], v[4:7]
	v_mfma_f32_16x16x32_bf16 v[0:3], v[180:183], v[212:215], v[0:3]
	s_barrier
	s_add_i32 s60, s60, 2
	s_add_u32 s58, s58, 0x100
	s_addc_u32 s59, s59, 0
	s_cmp_gt_u32 s60, 13
	s_mov_b64 s[8:9], s[6:7]
	s_cbranch_scc0 .LBB0_1529
	s_and_b64 vcc, exec, s[16:17]
	s_cbranch_vccz .LBB0_1532
	s_barrier

.Lprio_skip_15:
	s_cmpk_gt_i32 s38, 0x57f
	v_readfirstlane_b32 s10, v8
	s_cbranch_scc1 .LBB0_1620
	v_lshlrev_b32_e32 v0, 4, v8
	v_add_u32_e32 v1, 0x2000, v0
	v_ashrrev_i32_e32 v2, 31, v1
	v_lshrrev_b32_e32 v2, 22, v2
	v_add_u32_e32 v2, v1, v2
	v_ashrrev_i32_e32 v9, 10, v2
	v_mul_i32_i24_e32 v2, 0x400, v9
	v_sub_u32_e32 v1, v1, v2
	v_lshrrev_b32_e32 v2, 4, v1
	v_bitop3_b32 v1, v2, v1, 32 bitop3:0x6c
	v_ashrrev_i32_e32 v2, 31, v1
	v_lshrrev_b32_e32 v2, 26, v2
	v_add_u32_e32 v2, v1, v2
	v_lshlrev_b32_e32 v3, 3, v9
	v_ashrrev_i32_e32 v10, 6, v2
	v_and_b32_e32 v3, -16, v3
	v_add_u32_e32 v3, v10, v3
	s_load_dwordx2 s[8:9], s[4:5], 0x130
	s_load_dwordx2 s[12:13], s[6:7], 0x138
	v_and_b32_e32 v4, 3, v10
	s_mov_b32 s4, 0x1fffe0
	v_lshrrev_b32_e32 v5, 2, v3
	v_lshlrev_b32_e32 v6, 1, v3
	v_and_b32_e32 v2, 0xc0, v2
	v_and_or_b32 v4, v3, s4, v4
	v_and_b32_e32 v5, 4, v5
	v_and_b32_e32 v6, 24, v6
	v_sub_u32_e32 v1, v1, v2
	v_mov_b32_e32 v2, 1
	v_or3_b32 v4, v4, v5, v6
	v_lshlrev_b32_e32 v5, 5, v9
	v_ashrrev_i16_sdwa v1, v2, sext(v1) dst_sel:DWORD dst_unused:UNUSED_PAD src0_sel:DWORD src1_sel:BYTE_0
	v_and_b32_e32 v5, 32, v5
	v_bfe_i32 v11, v1, 0, 16
	v_add_lshl_u32 v1, v5, v11, 1
	v_lshl_add_u32 v128, v4, 11, v1
	v_lshl_add_u32 v130, v3, 11, v1
	v_bfe_i32 v1, v8, 27, 1
	v_lshrrev_b32_e32 v1, 22, v1
	v_add_u32_e32 v1, v0, v1
	v_and_b32_e32 v1, 0xfffffc00, v1
	v_sub_u32_e32 v0, v0, v1
	v_lshrrev_b32_e32 v1, 4, v0
	v_ashrrev_i32_e32 v3, 31, v8
	v_bitop3_b32 v0, v1, v0, 32 bitop3:0x6c
	v_lshrrev_b32_e32 v3, 26, v3
	v_ashrrev_i32_e32 v1, 31, v0
	v_add_u32_e32 v3, v8, v3
	s_waitcnt lgkmcnt(0)
	s_add_u32 s39, s8, 0x2000000
	v_lshrrev_b32_e32 v1, 26, v1
	v_ashrrev_i32_e32 v13, 6, v3
	s_addc_u32 s40, s9, 0
	v_add_u32_e32 v1, v0, v1
	v_lshlrev_b32_e32 v3, 3, v13
	s_add_u32 s41, s12, 0xa80000
	v_ashrrev_i32_e32 v12, 6, v1
	v_and_b32_e32 v3, -16, v3
	s_addc_u32 s42, s13, 0
	v_add_u32_e32 v3, v12, v3
	v_and_b32_e32 v4, 3, v12
	s_ashr_i32 s44, s38, 31
	v_and_or_b32 v4, v3, s4, v4
	s_lshr_b32 s4, s44, 29
	s_add_i32 s4, s38, s4
	s_ashr_i32 s8, s10, 6
	s_ashr_i32 s6, s4, 3
	s_and_b32 s4, s4, -8
	s_ashr_i32 s5, s10, 8
	s_lshl_b32 s43, s8, 10
	s_sub_i32 s4, s38, s4
	s_cmp_lt_i32 s4, 0
	s_movk_i32 s45, 0xb1
	s_cselect_b32 s7, s45, 0xb0
	s_mul_i32 s4, s7, s4
	s_add_i32 s4, s4, s6
	s_mul_hi_i32 s6, s4, 0x2e8ba2e9
	s_lshr_b32 s7, s6, 31
	s_ashr_i32 s6, s6, 5
	s_add_i32 s6, s6, s7
	s_lshl_b32 s7, s6, 3
	s_mulk_i32 s6, 0xb0
	s_sub_i32 s6, s4, s6
	s_bfe_u32 s4, s6, 0x3001c
	s_add_i32 s9, s6, s4
	s_sext_i32_i16 s4, s9
	s_and_b32 s9, s9, 0xfff8
	s_sub_i32 s6, s6, s9
	s_sext_i32_i16 s6, s6
	v_lshrrev_b32_e32 v5, 2, v3
	v_lshlrev_b32_e32 v6, 1, v3
	v_and_b32_e32 v1, 0xc0, v1
	s_lshr_b32 s4, s4, 3
	s_add_i32 s30, s7, s6
	v_and_b32_e32 v5, 4, v5
	v_and_b32_e32 v6, 24, v6
	v_sub_u32_e32 v0, v0, v1
	s_ashr_i32 s31, s30, 31
	s_bfe_i64 s[12:13], s[4:5], 0x100000
	v_or3_b32 v4, v4, v5, v6
	v_lshlrev_b32_e32 v5, 5, v13
	v_ashrrev_i16_sdwa v0, v2, sext(v0) dst_sel:DWORD dst_unused:UNUSED_PAD src0_sel:DWORD src1_sel:BYTE_0
	s_lshl_b64 s[6:7], s[30:31], 19
	s_lshl_b64 s[12:13], s[12:13], 19
	v_and_b32_e32 v5, 32, v5
	v_bfe_i32 v14, v0, 0, 16
	s_add_u32 s28, s41, s12
	v_add_lshl_u32 v0, v5, v14, 1
	s_addc_u32 s29, s42, s13
	s_add_i32 s31, s43, 0
	v_lshl_add_u32 v132, v4, 11, v0
	s_add_i32 m0, s31, 0x10000
	v_lshl_add_u32 v134, v3, 11, v0
	global_load_lds_dwordx4 v132, s[28:29]
	s_add_i32 m0, s31, 0x12000
	s_add_u32 s12, s28, 0x40000
	global_load_lds_dwordx4 v128, s[28:29]
	s_addc_u32 s13, s29, 0
	s_add_i32 m0, s31, 0x14000
	v_mov_b32_e32 v133, 0
	global_load_lds_dwordx4 v132, s[12:13]
	s_add_i32 m0, s31, 0x16000
	s_add_u32 s34, s39, s6
	s_addc_u32 s35, s40, s7
	s_add_i32 s46, s31, 0x2000
	global_load_lds_dwordx4 v128, s[12:13]
	s_mov_b32 m0, s31
	s_add_u32 s6, s34, 0x40000
	global_load_lds_dwordx4 v134, s[34:35]
	s_mov_b32 m0, s46
	s_addc_u32 s7, s35, 0
	s_add_i32 s47, s31, 0x4000
	global_load_lds_dwordx4 v130, s[34:35]
	s_mov_b32 m0, s47
	s_add_i32 s48, s31, 0x6000
	global_load_lds_dwordx4 v134, s[6:7]
	s_mov_b32 m0, s48
	v_mov_b32_e32 v129, v133
	global_load_lds_dwordx4 v130, s[6:7]
	v_mov_b32_e32 v135, v133
	v_mov_b32_e32 v131, v133
	s_cmp_eq_u32 s5, 1
	s_mov_b32 s49, 0
	v_lshl_add_u64 v[6:7], s[28:29], 0, v[132:133]
	v_lshl_add_u64 v[4:5], s[28:29], 0, v[128:129]
	v_lshl_add_u64 v[0:1], s[34:35], 0, v[134:135]
	s_cselect_b64 s[6:7], -1, 0
	s_cmp_lg_u32 s5, 1
	v_lshl_add_u64 v[2:3], s[34:35], 0, v[130:131]
	s_cbranch_scc1 .LBB0_1607
	s_barrier

.LBB0_1613:
	ds_read_b128 v[144:147], v149
	ds_read_b128 v[156:159], v149 offset:1024
	ds_read_b128 v[160:163], v149 offset:2048
	ds_read_b128 v[164:167], v149 offset:3072
	ds_read_b128 v[168:171], v150
	ds_read_b128 v[172:175], v150 offset:1024
	ds_read_b128 v[176:179], v150 offset:2048
	ds_read_b128 v[180:183], v150 offset:3072
	s_add_u32 s34, s28, 0xfffc0080
	s_addc_u32 s35, s29, -1
	s_cmp_eq_u32 s63, 12
	s_cselect_b32 s37, s17, s35
	s_cselect_b32 s36, s59, s34
	s_cselect_b32 s35, s15, s62
	s_cselect_b32 s34, s60, s61
	v_lshl_add_u64 v[216:217], s[28:29], 0, v[138:139]
	s_add_i32 m0, s31, 0xc000
	ds_read_b128 v[184:187], v151
	ds_read_b128 v[188:191], v151 offset:1024
	ds_read_b128 v[192:195], v151 offset:2048
	ds_read_b128 v[196:199], v151 offset:3072
	ds_read_b128 v[200:203], v151 offset:4096
	ds_read_b128 v[204:207], v151 offset:5120
	ds_read_b128 v[208:211], v151 offset:6144
	ds_read_b128 v[212:215], v151 offset:7168
	global_load_lds_dwordx4 v[216:217], off
	v_lshl_add_u64 v[216:217], s[28:29], 0, v[136:137]
	s_add_i32 m0, s31, 0xe000
	s_nop 0
	global_load_lds_dwordx4 v[216:217], off
	s_waitcnt vmcnt(8)
	s_waitcnt lgkmcnt(0)
	s_barrier
	s_waitcnt lgkmcnt(0)
	v_mfma_f32_16x16x32_bf16 v[124:127], v[144:147], v[184:187], v[124:127]
	v_mfma_f32_16x16x32_bf16 v[120:123], v[160:163], v[184:187], v[120:123]
	v_mfma_f32_16x16x32_bf16 v[108:111], v[144:147], v[192:195], v[108:111]
	v_mfma_f32_16x16x32_bf16 v[104:107], v[160:163], v[192:195], v[104:107]
	v_mfma_f32_16x16x32_bf16 v[92:95], v[144:147], v[200:203], v[92:95]
	v_mfma_f32_16x16x32_bf16 v[88:91], v[160:163], v[200:203], v[88:91]
	v_mfma_f32_16x16x32_bf16 v[76:79], v[144:147], v[208:211], v[76:79]
	v_mfma_f32_16x16x32_bf16 v[72:75], v[160:163], v[208:211], v[72:75]
	v_mfma_f32_16x16x32_bf16 v[124:127], v[156:159], v[188:191], v[124:127]
	v_mfma_f32_16x16x32_bf16 v[120:123], v[164:167], v[188:191], v[120:123]
	v_mfma_f32_16x16x32_bf16 v[108:111], v[156:159], v[196:199], v[108:111]
	v_mfma_f32_16x16x32_bf16 v[104:107], v[164:167], v[196:199], v[104:107]
	v_mfma_f32_16x16x32_bf16 v[92:95], v[156:159], v[204:207], v[92:95]
	v_mfma_f32_16x16x32_bf16 v[88:91], v[164:167], v[204:207], v[88:91]
	v_mfma_f32_16x16x32_bf16 v[76:79], v[156:159], v[212:215], v[76:79]
	v_mfma_f32_16x16x32_bf16 v[72:75], v[164:167], v[212:215], v[72:75]
	v_mfma_f32_16x16x32_bf16 v[116:119], v[168:171], v[184:187], v[116:119]
	v_mfma_f32_16x16x32_bf16 v[112:115], v[176:179], v[184:187], v[112:115]
	v_mfma_f32_16x16x32_bf16 v[100:103], v[168:171], v[192:195], v[100:103]
	v_mfma_f32_16x16x32_bf16 v[96:99], v[176:179], v[192:195], v[96:99]
	v_mfma_f32_16x16x32_bf16 v[84:87], v[168:171], v[200:203], v[84:87]
	v_mfma_f32_16x16x32_bf16 v[80:83], v[176:179], v[200:203], v[80:83]
	v_mfma_f32_16x16x32_bf16 v[68:71], v[168:171], v[208:211], v[68:71]
	v_mfma_f32_16x16x32_bf16 v[64:67], v[176:179], v[208:211], v[64:67]
	v_mfma_f32_16x16x32_bf16 v[116:119], v[172:175], v[188:191], v[116:119]
	v_mfma_f32_16x16x32_bf16 v[112:115], v[180:183], v[188:191], v[112:115]
	v_mfma_f32_16x16x32_bf16 v[100:103], v[172:175], v[196:199], v[100:103]
	v_mfma_f32_16x16x32_bf16 v[96:99], v[180:183], v[196:199], v[96:99]
	v_mfma_f32_16x16x32_bf16 v[84:87], v[172:175], v[204:207], v[84:87]
	v_mfma_f32_16x16x32_bf16 v[80:83], v[180:183], v[204:207], v[80:83]
	v_mfma_f32_16x16x32_bf16 v[68:71], v[172:175], v[212:215], v[68:71]
	v_mfma_f32_16x16x32_bf16 v[64:67], v[180:183], v[212:215], v[64:67]
	s_barrier
	s_add_i32 s64, s55, s43
	v_lshl_add_u64 v[216:217], s[34:35], 0, v[132:133]
	s_mov_b32 m0, s64
	ds_read_b128 v[184:187], v151 offset:16384
	ds_read_b128 v[188:191], v151 offset:17408
	ds_read_b128 v[192:195], v151 offset:18432
	ds_read_b128 v[196:199], v151 offset:19456
	ds_read_b128 v[200:203], v151 offset:20480
	ds_read_b128 v[204:207], v151 offset:21504
	ds_read_b128 v[208:211], v151 offset:22528
	ds_read_b128 v[212:215], v151 offset:23552
	global_load_lds_dwordx4 v[216:217], off
	s_add_i32 m0, s64, 0x2000
	s_add_u32 s64, s34, 0x40000
	v_lshl_add_u64 v[218:219], s[34:35], 0, v[128:129]
	s_addc_u32 s65, s35, 0
	s_add_i32 s66, s56, s43
	global_load_lds_dwordx4 v[218:219], off
	v_lshl_add_u64 v[220:221], s[64:65], 0, v[132:133]
	s_mov_b32 m0, s66
	v_lshl_add_u64 v[222:223], s[36:37], 0, v[130:131]
	global_load_lds_dwordx4 v[220:221], off
	v_lshl_add_u64 v[220:221], s[64:65], 0, v[128:129]
	s_add_i32 m0, s66, 0x2000
	s_nop 0
	global_load_lds_dwordx4 v[220:221], off
	v_lshl_add_u64 v[220:221], s[36:37], 0, v[134:135]
	s_mov_b32 m0, s31
	s_nop 0
	global_load_lds_dwordx4 v[220:221], off
	s_mov_b32 m0, s46
	s_nop 0
	global_load_lds_dwordx4 v[222:223], off
	s_waitcnt vmcnt(8)
	s_waitcnt lgkmcnt(0)
	s_barrier
	s_waitcnt lgkmcnt(0)
	v_mfma_f32_16x16x32_bf16 v[60:63], v[144:147], v[184:187], v[60:63]
	v_mfma_f32_16x16x32_bf16 v[56:59], v[160:163], v[184:187], v[56:59]
	v_mfma_f32_16x16x32_bf16 v[44:47], v[144:147], v[192:195], v[44:47]
	v_mfma_f32_16x16x32_bf16 v[40:43], v[160:163], v[192:195], v[40:43]
	v_mfma_f32_16x16x32_bf16 v[28:31], v[144:147], v[200:203], v[28:31]
	v_mfma_f32_16x16x32_bf16 v[24:27], v[160:163], v[200:203], v[24:27]
	v_mfma_f32_16x16x32_bf16 v[12:15], v[144:147], v[208:211], v[12:15]
	v_mfma_f32_16x16x32_bf16 v[8:11], v[160:163], v[208:211], v[8:11]
	v_mfma_f32_16x16x32_bf16 v[60:63], v[156:159], v[188:191], v[60:63]
	v_mfma_f32_16x16x32_bf16 v[56:59], v[164:167], v[188:191], v[56:59]
	v_mfma_f32_16x16x32_bf16 v[44:47], v[156:159], v[196:199], v[44:47]
	v_mfma_f32_16x16x32_bf16 v[40:43], v[164:167], v[196:199], v[40:43]
	v_mfma_f32_16x16x32_bf16 v[28:31], v[156:159], v[204:207], v[28:31]
	v_mfma_f32_16x16x32_bf16 v[24:27], v[164:167], v[204:207], v[24:27]
	v_mfma_f32_16x16x32_bf16 v[12:15], v[156:159], v[212:215], v[12:15]
	v_mfma_f32_16x16x32_bf16 v[8:11], v[164:167], v[212:215], v[8:11]
	v_mfma_f32_16x16x32_bf16 v[52:55], v[168:171], v[184:187], v[52:55]
	v_mfma_f32_16x16x32_bf16 v[48:51], v[176:179], v[184:187], v[48:51]
	v_mfma_f32_16x16x32_bf16 v[36:39], v[168:171], v[192:195], v[36:39]
	v_mfma_f32_16x16x32_bf16 v[32:35], v[176:179], v[192:195], v[32:35]
	v_mfma_f32_16x16x32_bf16 v[20:23], v[168:171], v[200:203], v[20:23]
	v_mfma_f32_16x16x32_bf16 v[16:19], v[176:179], v[200:203], v[16:19]
	v_mfma_f32_16x16x32_bf16 v[4:7], v[168:171], v[208:211], v[4:7]
	v_mfma_f32_16x16x32_bf16 v[0:3], v[176:179], v[208:211], v[0:3]
	v_mfma_f32_16x16x32_bf16 v[52:55], v[172:175], v[188:191], v[52:55]
	v_mfma_f32_16x16x32_bf16 v[48:51], v[180:183], v[188:191], v[48:51]
	v_mfma_f32_16x16x32_bf16 v[36:39], v[172:175], v[196:199], v[36:39]
	v_mfma_f32_16x16x32_bf16 v[32:35], v[180:183], v[196:199], v[32:35]
	v_mfma_f32_16x16x32_bf16 v[20:23], v[172:175], v[204:207], v[20:23]
	v_mfma_f32_16x16x32_bf16 v[16:19], v[180:183], v[204:207], v[16:19]
	v_mfma_f32_16x16x32_bf16 v[4:7], v[172:175], v[212:215], v[4:7]
	v_mfma_f32_16x16x32_bf16 v[0:3], v[180:183], v[212:215], v[0:3]
	s_barrier
	s_add_i32 s64, 0, 0x18000
	v_add_u32_e32 v153, s64, v148
	s_add_i32 s65, 0, 0x1c000
	ds_read_b128 v[144:147], v153
	ds_read_b128 v[156:159], v153 offset:1024
	ds_read_b128 v[160:163], v153 offset:2048
	ds_read_b128 v[164:167], v153 offset:3072
	v_add_u32_e32 v153, s65, v148
	ds_read_b128 v[168:171], v153
	ds_read_b128 v[172:175], v153 offset:1024
	ds_read_b128 v[176:179], v153 offset:2048
	ds_read_b128 v[180:183], v153 offset:3072
	s_add_u32 s36, s36, 0x40000
	s_addc_u32 s37, s37, 0
	s_mov_b32 m0, s47
	v_lshl_add_u64 v[224:225], s[36:37], 0, v[134:135]
	ds_read_b128 v[184:187], v151 offset:32768
	ds_read_b128 v[188:191], v151 offset:33792
	ds_read_b128 v[192:195], v151 offset:34816
	ds_read_b128 v[196:199], v151 offset:35840
	ds_read_b128 v[200:203], v151 offset:36864
	ds_read_b128 v[204:207], v151 offset:37888
	ds_read_b128 v[208:211], v151 offset:38912
	ds_read_b128 v[212:215], v151 offset:39936
	global_load_lds_dwordx4 v[224:225], off
	v_lshl_add_u64 v[224:225], s[36:37], 0, v[130:131]
	s_mov_b32 m0, s48
	s_nop 0
	global_load_lds_dwordx4 v[224:225], off
	s_waitcnt vmcnt(8)
	s_waitcnt lgkmcnt(0)
	s_barrier
	s_waitcnt lgkmcnt(0)
	v_mfma_f32_16x16x32_bf16 v[124:127], v[144:147], v[184:187], v[124:127]
	v_mfma_f32_16x16x32_bf16 v[120:123], v[160:163], v[184:187], v[120:123]
	v_mfma_f32_16x16x32_bf16 v[108:111], v[144:147], v[192:195], v[108:111]
	v_mfma_f32_16x16x32_bf16 v[104:107], v[160:163], v[192:195], v[104:107]
	v_mfma_f32_16x16x32_bf16 v[92:95], v[144:147], v[200:203], v[92:95]
	v_mfma_f32_16x16x32_bf16 v[88:91], v[160:163], v[200:203], v[88:91]
	v_mfma_f32_16x16x32_bf16 v[76:79], v[144:147], v[208:211], v[76:79]
	v_mfma_f32_16x16x32_bf16 v[72:75], v[160:163], v[208:211], v[72:75]
	v_mfma_f32_16x16x32_bf16 v[124:127], v[156:159], v[188:191], v[124:127]
	v_mfma_f32_16x16x32_bf16 v[120:123], v[164:167], v[188:191], v[120:123]
	v_mfma_f32_16x16x32_bf16 v[108:111], v[156:159], v[196:199], v[108:111]
	v_mfma_f32_16x16x32_bf16 v[104:107], v[164:167], v[196:199], v[104:107]
	v_mfma_f32_16x16x32_bf16 v[92:95], v[156:159], v[204:207], v[92:95]
	v_mfma_f32_16x16x32_bf16 v[88:91], v[164:167], v[204:207], v[88:91]
	v_mfma_f32_16x16x32_bf16 v[76:79], v[156:159], v[212:215], v[76:79]
	v_mfma_f32_16x16x32_bf16 v[72:75], v[164:167], v[212:215], v[72:75]
	v_mfma_f32_16x16x32_bf16 v[116:119], v[168:171], v[184:187], v[116:119]
	v_mfma_f32_16x16x32_bf16 v[112:115], v[176:179], v[184:187], v[112:115]
	v_mfma_f32_16x16x32_bf16 v[100:103], v[168:171], v[192:195], v[100:103]
	v_mfma_f32_16x16x32_bf16 v[96:99], v[176:179], v[192:195], v[96:99]
	v_mfma_f32_16x16x32_bf16 v[84:87], v[168:171], v[200:203], v[84:87]
	v_mfma_f32_16x16x32_bf16 v[80:83], v[176:179], v[200:203], v[80:83]
	v_mfma_f32_16x16x32_bf16 v[68:71], v[168:171], v[208:211], v[68:71]
	v_mfma_f32_16x16x32_bf16 v[64:67], v[176:179], v[208:211], v[64:67]
	v_mfma_f32_16x16x32_bf16 v[116:119], v[172:175], v[188:191], v[116:119]
	v_mfma_f32_16x16x32_bf16 v[112:115], v[180:183], v[188:191], v[112:115]
	v_mfma_f32_16x16x32_bf16 v[100:103], v[172:175], v[196:199], v[100:103]
	v_mfma_f32_16x16x32_bf16 v[96:99], v[180:183], v[196:199], v[96:99]
	v_mfma_f32_16x16x32_bf16 v[84:87], v[172:175], v[204:207], v[84:87]
	v_mfma_f32_16x16x32_bf16 v[80:83], v[180:183], v[204:207], v[80:83]
	v_mfma_f32_16x16x32_bf16 v[68:71], v[172:175], v[212:215], v[68:71]
	v_mfma_f32_16x16x32_bf16 v[64:67], v[180:183], v[212:215], v[64:67]
	s_barrier
	s_add_i32 s36, s64, s43
	v_lshl_add_u64 v[216:217], v[216:217], 0, s[8:9]
	s_mov_b32 m0, s36
	ds_read_b128 v[184:187], v151 offset:49152
	ds_read_b128 v[188:191], v151 offset:50176
	ds_read_b128 v[192:195], v151 offset:51200
	ds_read_b128 v[196:199], v151 offset:52224
	ds_read_b128 v[200:203], v151 offset:53248
	ds_read_b128 v[204:207], v151 offset:54272
	ds_read_b128 v[208:211], v151 offset:55296
	ds_read_b128 v[212:215], v151 offset:56320
	global_load_lds_dwordx4 v[216:217], off
	s_add_i32 m0, s36, 0x2000
	s_add_u32 s34, s34, 0x40080
	v_lshl_add_u64 v[216:217], v[218:219], 0, s[8:9]
	s_addc_u32 s35, s35, 0
	s_add_i32 s36, s65, s43
	global_load_lds_dwordx4 v[216:217], off
	v_lshl_add_u64 v[216:217], s[34:35], 0, v[132:133]
	s_mov_b32 m0, s36
	s_nop 0
	global_load_lds_dwordx4 v[216:217], off
	v_lshl_add_u64 v[216:217], s[34:35], 0, v[128:129]
	s_add_i32 m0, s36, 0x2000
	s_nop 0
	global_load_lds_dwordx4 v[216:217], off
	v_lshl_add_u64 v[216:217], v[220:221], 0, s[8:9]
	s_mov_b32 m0, s51
	s_nop 0
	global_load_lds_dwordx4 v[216:217], off
	v_lshl_add_u64 v[216:217], v[222:223], 0, s[8:9]
	s_mov_b32 m0, s52
	s_nop 0
	global_load_lds_dwordx4 v[216:217], off
	s_waitcnt vmcnt(8)
	s_waitcnt lgkmcnt(0)
	s_barrier
	s_waitcnt lgkmcnt(0)
	v_mfma_f32_16x16x32_bf16 v[60:63], v[144:147], v[184:187], v[60:63]
	v_mfma_f32_16x16x32_bf16 v[56:59], v[160:163], v[184:187], v[56:59]
	v_mfma_f32_16x16x32_bf16 v[44:47], v[144:147], v[192:195], v[44:47]
	v_mfma_f32_16x16x32_bf16 v[40:43], v[160:163], v[192:195], v[40:43]
	v_mfma_f32_16x16x32_bf16 v[28:31], v[144:147], v[200:203], v[28:31]
	v_mfma_f32_16x16x32_bf16 v[24:27], v[160:163], v[200:203], v[24:27]
	v_mfma_f32_16x16x32_bf16 v[12:15], v[144:147], v[208:211], v[12:15]
	v_mfma_f32_16x16x32_bf16 v[8:11], v[160:163], v[208:211], v[8:11]
	v_mfma_f32_16x16x32_bf16 v[60:63], v[156:159], v[188:191], v[60:63]
	v_mfma_f32_16x16x32_bf16 v[56:59], v[164:167], v[188:191], v[56:59]
	v_mfma_f32_16x16x32_bf16 v[44:47], v[156:159], v[196:199], v[44:47]
	v_mfma_f32_16x16x32_bf16 v[40:43], v[164:167], v[196:199], v[40:43]
	v_mfma_f32_16x16x32_bf16 v[28:31], v[156:159], v[204:207], v[28:31]
	v_mfma_f32_16x16x32_bf16 v[24:27], v[164:167], v[204:207], v[24:27]
	v_mfma_f32_16x16x32_bf16 v[12:15], v[156:159], v[212:215], v[12:15]
	v_mfma_f32_16x16x32_bf16 v[8:11], v[164:167], v[212:215], v[8:11]
	v_mfma_f32_16x16x32_bf16 v[52:55], v[168:171], v[184:187], v[52:55]
	v_mfma_f32_16x16x32_bf16 v[48:51], v[176:179], v[184:187], v[48:51]
	v_mfma_f32_16x16x32_bf16 v[36:39], v[168:171], v[192:195], v[36:39]
	v_mfma_f32_16x16x32_bf16 v[32:35], v[176:179], v[192:195], v[32:35]
	v_mfma_f32_16x16x32_bf16 v[20:23], v[168:171], v[200:203], v[20:23]
	v_mfma_f32_16x16x32_bf16 v[16:19], v[176:179], v[200:203], v[16:19]
	v_mfma_f32_16x16x32_bf16 v[4:7], v[168:171], v[208:211], v[4:7]
	v_mfma_f32_16x16x32_bf16 v[0:3], v[176:179], v[208:211], v[0:3]
	v_mfma_f32_16x16x32_bf16 v[52:55], v[172:175], v[188:191], v[52:55]
	v_mfma_f32_16x16x32_bf16 v[48:51], v[180:183], v[188:191], v[48:51]
	v_mfma_f32_16x16x32_bf16 v[36:39], v[172:175], v[196:199], v[36:39]
	v_mfma_f32_16x16x32_bf16 v[32:35], v[180:183], v[196:199], v[32:35]
	v_mfma_f32_16x16x32_bf16 v[20:23], v[172:175], v[204:207], v[20:23]
	v_mfma_f32_16x16x32_bf16 v[16:19], v[180:183], v[204:207], v[16:19]
	v_mfma_f32_16x16x32_bf16 v[4:7], v[172:175], v[212:215], v[4:7]
	v_mfma_f32_16x16x32_bf16 v[0:3], v[180:183], v[212:215], v[0:3]
	s_barrier
	s_add_i32 s63, s63, 2
	s_add_u32 s61, s61, 0x100
	s_addc_u32 s62, s62, 0
	s_add_u32 s28, s28, 0x100
	s_addc_u32 s29, s29, 0
	s_cmp_gt_u32 s63, 13
	s_cbranch_scc0 .LBB0_1613
	s_and_b64 vcc, exec, s[10:11]
	s_cbranch_vccz .LBB0_1616
	s_barrier

.LBB0_1742:
	s_mov_b64 s[6:7], s[0:1]
	s_getreg_b32 s3, hwreg(HW_REG_XCC_ID, 0, 4)
	s_setprio 0
	s_waitcnt vmcnt(0)
	s_waitcnt lgkmcnt(0)
	s_barrier
	s_and_saveexec_b64 s[4:5], s[20:21]
	s_cbranch_execz .LBB0_1794
	s_add_i32 s8, 0, 0x23fc0
	v_mov_b32_e32 v0, s8
	s_load_dwordx2 s[6:7], s[6:7], 0x138
	s_waitcnt vmcnt(0) expcnt(0) lgkmcnt(0)
	ds_read_b32 v2, v0
	s_add_i32 s8, 0, 0x23fc4
	v_mov_b32_e32 v0, s8
	ds_read_b32 v0, v0
	s_and_b32 s3, s3, 15
	s_waitcnt lgkmcnt(1)
	v_cmp_ne_u32_e32 vcc, 0, v2
	s_cbranch_vccnz .LBB0_1758
	s_load_dword s8, s[22:23], 0x14
	s_mov_b32 s54, 1
	v_mov_b32_e32 v16, 0
	s_waitcnt lgkmcnt(0)
	s_lshr_b32 s10, s8, 16
	s_and_b32 s8, s8, 0xffff
	s_cmp_lg_u32 s8, 0
	s_cselect_b64 s[8:9], -1, 0
	s_cmp_lg_u64 s[8:9], 0
	s_addc_u32 s8, s24, 0
	s_cmp_lg_u32 s10, 0
	s_mul_i32 s55, s8, s33
	s_cselect_b64 s[8:9], -1, 0
	s_cmp_lg_u64 s[8:9], 0
	s_addc_u32 s8, s25, 0
	s_mul_i32 s55, s55, s8
	s_add_u32 s8, s6, 0x4200
	s_addc_u32 s9, s7, 0
	s_add_u32 s10, s6, 0x4400
	s_addc_u32 s11, s7, 0
	s_add_u32 s12, s6, 0x4500
	s_addc_u32 s13, s7, 0
	s_add_u32 s14, s6, 0x4600
	s_addc_u32 s15, s7, 0
	s_add_u32 s16, s6, 0x4700
	s_addc_u32 s17, s7, 0
	s_add_u32 s18, s6, 0x4800
	s_addc_u32 s19, s7, 0
	s_add_u32 s22, s6, 0x4900
	s_addc_u32 s23, s7, 0
	s_add_u32 s26, s6, 0x4a00
	s_addc_u32 s27, s7, 0
	s_add_u32 s28, s6, 0x4b00
	s_addc_u32 s29, s7, 0
	s_add_u32 s30, s6, 0x4c00
	s_addc_u32 s31, s7, 0
	s_add_u32 s34, s6, 0x4d00
	s_addc_u32 s35, s7, 0
	s_add_u32 s36, s6, 0x4e00
	s_addc_u32 s37, s7, 0
	s_add_u32 s38, s6, 0x4f00
	s_addc_u32 s39, s7, 0
	s_add_u32 s40, s6, 0x5000
	s_addc_u32 s41, s7, 0
	s_add_u32 s42, s6, 0x5100
	s_addc_u32 s43, s7, 0
	s_add_u32 s44, s6, 0x5200
	s_addc_u32 s45, s7, 0
	s_add_u32 s46, s6, 0x5300
	s_addc_u32 s47, s7, 0
	s_branch .LBB0_1746

.LBB0_1794:
	s_or_b64 exec, exec, s[4:5]
	s_mov_b64 s[8:9], s[0:1]
	s_mov_b32 s3, s33
	s_mov_b32 s44, s2
	s_waitcnt lgkmcnt(0)
	s_barrier
	v_readfirstlane_b32 s94, v154
	s_cmpk_ge_u32 s94, 0x100
	s_cbranch_scc1 .Lprio_skip_17
	s_setprio 1
.Lprio_skip_17:
	v_mov_b32_e32 v8, v154
	s_cmpk_lt_i32 s44, 0x100
	s_cselect_b64 s[10:11], -1, 0
	s_cmpk_gt_i32 s44, 0xff
	v_readfirstlane_b32 s14, v8
	s_cbranch_scc1 .LBB0_1800
	s_ashr_i32 s4, s44, 31
	s_lshr_b32 s4, s4, 29
	s_add_i32 s12, s44, s4
	s_and_b32 s4, s12, -8
	s_sub_i32 s6, s44, s4
	s_cmp_gt_i32 s6, -1
	s_cbranch_scc0 .LBB0_1797
	s_lshl_b32 s7, s6, 5
	s_ashr_i32 s4, s12, 3
	s_cbranch_execz .LBB0_1798
	s_branch .LBB0_1799

.LBB0_1813:
	ds_read_b128 v[144:147], v157
	ds_read_b128 v[148:151], v157 offset:1024
	ds_read_b128 v[162:165], v157 offset:2048
	ds_read_b128 v[166:169], v157 offset:3072
	ds_read_b128 v[170:173], v158
	ds_read_b128 v[174:177], v158 offset:1024
	ds_read_b128 v[178:181], v158 offset:2048
	ds_read_b128 v[182:185], v158 offset:3072
	s_add_u32 s10, s8, 0xfffc0080
	s_addc_u32 s11, s9, -1
	s_cmp_eq_u32 s39, 12
	s_cselect_b32 s31, s23, s11
	s_cselect_b32 s30, s34, s10
	s_cselect_b32 s11, s19, s37
	s_cselect_b32 s10, s35, s36
	v_lshl_add_u64 v[152:153], s[8:9], 0, v[138:139]
	s_add_i32 m0, s41, 0xc000
	ds_read_b128 v[186:189], v159
	ds_read_b128 v[190:193], v159 offset:1024
	ds_read_b128 v[194:197], v159 offset:2048
	ds_read_b128 v[198:201], v159 offset:3072
	ds_read_b128 v[202:205], v159 offset:4096
	ds_read_b128 v[206:209], v159 offset:5120
	ds_read_b128 v[210:213], v159 offset:6144
	ds_read_b128 v[214:217], v159 offset:7168
	global_load_lds_dwordx4 v[152:153], off
	v_lshl_add_u64 v[152:153], s[8:9], 0, v[136:137]
	s_add_i32 m0, s41, 0xe000
	s_nop 0
	global_load_lds_dwordx4 v[152:153], off
	s_waitcnt vmcnt(8)
	s_waitcnt lgkmcnt(0)
	s_barrier
	s_waitcnt lgkmcnt(0)
	v_mfma_f32_16x16x32_bf16 v[124:127], v[144:147], v[186:189], v[124:127]
	v_mfma_f32_16x16x32_bf16 v[120:123], v[162:165], v[186:189], v[120:123]
	v_mfma_f32_16x16x32_bf16 v[108:111], v[144:147], v[194:197], v[108:111]
	v_mfma_f32_16x16x32_bf16 v[104:107], v[162:165], v[194:197], v[104:107]
	v_mfma_f32_16x16x32_bf16 v[92:95], v[144:147], v[202:205], v[92:95]
	v_mfma_f32_16x16x32_bf16 v[88:91], v[162:165], v[202:205], v[88:91]
	v_mfma_f32_16x16x32_bf16 v[76:79], v[144:147], v[210:213], v[76:79]
	v_mfma_f32_16x16x32_bf16 v[72:75], v[162:165], v[210:213], v[72:75]
	v_mfma_f32_16x16x32_bf16 v[124:127], v[148:151], v[190:193], v[124:127]
	v_mfma_f32_16x16x32_bf16 v[120:123], v[166:169], v[190:193], v[120:123]
	v_mfma_f32_16x16x32_bf16 v[108:111], v[148:151], v[198:201], v[108:111]
	v_mfma_f32_16x16x32_bf16 v[104:107], v[166:169], v[198:201], v[104:107]
	v_mfma_f32_16x16x32_bf16 v[92:95], v[148:151], v[206:209], v[92:95]
	v_mfma_f32_16x16x32_bf16 v[88:91], v[166:169], v[206:209], v[88:91]
	v_mfma_f32_16x16x32_bf16 v[76:79], v[148:151], v[214:217], v[76:79]
	v_mfma_f32_16x16x32_bf16 v[72:75], v[166:169], v[214:217], v[72:75]
	v_mfma_f32_16x16x32_bf16 v[116:119], v[170:173], v[186:189], v[116:119]
	v_mfma_f32_16x16x32_bf16 v[112:115], v[178:181], v[186:189], v[112:115]
	v_mfma_f32_16x16x32_bf16 v[100:103], v[170:173], v[194:197], v[100:103]
	v_mfma_f32_16x16x32_bf16 v[96:99], v[178:181], v[194:197], v[96:99]
	v_mfma_f32_16x16x32_bf16 v[84:87], v[170:173], v[202:205], v[84:87]
	v_mfma_f32_16x16x32_bf16 v[80:83], v[178:181], v[202:205], v[80:83]
	v_mfma_f32_16x16x32_bf16 v[68:71], v[170:173], v[210:213], v[68:71]
	v_mfma_f32_16x16x32_bf16 v[64:67], v[178:181], v[210:213], v[64:67]
	v_mfma_f32_16x16x32_bf16 v[116:119], v[174:177], v[190:193], v[116:119]
	v_mfma_f32_16x16x32_bf16 v[112:115], v[182:185], v[190:193], v[112:115]
	v_mfma_f32_16x16x32_bf16 v[100:103], v[174:177], v[198:201], v[100:103]
	v_mfma_f32_16x16x32_bf16 v[96:99], v[182:185], v[198:201], v[96:99]
	v_mfma_f32_16x16x32_bf16 v[84:87], v[174:177], v[206:209], v[84:87]
	v_mfma_f32_16x16x32_bf16 v[80:83], v[182:185], v[206:209], v[80:83]
	v_mfma_f32_16x16x32_bf16 v[68:71], v[174:177], v[214:217], v[68:71]
	v_mfma_f32_16x16x32_bf16 v[64:67], v[182:185], v[214:217], v[64:67]
	s_barrier
	s_add_i32 s42, s61, s49
	v_lshl_add_u64 v[152:153], s[10:11], 0, v[130:131]
	s_mov_b32 m0, s42
	ds_read_b128 v[186:189], v159 offset:16384
	ds_read_b128 v[190:193], v159 offset:17408
	ds_read_b128 v[194:197], v159 offset:18432
	ds_read_b128 v[198:201], v159 offset:19456
	ds_read_b128 v[202:205], v159 offset:20480
	ds_read_b128 v[206:209], v159 offset:21504
	ds_read_b128 v[210:213], v159 offset:22528
	ds_read_b128 v[214:217], v159 offset:23552
	global_load_lds_dwordx4 v[152:153], off
	s_add_i32 m0, s42, 0x2000
	s_add_u32 s42, s10, 0x40000
	v_lshl_add_u64 v[218:219], s[10:11], 0, v[134:135]
	s_addc_u32 s43, s11, 0
	s_add_i32 s64, s62, s49
	global_load_lds_dwordx4 v[218:219], off
	v_lshl_add_u64 v[220:221], s[42:43], 0, v[130:131]
	s_mov_b32 m0, s64
	v_lshl_add_u64 v[222:223], s[30:31], 0, v[132:133]
	global_load_lds_dwordx4 v[220:221], off
	v_lshl_add_u64 v[220:221], s[42:43], 0, v[134:135]
	s_add_i32 m0, s64, 0x2000
	s_nop 0
	global_load_lds_dwordx4 v[220:221], off
	v_lshl_add_u64 v[220:221], s[30:31], 0, v[128:129]
	s_mov_b32 m0, s41
	s_nop 0
	global_load_lds_dwordx4 v[220:221], off
	s_mov_b32 m0, s50
	s_nop 0
	global_load_lds_dwordx4 v[222:223], off
	s_waitcnt vmcnt(8)
	s_waitcnt lgkmcnt(0)
	s_barrier
	s_waitcnt lgkmcnt(0)
	v_mfma_f32_16x16x32_bf16 v[60:63], v[144:147], v[186:189], v[60:63]
	v_mfma_f32_16x16x32_bf16 v[56:59], v[162:165], v[186:189], v[56:59]
	v_mfma_f32_16x16x32_bf16 v[44:47], v[144:147], v[194:197], v[44:47]
	v_mfma_f32_16x16x32_bf16 v[40:43], v[162:165], v[194:197], v[40:43]
	v_mfma_f32_16x16x32_bf16 v[28:31], v[144:147], v[202:205], v[28:31]
	v_mfma_f32_16x16x32_bf16 v[24:27], v[162:165], v[202:205], v[24:27]
	v_mfma_f32_16x16x32_bf16 v[12:15], v[144:147], v[210:213], v[12:15]
	v_mfma_f32_16x16x32_bf16 v[8:11], v[162:165], v[210:213], v[8:11]
	v_mfma_f32_16x16x32_bf16 v[60:63], v[148:151], v[190:193], v[60:63]
	v_mfma_f32_16x16x32_bf16 v[56:59], v[166:169], v[190:193], v[56:59]
	v_mfma_f32_16x16x32_bf16 v[44:47], v[148:151], v[198:201], v[44:47]
	v_mfma_f32_16x16x32_bf16 v[40:43], v[166:169], v[198:201], v[40:43]
	v_mfma_f32_16x16x32_bf16 v[28:31], v[148:151], v[206:209], v[28:31]
	v_mfma_f32_16x16x32_bf16 v[24:27], v[166:169], v[206:209], v[24:27]
	v_mfma_f32_16x16x32_bf16 v[12:15], v[148:151], v[214:217], v[12:15]
	v_mfma_f32_16x16x32_bf16 v[8:11], v[166:169], v[214:217], v[8:11]
	v_mfma_f32_16x16x32_bf16 v[52:55], v[170:173], v[186:189], v[52:55]
	v_mfma_f32_16x16x32_bf16 v[48:51], v[178:181], v[186:189], v[48:51]
	v_mfma_f32_16x16x32_bf16 v[36:39], v[170:173], v[194:197], v[36:39]
	v_mfma_f32_16x16x32_bf16 v[32:35], v[178:181], v[194:197], v[32:35]
	v_mfma_f32_16x16x32_bf16 v[20:23], v[170:173], v[202:205], v[20:23]
	v_mfma_f32_16x16x32_bf16 v[16:19], v[178:181], v[202:205], v[16:19]
	v_mfma_f32_16x16x32_bf16 v[4:7], v[170:173], v[210:213], v[4:7]
	v_mfma_f32_16x16x32_bf16 v[0:3], v[178:181], v[210:213], v[0:3]
	v_mfma_f32_16x16x32_bf16 v[52:55], v[174:177], v[190:193], v[52:55]
	v_mfma_f32_16x16x32_bf16 v[48:51], v[182:185], v[190:193], v[48:51]
	v_mfma_f32_16x16x32_bf16 v[36:39], v[174:177], v[198:201], v[36:39]
	v_mfma_f32_16x16x32_bf16 v[32:35], v[182:185], v[198:201], v[32:35]
	v_mfma_f32_16x16x32_bf16 v[20:23], v[174:177], v[206:209], v[20:23]
	v_mfma_f32_16x16x32_bf16 v[16:19], v[182:185], v[206:209], v[16:19]
	v_mfma_f32_16x16x32_bf16 v[4:7], v[174:177], v[214:217], v[4:7]
	v_mfma_f32_16x16x32_bf16 v[0:3], v[182:185], v[214:217], v[0:3]
	s_barrier
	s_add_i32 s42, 0, 0x18000
	v_add_u32_e32 v161, s42, v156
	s_add_i32 s43, 0, 0x1c000
	ds_read_b128 v[144:147], v161
	ds_read_b128 v[148:151], v161 offset:1024
	ds_read_b128 v[162:165], v161 offset:2048
	ds_read_b128 v[166:169], v161 offset:3072
	v_add_u32_e32 v161, s43, v156
	ds_read_b128 v[170:173], v161
	ds_read_b128 v[174:177], v161 offset:1024
	ds_read_b128 v[178:181], v161 offset:2048
	ds_read_b128 v[182:185], v161 offset:3072
	s_add_u32 s30, s30, 0x40000
	s_addc_u32 s31, s31, 0
	s_mov_b32 m0, s51
	v_lshl_add_u64 v[224:225], s[30:31], 0, v[128:129]
	ds_read_b128 v[186:189], v159 offset:32768
	ds_read_b128 v[190:193], v159 offset:33792
	ds_read_b128 v[194:197], v159 offset:34816
	ds_read_b128 v[198:201], v159 offset:35840
	ds_read_b128 v[202:205], v159 offset:36864
	ds_read_b128 v[206:209], v159 offset:37888
	ds_read_b128 v[210:213], v159 offset:38912
	ds_read_b128 v[214:217], v159 offset:39936
	global_load_lds_dwordx4 v[224:225], off
	v_lshl_add_u64 v[224:225], s[30:31], 0, v[132:133]
	s_mov_b32 m0, s52
	s_nop 0
	global_load_lds_dwordx4 v[224:225], off
	s_waitcnt vmcnt(8)
	s_waitcnt lgkmcnt(0)
	s_barrier
	s_waitcnt lgkmcnt(0)
	v_mfma_f32_16x16x32_bf16 v[124:127], v[144:147], v[186:189], v[124:127]
	v_mfma_f32_16x16x32_bf16 v[120:123], v[162:165], v[186:189], v[120:123]
	v_mfma_f32_16x16x32_bf16 v[108:111], v[144:147], v[194:197], v[108:111]
	v_mfma_f32_16x16x32_bf16 v[104:107], v[162:165], v[194:197], v[104:107]
	v_mfma_f32_16x16x32_bf16 v[92:95], v[144:147], v[202:205], v[92:95]
	v_mfma_f32_16x16x32_bf16 v[88:91], v[162:165], v[202:205], v[88:91]
	v_mfma_f32_16x16x32_bf16 v[76:79], v[144:147], v[210:213], v[76:79]
	v_mfma_f32_16x16x32_bf16 v[72:75], v[162:165], v[210:213], v[72:75]
	v_mfma_f32_16x16x32_bf16 v[124:127], v[148:151], v[190:193], v[124:127]
	v_mfma_f32_16x16x32_bf16 v[120:123], v[166:169], v[190:193], v[120:123]
	v_mfma_f32_16x16x32_bf16 v[108:111], v[148:151], v[198:201], v[108:111]
	v_mfma_f32_16x16x32_bf16 v[104:107], v[166:169], v[198:201], v[104:107]
	v_mfma_f32_16x16x32_bf16 v[92:95], v[148:151], v[206:209], v[92:95]
	v_mfma_f32_16x16x32_bf16 v[88:91], v[166:169], v[206:209], v[88:91]
	v_mfma_f32_16x16x32_bf16 v[76:79], v[148:151], v[214:217], v[76:79]
	v_mfma_f32_16x16x32_bf16 v[72:75], v[166:169], v[214:217], v[72:75]
	v_mfma_f32_16x16x32_bf16 v[116:119], v[170:173], v[186:189], v[116:119]
	v_mfma_f32_16x16x32_bf16 v[112:115], v[178:181], v[186:189], v[112:115]
	v_mfma_f32_16x16x32_bf16 v[100:103], v[170:173], v[194:197], v[100:103]
	v_mfma_f32_16x16x32_bf16 v[96:99], v[178:181], v[194:197], v[96:99]
	v_mfma_f32_16x16x32_bf16 v[84:87], v[170:173], v[202:205], v[84:87]
	v_mfma_f32_16x16x32_bf16 v[80:83], v[178:181], v[202:205], v[80:83]
	v_mfma_f32_16x16x32_bf16 v[68:71], v[170:173], v[210:213], v[68:71]
	v_mfma_f32_16x16x32_bf16 v[64:67], v[178:181], v[210:213], v[64:67]
	v_mfma_f32_16x16x32_bf16 v[116:119], v[174:177], v[190:193], v[116:119]
	v_mfma_f32_16x16x32_bf16 v[112:115], v[182:185], v[190:193], v[112:115]
	v_mfma_f32_16x16x32_bf16 v[100:103], v[174:177], v[198:201], v[100:103]
	v_mfma_f32_16x16x32_bf16 v[96:99], v[182:185], v[198:201], v[96:99]
	v_mfma_f32_16x16x32_bf16 v[84:87], v[174:177], v[206:209], v[84:87]
	v_mfma_f32_16x16x32_bf16 v[80:83], v[182:185], v[206:209], v[80:83]
	v_mfma_f32_16x16x32_bf16 v[68:71], v[174:177], v[214:217], v[68:71]
	v_mfma_f32_16x16x32_bf16 v[64:67], v[182:185], v[214:217], v[64:67]
	s_barrier
	s_add_i32 s30, s42, s49
	v_lshl_add_u64 v[152:153], v[152:153], 0, s[12:13]
	s_mov_b32 m0, s30
	ds_read_b128 v[186:189], v159 offset:49152
	ds_read_b128 v[190:193], v159 offset:50176
	ds_read_b128 v[194:197], v159 offset:51200
	ds_read_b128 v[198:201], v159 offset:52224
	ds_read_b128 v[202:205], v159 offset:53248
	ds_read_b128 v[206:209], v159 offset:54272
	ds_read_b128 v[210:213], v159 offset:55296
	ds_read_b128 v[214:217], v159 offset:56320
	global_load_lds_dwordx4 v[152:153], off
	s_add_i32 m0, s30, 0x2000
	s_add_u32 s10, s10, 0x40080
	v_lshl_add_u64 v[152:153], v[218:219], 0, s[12:13]
	s_addc_u32 s11, s11, 0
	s_add_i32 s30, s43, s49
	global_load_lds_dwordx4 v[152:153], off
	v_lshl_add_u64 v[152:153], s[10:11], 0, v[130:131]
	s_mov_b32 m0, s30
	s_nop 0
	global_load_lds_dwordx4 v[152:153], off
	v_lshl_add_u64 v[152:153], s[10:11], 0, v[134:135]
	s_add_i32 m0, s30, 0x2000
	s_nop 0
	global_load_lds_dwordx4 v[152:153], off
	v_lshl_add_u64 v[152:153], v[220:221], 0, s[12:13]
	s_mov_b32 m0, s57
	s_nop 0
	global_load_lds_dwordx4 v[152:153], off
	v_lshl_add_u64 v[152:153], v[222:223], 0, s[12:13]
	s_mov_b32 m0, s58
	s_nop 0
	global_load_lds_dwordx4 v[152:153], off
	s_waitcnt vmcnt(8)
	s_waitcnt lgkmcnt(0)
	s_barrier
	s_waitcnt lgkmcnt(0)
	v_mfma_f32_16x16x32_bf16 v[60:63], v[144:147], v[186:189], v[60:63]
	v_mfma_f32_16x16x32_bf16 v[56:59], v[162:165], v[186:189], v[56:59]
	v_mfma_f32_16x16x32_bf16 v[44:47], v[144:147], v[194:197], v[44:47]
	v_mfma_f32_16x16x32_bf16 v[40:43], v[162:165], v[194:197], v[40:43]
	v_mfma_f32_16x16x32_bf16 v[28:31], v[144:147], v[202:205], v[28:31]
	v_mfma_f32_16x16x32_bf16 v[24:27], v[162:165], v[202:205], v[24:27]
	v_mfma_f32_16x16x32_bf16 v[12:15], v[144:147], v[210:213], v[12:15]
	v_mfma_f32_16x16x32_bf16 v[8:11], v[162:165], v[210:213], v[8:11]
	v_mfma_f32_16x16x32_bf16 v[60:63], v[148:151], v[190:193], v[60:63]
	v_mfma_f32_16x16x32_bf16 v[56:59], v[166:169], v[190:193], v[56:59]
	v_mfma_f32_16x16x32_bf16 v[44:47], v[148:151], v[198:201], v[44:47]
	v_mfma_f32_16x16x32_bf16 v[40:43], v[166:169], v[198:201], v[40:43]
	v_mfma_f32_16x16x32_bf16 v[28:31], v[148:151], v[206:209], v[28:31]
	v_mfma_f32_16x16x32_bf16 v[24:27], v[166:169], v[206:209], v[24:27]
	v_mfma_f32_16x16x32_bf16 v[12:15], v[148:151], v[214:217], v[12:15]
	v_mfma_f32_16x16x32_bf16 v[8:11], v[166:169], v[214:217], v[8:11]
	v_mfma_f32_16x16x32_bf16 v[52:55], v[170:173], v[186:189], v[52:55]
	v_mfma_f32_16x16x32_bf16 v[48:51], v[178:181], v[186:189], v[48:51]
	v_mfma_f32_16x16x32_bf16 v[36:39], v[170:173], v[194:197], v[36:39]
	v_mfma_f32_16x16x32_bf16 v[32:35], v[178:181], v[194:197], v[32:35]
	v_mfma_f32_16x16x32_bf16 v[20:23], v[170:173], v[202:205], v[20:23]
	v_mfma_f32_16x16x32_bf16 v[16:19], v[178:181], v[202:205], v[16:19]
	v_mfma_f32_16x16x32_bf16 v[4:7], v[170:173], v[210:213], v[4:7]
	v_mfma_f32_16x16x32_bf16 v[0:3], v[178:181], v[210:213], v[0:3]
	v_mfma_f32_16x16x32_bf16 v[52:55], v[174:177], v[190:193], v[52:55]
	v_mfma_f32_16x16x32_bf16 v[48:51], v[182:185], v[190:193], v[48:51]
	v_mfma_f32_16x16x32_bf16 v[36:39], v[174:177], v[198:201], v[36:39]
	v_mfma_f32_16x16x32_bf16 v[32:35], v[182:185], v[198:201], v[32:35]
	v_mfma_f32_16x16x32_bf16 v[20:23], v[174:177], v[206:209], v[20:23]
	v_mfma_f32_16x16x32_bf16 v[16:19], v[182:185], v[206:209], v[16:19]
	v_mfma_f32_16x16x32_bf16 v[4:7], v[174:177], v[214:217], v[4:7]
	v_mfma_f32_16x16x32_bf16 v[0:3], v[182:185], v[214:217], v[0:3]
	s_barrier
	s_add_i32 s39, s39, 2
	s_add_u32 s36, s36, 0x100
	s_addc_u32 s37, s37, 0
	s_add_u32 s8, s8, 0x100
	s_addc_u32 s9, s9, 0
	s_cmp_gt_u32 s39, 13
	s_cbranch_scc0 .LBB0_1813
	s_and_b64 vcc, exec, s[14:15]
	s_cbranch_vccz .LBB0_1816
	s_barrier

.LBB0_1836:
	s_waitcnt lgkmcnt(0)
	s_mov_b64 s[6:7], s[0:1]
	s_getreg_b32 s3, hwreg(HW_REG_XCC_ID, 0, 4)
	s_setprio 0
	s_waitcnt vmcnt(0)
	s_barrier
	s_and_saveexec_b64 s[4:5], s[20:21]
	s_cbranch_execz .LBB0_1888
	s_add_i32 s8, 0, 0x23fc0
	v_mov_b32_e32 v0, s8
	s_load_dwordx2 s[6:7], s[6:7], 0x138
	s_waitcnt vmcnt(0) expcnt(0) lgkmcnt(0)
	ds_read_b32 v2, v0
	s_add_i32 s8, 0, 0x23fc4
	v_mov_b32_e32 v0, s8
	ds_read_b32 v0, v0
	s_and_b32 s3, s3, 15
	s_waitcnt lgkmcnt(1)
	v_cmp_ne_u32_e32 vcc, 0, v2
	s_cbranch_vccnz .LBB0_1852
	s_add_u32 s8, s6, 0x4200
	s_addc_u32 s9, s7, 0
	s_add_u32 s10, s6, 0x4400
	s_addc_u32 s11, s7, 0
	s_add_u32 s12, s6, 0x4500
	s_addc_u32 s13, s7, 0
	s_add_u32 s14, s6, 0x4600
	s_addc_u32 s15, s7, 0
	s_add_u32 s16, s6, 0x4700
	s_addc_u32 s17, s7, 0
	s_add_u32 s18, s6, 0x4800
	s_addc_u32 s19, s7, 0
	s_add_u32 s20, s6, 0x4900
	s_addc_u32 s21, s7, 0
	s_add_u32 s22, s6, 0x4a00
	s_mul_i32 s50, s25, s33
	s_addc_u32 s23, s7, 0
	s_mul_i32 s50, s50, s24
	s_add_u32 s24, s6, 0x4b00
	s_addc_u32 s25, s7, 0
	s_add_u32 s26, s6, 0x4c00
	s_addc_u32 s27, s7, 0
	s_add_u32 s28, s6, 0x4d00
	s_addc_u32 s29, s7, 0
	s_add_u32 s30, s6, 0x4e00
	s_addc_u32 s31, s7, 0
	s_add_u32 s34, s6, 0x4f00
	s_addc_u32 s35, s7, 0
	s_add_u32 s36, s6, 0x5000
	s_addc_u32 s37, s7, 0
	s_add_u32 s38, s6, 0x5100
	s_addc_u32 s39, s7, 0
	s_add_u32 s40, s6, 0x5200
	s_addc_u32 s41, s7, 0
	s_add_u32 s42, s6, 0x5300
	s_addc_u32 s43, s7, 0
	s_mov_b32 s51, 1
	v_mov_b32_e32 v16, 0
	s_branch .LBB0_1840
